# cache-policy hint on loads: read-once inputs of the scan / kv / ret / sgu units marked nt
# baseline (speedup 1.0000x reference)
; __device__ __forceinline__ unsigned pk2(float lo, float hi) { return pg8::cvt_pk_bf16(lo, hi); }
; __device__ __forceinline__ float ret_log2gamma(int h) { return log2f(1.f - exp2f(-5.f - (float)h)); }
; __device__ __forceinline__ void st_sc1_u2(void* p, unsigned lo, unsigned hi) { __hip_atomic_store((GAS unsigned long long*)p, ((unsigned long long)hi << 32) | (unsigned long long)lo, __ATOMIC_RELAXED, __HIP_MEMORY_SCOPE_AGENT); }
; __device__ __forceinline__ void scan_unit(const float* KVT, bfu* RT, int s) {
;     int tid = threadIdx.x; asm volatile("" : "+v"(tid)); const int lane = tid & 63, wid = __builtin_amdgcn_readfirstlane(tid >> 6); (void)lane; (void)wid;
;     const int bh = s >> 3, part = s & 7, h = bh % 6; const float G = exp2f(ret_log2gamma(h) * 128.f);
;     const size_t e = (size_t)bh * 64 * 16384 + part * 2048 + tid * 4; f32x4 st = (f32x4){0.f, 0.f, 0.f, 0.f};
; #pragma unroll 8
;     for (int i = 0; i < 64; ++i) { const f32x4 cur = *(const f32x4*)(KVT + e + (size_t)i * 16384); st_sc1_u2(RT + e + (size_t)i * 16384, pk2(st[0], st[1]), pk2(st[2], st[3])); st = cur + st * G; }
; }
.LBB0_268:
	v_mov_b32_e32 v3, v2
	s_mov_b32 s20, 0xfff90000
	v_add_co_u32_e32 v24, vcc, s20, v8
	s_nop 1
	v_addc_co_u32_e32 v25, vcc, -1, v9, vcc
	s_mov_b32 s20, 0x33600000
	v_add_co_u32_e32 v26, vcc, s20, v6
	s_nop 1
	v_addc_co_u32_e32 v27, vcc, 0, v7, vcc
	s_mov_b64 s[42:43], 0x10000
	s_mov_b64 s[46:47], 0x8000
	global_load_dwordx4 v[64:67], v[24:25], off nt
	v_lshl_add_u64 v[24:25], v[24:25], 0, s[42:43]
	global_load_dwordx4 v[68:71], v[24:25], off nt
	v_lshl_add_u64 v[24:25], v[24:25], 0, s[42:43]
	global_load_dwordx4 v[72:75], v[24:25], off nt
	v_lshl_add_u64 v[24:25], v[24:25], 0, s[42:43]
	global_load_dwordx4 v[76:79], v[24:25], off nt
	v_lshl_add_u64 v[24:25], v[24:25], 0, s[42:43]
	global_load_dwordx4 v[80:83], v[24:25], off nt
	v_lshl_add_u64 v[24:25], v[24:25], 0, s[42:43]
	global_load_dwordx4 v[84:87], v[24:25], off nt
	v_lshl_add_u64 v[24:25], v[24:25], 0, s[42:43]
	global_load_dwordx4 v[88:91], v[24:25], off nt
	v_lshl_add_u64 v[24:25], v[24:25], 0, s[42:43]
	global_load_dwordx4 v[92:95], v[24:25], off nt
	v_lshl_add_u64 v[24:25], v[24:25], 0, s[42:43]
	global_load_dwordx4 v[96:99], v[24:25], off nt
	v_lshl_add_u64 v[24:25], v[24:25], 0, s[42:43]
	global_load_dwordx4 v[100:103], v[24:25], off nt
	v_lshl_add_u64 v[24:25], v[24:25], 0, s[42:43]
	global_load_dwordx4 v[104:107], v[24:25], off nt
	v_lshl_add_u64 v[24:25], v[24:25], 0, s[42:43]
	global_load_dwordx4 v[108:111], v[24:25], off nt
	v_lshl_add_u64 v[24:25], v[24:25], 0, s[42:43]
	global_load_dwordx4 v[112:115], v[24:25], off nt
	v_lshl_add_u64 v[24:25], v[24:25], 0, s[42:43]
	global_load_dwordx4 v[116:119], v[24:25], off nt
	v_lshl_add_u64 v[24:25], v[24:25], 0, s[42:43]
	global_load_dwordx4 v[120:123], v[24:25], off nt
	v_lshl_add_u64 v[24:25], v[24:25], 0, s[42:43]
	global_load_dwordx4 v[124:127], v[24:25], off nt
	v_lshl_add_u64 v[24:25], v[24:25], 0, s[42:43]
	global_load_dwordx4 v[128:131], v[24:25], off nt
	v_lshl_add_u64 v[24:25], v[24:25], 0, s[42:43]
	global_load_dwordx4 v[132:135], v[24:25], off nt
	v_lshl_add_u64 v[24:25], v[24:25], 0, s[42:43]
	global_load_dwordx4 v[136:139], v[24:25], off nt
	v_lshl_add_u64 v[24:25], v[24:25], 0, s[42:43]
	global_load_dwordx4 v[140:143], v[24:25], off nt
	v_lshl_add_u64 v[24:25], v[24:25], 0, s[42:43]
	global_load_dwordx4 v[144:147], v[24:25], off nt
	v_lshl_add_u64 v[24:25], v[24:25], 0, s[42:43]
	global_load_dwordx4 v[148:151], v[24:25], off nt
	v_lshl_add_u64 v[24:25], v[24:25], 0, s[42:43]
	global_load_dwordx4 v[152:155], v[24:25], off nt
	v_lshl_add_u64 v[24:25], v[24:25], 0, s[42:43]
	global_load_dwordx4 v[156:159], v[24:25], off nt
	v_lshl_add_u64 v[24:25], v[24:25], 0, s[42:43]
	global_load_dwordx4 v[160:163], v[24:25], off nt
	v_lshl_add_u64 v[24:25], v[24:25], 0, s[42:43]
	global_load_dwordx4 v[164:167], v[24:25], off nt
	v_lshl_add_u64 v[24:25], v[24:25], 0, s[42:43]
	global_load_dwordx4 v[168:171], v[24:25], off nt
	v_lshl_add_u64 v[24:25], v[24:25], 0, s[42:43]
	global_load_dwordx4 v[172:175], v[24:25], off nt
	v_lshl_add_u64 v[24:25], v[24:25], 0, s[42:43]
	global_load_dwordx4 v[176:179], v[24:25], off nt
	v_lshl_add_u64 v[24:25], v[24:25], 0, s[42:43]
	global_load_dwordx4 v[180:183], v[24:25], off nt
	v_lshl_add_u64 v[24:25], v[24:25], 0, s[42:43]
	global_load_dwordx4 v[184:187], v[24:25], off nt
	v_lshl_add_u64 v[24:25], v[24:25], 0, s[42:43]
	global_load_dwordx4 v[188:191], v[24:25], off nt
	v_lshl_add_u64 v[24:25], v[24:25], 0, s[42:43]
	v_cvt_pk_bf16_f32 v22, v12, v13
	v_cvt_pk_bf16_f32 v23, v14, v15
	global_store_dwordx2 v[26:27], v[22:23], off sc1
	v_lshl_add_u64 v[26:27], v[26:27], 0, s[46:47]
	s_waitcnt vmcnt(31)
	v_pk_fma_f32 v[12:13], v[4:5], v[12:13], v[64:65]
	v_pk_fma_f32 v[14:15], v[2:3], v[14:15], v[66:67]
	global_load_dwordx4 v[64:67], v[24:25], off nt
	v_lshl_add_u64 v[24:25], v[24:25], 0, s[42:43]
	v_cvt_pk_bf16_f32 v28, v12, v13
	v_cvt_pk_bf16_f32 v29, v14, v15
	global_store_dwordx2 v[26:27], v[28:29], off sc1
	v_lshl_add_u64 v[26:27], v[26:27], 0, s[46:47]
	s_waitcnt vmcnt(31)
	v_pk_fma_f32 v[12:13], v[4:5], v[12:13], v[68:69]
	v_pk_fma_f32 v[14:15], v[2:3], v[14:15], v[70:71]
	global_load_dwordx4 v[68:71], v[24:25], off nt
	v_lshl_add_u64 v[24:25], v[24:25], 0, s[42:43]
	v_cvt_pk_bf16_f32 v22, v12, v13
	v_cvt_pk_bf16_f32 v23, v14, v15
	global_store_dwordx2 v[26:27], v[22:23], off sc1
	v_lshl_add_u64 v[26:27], v[26:27], 0, s[46:47]
	s_waitcnt vmcnt(31)
	v_pk_fma_f32 v[12:13], v[4:5], v[12:13], v[72:73]
	v_pk_fma_f32 v[14:15], v[2:3], v[14:15], v[74:75]
	global_load_dwordx4 v[72:75], v[24:25], off nt
	v_lshl_add_u64 v[24:25], v[24:25], 0, s[42:43]
	v_cvt_pk_bf16_f32 v28, v12, v13
	v_cvt_pk_bf16_f32 v29, v14, v15
	global_store_dwordx2 v[26:27], v[28:29], off sc1
	v_lshl_add_u64 v[26:27], v[26:27], 0, s[46:47]
	s_waitcnt vmcnt(31)
	v_pk_fma_f32 v[12:13], v[4:5], v[12:13], v[76:77]
	v_pk_fma_f32 v[14:15], v[2:3], v[14:15], v[78:79]
	global_load_dwordx4 v[76:79], v[24:25], off nt
	v_lshl_add_u64 v[24:25], v[24:25], 0, s[42:43]
	v_cvt_pk_bf16_f32 v22, v12, v13
	v_cvt_pk_bf16_f32 v23, v14, v15
	global_store_dwordx2 v[26:27], v[22:23], off sc1
	v_lshl_add_u64 v[26:27], v[26:27], 0, s[46:47]
	s_waitcnt vmcnt(31)
	v_pk_fma_f32 v[12:13], v[4:5], v[12:13], v[80:81]
	v_pk_fma_f32 v[14:15], v[2:3], v[14:15], v[82:83]
	global_load_dwordx4 v[80:83], v[24:25], off nt
	v_lshl_add_u64 v[24:25], v[24:25], 0, s[42:43]
	v_cvt_pk_bf16_f32 v28, v12, v13
	v_cvt_pk_bf16_f32 v29, v14, v15
	global_store_dwordx2 v[26:27], v[28:29], off sc1
	v_lshl_add_u64 v[26:27], v[26:27], 0, s[46:47]
	s_waitcnt vmcnt(31)
; __device__ __forceinline__ unsigned pk2(float lo, float hi) { return pg8::cvt_pk_bf16(lo, hi); }
; __device__ __forceinline__ float ret_log2gamma(int h) { return log2f(1.f - exp2f(-5.f - (float)h)); }
; __device__ __forceinline__ void st_sc1_u2(void* p, unsigned lo, unsigned hi) { __hip_atomic_store((GAS unsigned long long*)p, ((unsigned long long)hi << 32) | (unsigned long long)lo, __ATOMIC_RELAXED, __HIP_MEMORY_SCOPE_AGENT); }
; __device__ __forceinline__ void scan_unit(const float* KVT, bfu* RT, int s) {
;     int tid = threadIdx.x; asm volatile("" : "+v"(tid)); const int lane = tid & 63, wid = __builtin_amdgcn_readfirstlane(tid >> 6); (void)lane; (void)wid;
;     const int bh = s >> 3, part = s & 7, h = bh % 6; const float G = exp2f(ret_log2gamma(h) * 128.f);
;     const size_t e = (size_t)bh * 64 * 16384 + part * 2048 + tid * 4; f32x4 st = (f32x4){0.f, 0.f, 0.f, 0.f};
; #pragma unroll 8
;     for (int i = 0; i < 64; ++i) { const f32x4 cur = *(const f32x4*)(KVT + e + (size_t)i * 16384); st_sc1_u2(RT + e + (size_t)i * 16384, pk2(st[0], st[1]), pk2(st[2], st[3])); st = cur + st * G; }
; }
	v_pk_fma_f32 v[12:13], v[4:5], v[12:13], v[84:85]
	v_pk_fma_f32 v[14:15], v[2:3], v[14:15], v[86:87]
	global_load_dwordx4 v[84:87], v[24:25], off nt
	v_lshl_add_u64 v[24:25], v[24:25], 0, s[42:43]
	v_cvt_pk_bf16_f32 v22, v12, v13
	v_cvt_pk_bf16_f32 v23, v14, v15
	global_store_dwordx2 v[26:27], v[22:23], off sc1
	v_lshl_add_u64 v[26:27], v[26:27], 0, s[46:47]
	s_waitcnt vmcnt(31)
	v_pk_fma_f32 v[12:13], v[4:5], v[12:13], v[88:89]
	v_pk_fma_f32 v[14:15], v[2:3], v[14:15], v[90:91]
	global_load_dwordx4 v[88:91], v[24:25], off nt
	v_lshl_add_u64 v[24:25], v[24:25], 0, s[42:43]
	v_cvt_pk_bf16_f32 v28, v12, v13
	v_cvt_pk_bf16_f32 v29, v14, v15
	global_store_dwordx2 v[26:27], v[28:29], off sc1
	v_lshl_add_u64 v[26:27], v[26:27], 0, s[46:47]
	s_waitcnt vmcnt(31)
	v_pk_fma_f32 v[12:13], v[4:5], v[12:13], v[92:93]
	v_pk_fma_f32 v[14:15], v[2:3], v[14:15], v[94:95]
	global_load_dwordx4 v[92:95], v[24:25], off nt
	v_lshl_add_u64 v[24:25], v[24:25], 0, s[42:43]
	v_cvt_pk_bf16_f32 v22, v12, v13
	v_cvt_pk_bf16_f32 v23, v14, v15
	global_store_dwordx2 v[26:27], v[22:23], off sc1
	v_lshl_add_u64 v[26:27], v[26:27], 0, s[46:47]
	s_waitcnt vmcnt(31)
	v_pk_fma_f32 v[12:13], v[4:5], v[12:13], v[96:97]
	v_pk_fma_f32 v[14:15], v[2:3], v[14:15], v[98:99]
	global_load_dwordx4 v[96:99], v[24:25], off nt
	v_lshl_add_u64 v[24:25], v[24:25], 0, s[42:43]
	v_cvt_pk_bf16_f32 v28, v12, v13
	v_cvt_pk_bf16_f32 v29, v14, v15
	global_store_dwordx2 v[26:27], v[28:29], off sc1
	v_lshl_add_u64 v[26:27], v[26:27], 0, s[46:47]
	s_waitcnt vmcnt(31)
	v_pk_fma_f32 v[12:13], v[4:5], v[12:13], v[100:101]
	v_pk_fma_f32 v[14:15], v[2:3], v[14:15], v[102:103]
	global_load_dwordx4 v[100:103], v[24:25], off nt
	v_lshl_add_u64 v[24:25], v[24:25], 0, s[42:43]
	v_cvt_pk_bf16_f32 v22, v12, v13
	v_cvt_pk_bf16_f32 v23, v14, v15
	global_store_dwordx2 v[26:27], v[22:23], off sc1
	v_lshl_add_u64 v[26:27], v[26:27], 0, s[46:47]
	s_waitcnt vmcnt(31)
	v_pk_fma_f32 v[12:13], v[4:5], v[12:13], v[104:105]
	v_pk_fma_f32 v[14:15], v[2:3], v[14:15], v[106:107]
	global_load_dwordx4 v[104:107], v[24:25], off nt
	v_lshl_add_u64 v[24:25], v[24:25], 0, s[42:43]
	v_cvt_pk_bf16_f32 v28, v12, v13
	v_cvt_pk_bf16_f32 v29, v14, v15
	global_store_dwordx2 v[26:27], v[28:29], off sc1
	v_lshl_add_u64 v[26:27], v[26:27], 0, s[46:47]
	s_waitcnt vmcnt(31)
	v_pk_fma_f32 v[12:13], v[4:5], v[12:13], v[108:109]
	v_pk_fma_f32 v[14:15], v[2:3], v[14:15], v[110:111]
	global_load_dwordx4 v[108:111], v[24:25], off nt
	v_lshl_add_u64 v[24:25], v[24:25], 0, s[42:43]
	v_cvt_pk_bf16_f32 v22, v12, v13
	v_cvt_pk_bf16_f32 v23, v14, v15
	global_store_dwordx2 v[26:27], v[22:23], off sc1
	v_lshl_add_u64 v[26:27], v[26:27], 0, s[46:47]
	s_waitcnt vmcnt(31)
	v_pk_fma_f32 v[12:13], v[4:5], v[12:13], v[112:113]
	v_pk_fma_f32 v[14:15], v[2:3], v[14:15], v[114:115]
	global_load_dwordx4 v[112:115], v[24:25], off nt
	v_lshl_add_u64 v[24:25], v[24:25], 0, s[42:43]
	v_cvt_pk_bf16_f32 v28, v12, v13
	v_cvt_pk_bf16_f32 v29, v14, v15
	global_store_dwordx2 v[26:27], v[28:29], off sc1
	v_lshl_add_u64 v[26:27], v[26:27], 0, s[46:47]
	s_waitcnt vmcnt(31)
	v_pk_fma_f32 v[12:13], v[4:5], v[12:13], v[116:117]
	v_pk_fma_f32 v[14:15], v[2:3], v[14:15], v[118:119]
	global_load_dwordx4 v[116:119], v[24:25], off nt
	v_lshl_add_u64 v[24:25], v[24:25], 0, s[42:43]
	v_cvt_pk_bf16_f32 v22, v12, v13
	v_cvt_pk_bf16_f32 v23, v14, v15
	global_store_dwordx2 v[26:27], v[22:23], off sc1
	v_lshl_add_u64 v[26:27], v[26:27], 0, s[46:47]
	s_waitcnt vmcnt(31)
	v_pk_fma_f32 v[12:13], v[4:5], v[12:13], v[120:121]
	v_pk_fma_f32 v[14:15], v[2:3], v[14:15], v[122:123]
	global_load_dwordx4 v[120:123], v[24:25], off nt
	v_lshl_add_u64 v[24:25], v[24:25], 0, s[42:43]
	v_cvt_pk_bf16_f32 v28, v12, v13
	v_cvt_pk_bf16_f32 v29, v14, v15
	global_store_dwordx2 v[26:27], v[28:29], off sc1
	v_lshl_add_u64 v[26:27], v[26:27], 0, s[46:47]
	s_waitcnt vmcnt(31)
	v_pk_fma_f32 v[12:13], v[4:5], v[12:13], v[124:125]
	v_pk_fma_f32 v[14:15], v[2:3], v[14:15], v[126:127]
	global_load_dwordx4 v[124:127], v[24:25], off nt
	v_lshl_add_u64 v[24:25], v[24:25], 0, s[42:43]
	v_cvt_pk_bf16_f32 v22, v12, v13
	v_cvt_pk_bf16_f32 v23, v14, v15
	global_store_dwordx2 v[26:27], v[22:23], off sc1
	v_lshl_add_u64 v[26:27], v[26:27], 0, s[46:47]
	s_waitcnt vmcnt(31)
	v_pk_fma_f32 v[12:13], v[4:5], v[12:13], v[128:129]
	v_pk_fma_f32 v[14:15], v[2:3], v[14:15], v[130:131]
	global_load_dwordx4 v[128:131], v[24:25], off nt
	v_lshl_add_u64 v[24:25], v[24:25], 0, s[42:43]
	v_cvt_pk_bf16_f32 v28, v12, v13
	v_cvt_pk_bf16_f32 v29, v14, v15
	global_store_dwordx2 v[26:27], v[28:29], off sc1
	v_lshl_add_u64 v[26:27], v[26:27], 0, s[46:47]
	s_waitcnt vmcnt(31)
	v_pk_fma_f32 v[12:13], v[4:5], v[12:13], v[132:133]
	v_pk_fma_f32 v[14:15], v[2:3], v[14:15], v[134:135]
	global_load_dwordx4 v[132:135], v[24:25], off nt
	v_lshl_add_u64 v[24:25], v[24:25], 0, s[42:43]
	v_cvt_pk_bf16_f32 v22, v12, v13
	v_cvt_pk_bf16_f32 v23, v14, v15
	global_store_dwordx2 v[26:27], v[22:23], off sc1
	v_lshl_add_u64 v[26:27], v[26:27], 0, s[46:47]
	s_waitcnt vmcnt(31)
	v_pk_fma_f32 v[12:13], v[4:5], v[12:13], v[136:137]
	v_pk_fma_f32 v[14:15], v[2:3], v[14:15], v[138:139]
	global_load_dwordx4 v[136:139], v[24:25], off nt
	v_lshl_add_u64 v[24:25], v[24:25], 0, s[42:43]
	v_cvt_pk_bf16_f32 v28, v12, v13
	v_cvt_pk_bf16_f32 v29, v14, v15
	global_store_dwordx2 v[26:27], v[28:29], off sc1
	v_lshl_add_u64 v[26:27], v[26:27], 0, s[46:47]
	s_waitcnt vmcnt(31)
	v_pk_fma_f32 v[12:13], v[4:5], v[12:13], v[140:141]
	v_pk_fma_f32 v[14:15], v[2:3], v[14:15], v[142:143]
	global_load_dwordx4 v[140:143], v[24:25], off nt
	v_lshl_add_u64 v[24:25], v[24:25], 0, s[42:43]
	v_cvt_pk_bf16_f32 v22, v12, v13
	v_cvt_pk_bf16_f32 v23, v14, v15
	global_store_dwordx2 v[26:27], v[22:23], off sc1
	v_lshl_add_u64 v[26:27], v[26:27], 0, s[46:47]
	s_waitcnt vmcnt(31)
; __device__ __forceinline__ unsigned pk2(float lo, float hi) { return pg8::cvt_pk_bf16(lo, hi); }
; __device__ __forceinline__ float ret_log2gamma(int h) { return log2f(1.f - exp2f(-5.f - (float)h)); }
; __device__ __forceinline__ void st_sc1_u2(void* p, unsigned lo, unsigned hi) { __hip_atomic_store((GAS unsigned long long*)p, ((unsigned long long)hi << 32) | (unsigned long long)lo, __ATOMIC_RELAXED, __HIP_MEMORY_SCOPE_AGENT); }
; __device__ __forceinline__ void scan_unit(const float* KVT, bfu* RT, int s) {
;     int tid = threadIdx.x; asm volatile("" : "+v"(tid)); const int lane = tid & 63, wid = __builtin_amdgcn_readfirstlane(tid >> 6); (void)lane; (void)wid;
;     const int bh = s >> 3, part = s & 7, h = bh % 6; const float G = exp2f(ret_log2gamma(h) * 128.f);
;     const size_t e = (size_t)bh * 64 * 16384 + part * 2048 + tid * 4; f32x4 st = (f32x4){0.f, 0.f, 0.f, 0.f};
; #pragma unroll 8
;     for (int i = 0; i < 64; ++i) { const f32x4 cur = *(const f32x4*)(KVT + e + (size_t)i * 16384); st_sc1_u2(RT + e + (size_t)i * 16384, pk2(st[0], st[1]), pk2(st[2], st[3])); st = cur + st * G; }
; }
	v_pk_fma_f32 v[12:13], v[4:5], v[12:13], v[144:145]
	v_pk_fma_f32 v[14:15], v[2:3], v[14:15], v[146:147]
	global_load_dwordx4 v[144:147], v[24:25], off nt
	v_lshl_add_u64 v[24:25], v[24:25], 0, s[42:43]
	v_cvt_pk_bf16_f32 v28, v12, v13
	v_cvt_pk_bf16_f32 v29, v14, v15
	global_store_dwordx2 v[26:27], v[28:29], off sc1
	v_lshl_add_u64 v[26:27], v[26:27], 0, s[46:47]
	s_waitcnt vmcnt(31)
	v_pk_fma_f32 v[12:13], v[4:5], v[12:13], v[148:149]
	v_pk_fma_f32 v[14:15], v[2:3], v[14:15], v[150:151]
	global_load_dwordx4 v[148:151], v[24:25], off nt
	v_lshl_add_u64 v[24:25], v[24:25], 0, s[42:43]
	v_cvt_pk_bf16_f32 v22, v12, v13
	v_cvt_pk_bf16_f32 v23, v14, v15
	global_store_dwordx2 v[26:27], v[22:23], off sc1
	v_lshl_add_u64 v[26:27], v[26:27], 0, s[46:47]
	s_waitcnt vmcnt(31)
	v_pk_fma_f32 v[12:13], v[4:5], v[12:13], v[152:153]
	v_pk_fma_f32 v[14:15], v[2:3], v[14:15], v[154:155]
	global_load_dwordx4 v[152:155], v[24:25], off nt
	v_lshl_add_u64 v[24:25], v[24:25], 0, s[42:43]
	v_cvt_pk_bf16_f32 v28, v12, v13
	v_cvt_pk_bf16_f32 v29, v14, v15
	global_store_dwordx2 v[26:27], v[28:29], off sc1
	v_lshl_add_u64 v[26:27], v[26:27], 0, s[46:47]
	s_waitcnt vmcnt(31)
	v_pk_fma_f32 v[12:13], v[4:5], v[12:13], v[156:157]
	v_pk_fma_f32 v[14:15], v[2:3], v[14:15], v[158:159]
	global_load_dwordx4 v[156:159], v[24:25], off nt
	v_lshl_add_u64 v[24:25], v[24:25], 0, s[42:43]
	v_cvt_pk_bf16_f32 v22, v12, v13
	v_cvt_pk_bf16_f32 v23, v14, v15
	global_store_dwordx2 v[26:27], v[22:23], off sc1
	v_lshl_add_u64 v[26:27], v[26:27], 0, s[46:47]
	s_waitcnt vmcnt(31)
	v_pk_fma_f32 v[12:13], v[4:5], v[12:13], v[160:161]
	v_pk_fma_f32 v[14:15], v[2:3], v[14:15], v[162:163]
	global_load_dwordx4 v[160:163], v[24:25], off nt
	v_lshl_add_u64 v[24:25], v[24:25], 0, s[42:43]
	v_cvt_pk_bf16_f32 v28, v12, v13
	v_cvt_pk_bf16_f32 v29, v14, v15
	global_store_dwordx2 v[26:27], v[28:29], off sc1
	v_lshl_add_u64 v[26:27], v[26:27], 0, s[46:47]
	s_waitcnt vmcnt(31)
	v_pk_fma_f32 v[12:13], v[4:5], v[12:13], v[164:165]
	v_pk_fma_f32 v[14:15], v[2:3], v[14:15], v[166:167]
	global_load_dwordx4 v[164:167], v[24:25], off nt
	v_lshl_add_u64 v[24:25], v[24:25], 0, s[42:43]
	v_cvt_pk_bf16_f32 v22, v12, v13
	v_cvt_pk_bf16_f32 v23, v14, v15
	global_store_dwordx2 v[26:27], v[22:23], off sc1
	v_lshl_add_u64 v[26:27], v[26:27], 0, s[46:47]
	s_waitcnt vmcnt(31)
	v_pk_fma_f32 v[12:13], v[4:5], v[12:13], v[168:169]
	v_pk_fma_f32 v[14:15], v[2:3], v[14:15], v[170:171]
	global_load_dwordx4 v[168:171], v[24:25], off nt
	v_lshl_add_u64 v[24:25], v[24:25], 0, s[42:43]
	v_cvt_pk_bf16_f32 v28, v12, v13
	v_cvt_pk_bf16_f32 v29, v14, v15
	global_store_dwordx2 v[26:27], v[28:29], off sc1
	v_lshl_add_u64 v[26:27], v[26:27], 0, s[46:47]
	s_waitcnt vmcnt(31)
	v_pk_fma_f32 v[12:13], v[4:5], v[12:13], v[172:173]
	v_pk_fma_f32 v[14:15], v[2:3], v[14:15], v[174:175]
	global_load_dwordx4 v[172:175], v[24:25], off nt
	v_lshl_add_u64 v[24:25], v[24:25], 0, s[42:43]
	v_cvt_pk_bf16_f32 v22, v12, v13
	v_cvt_pk_bf16_f32 v23, v14, v15
	global_store_dwordx2 v[26:27], v[22:23], off sc1
	v_lshl_add_u64 v[26:27], v[26:27], 0, s[46:47]
	s_waitcnt vmcnt(31)
	v_pk_fma_f32 v[12:13], v[4:5], v[12:13], v[176:177]
	v_pk_fma_f32 v[14:15], v[2:3], v[14:15], v[178:179]
	global_load_dwordx4 v[176:179], v[24:25], off nt
	v_lshl_add_u64 v[24:25], v[24:25], 0, s[42:43]
	v_cvt_pk_bf16_f32 v28, v12, v13
	v_cvt_pk_bf16_f32 v29, v14, v15
	global_store_dwordx2 v[26:27], v[28:29], off sc1
	v_lshl_add_u64 v[26:27], v[26:27], 0, s[46:47]
	s_waitcnt vmcnt(31)
	v_pk_fma_f32 v[12:13], v[4:5], v[12:13], v[180:181]
	v_pk_fma_f32 v[14:15], v[2:3], v[14:15], v[182:183]
	global_load_dwordx4 v[180:183], v[24:25], off nt
	v_lshl_add_u64 v[24:25], v[24:25], 0, s[42:43]
	v_cvt_pk_bf16_f32 v22, v12, v13
	v_cvt_pk_bf16_f32 v23, v14, v15
	global_store_dwordx2 v[26:27], v[22:23], off sc1
	v_lshl_add_u64 v[26:27], v[26:27], 0, s[46:47]
	s_waitcnt vmcnt(31)
	v_pk_fma_f32 v[12:13], v[4:5], v[12:13], v[184:185]
	v_pk_fma_f32 v[14:15], v[2:3], v[14:15], v[186:187]
	global_load_dwordx4 v[184:187], v[24:25], off nt
	v_lshl_add_u64 v[24:25], v[24:25], 0, s[42:43]
	v_cvt_pk_bf16_f32 v28, v12, v13
	v_cvt_pk_bf16_f32 v29, v14, v15
	global_store_dwordx2 v[26:27], v[28:29], off sc1
	v_lshl_add_u64 v[26:27], v[26:27], 0, s[46:47]
	s_waitcnt vmcnt(31)
	v_pk_fma_f32 v[12:13], v[4:5], v[12:13], v[188:189]
	v_pk_fma_f32 v[14:15], v[2:3], v[14:15], v[190:191]
	global_load_dwordx4 v[188:191], v[24:25], off nt
	v_lshl_add_u64 v[24:25], v[24:25], 0, s[42:43]
	v_cvt_pk_bf16_f32 v22, v12, v13
	v_cvt_pk_bf16_f32 v23, v14, v15
	global_store_dwordx2 v[26:27], v[22:23], off sc1
	v_lshl_add_u64 v[26:27], v[26:27], 0, s[46:47]
	s_waitcnt vmcnt(31)
	v_pk_fma_f32 v[12:13], v[4:5], v[12:13], v[64:65]
	v_pk_fma_f32 v[14:15], v[2:3], v[14:15], v[66:67]
	v_cvt_pk_bf16_f32 v28, v12, v13
	v_cvt_pk_bf16_f32 v29, v14, v15
	global_store_dwordx2 v[26:27], v[28:29], off sc1
	v_lshl_add_u64 v[26:27], v[26:27], 0, s[46:47]
	s_waitcnt vmcnt(30)
	v_pk_fma_f32 v[12:13], v[4:5], v[12:13], v[68:69]
	v_pk_fma_f32 v[14:15], v[2:3], v[14:15], v[70:71]
	v_cvt_pk_bf16_f32 v22, v12, v13
	v_cvt_pk_bf16_f32 v23, v14, v15
	global_store_dwordx2 v[26:27], v[22:23], off sc1
	v_lshl_add_u64 v[26:27], v[26:27], 0, s[46:47]
	s_waitcnt vmcnt(29)
	v_pk_fma_f32 v[12:13], v[4:5], v[12:13], v[72:73]
	v_pk_fma_f32 v[14:15], v[2:3], v[14:15], v[74:75]
	v_cvt_pk_bf16_f32 v28, v12, v13
	v_cvt_pk_bf16_f32 v29, v14, v15
	global_store_dwordx2 v[26:27], v[28:29], off sc1
	v_lshl_add_u64 v[26:27], v[26:27], 0, s[46:47]
	s_waitcnt vmcnt(28)
; __device__ __forceinline__ unsigned pk2(float lo, float hi) { return pg8::cvt_pk_bf16(lo, hi); }
; __device__ __forceinline__ float ret_log2gamma(int h) { return log2f(1.f - exp2f(-5.f - (float)h)); }
; __device__ __forceinline__ void st_sc1_u2(void* p, unsigned lo, unsigned hi) { __hip_atomic_store((GAS unsigned long long*)p, ((unsigned long long)hi << 32) | (unsigned long long)lo, __ATOMIC_RELAXED, __HIP_MEMORY_SCOPE_AGENT); }
; __device__ __forceinline__ void scan_unit(const float* KVT, bfu* RT, int s) {
;     int tid = threadIdx.x; asm volatile("" : "+v"(tid)); const int lane = tid & 63, wid = __builtin_amdgcn_readfirstlane(tid >> 6); (void)lane; (void)wid;
;     const int bh = s >> 3, part = s & 7, h = bh % 6; const float G = exp2f(ret_log2gamma(h) * 128.f);
;     const size_t e = (size_t)bh * 64 * 16384 + part * 2048 + tid * 4; f32x4 st = (f32x4){0.f, 0.f, 0.f, 0.f};
; #pragma unroll 8
;     for (int i = 0; i < 64; ++i) { const f32x4 cur = *(const f32x4*)(KVT + e + (size_t)i * 16384); st_sc1_u2(RT + e + (size_t)i * 16384, pk2(st[0], st[1]), pk2(st[2], st[3])); st = cur + st * G; }
; }
	v_pk_fma_f32 v[12:13], v[4:5], v[12:13], v[76:77]
	v_pk_fma_f32 v[14:15], v[2:3], v[14:15], v[78:79]
	v_cvt_pk_bf16_f32 v22, v12, v13
	v_cvt_pk_bf16_f32 v23, v14, v15
	global_store_dwordx2 v[26:27], v[22:23], off sc1
	v_lshl_add_u64 v[26:27], v[26:27], 0, s[46:47]
	s_waitcnt vmcnt(27)
	v_pk_fma_f32 v[12:13], v[4:5], v[12:13], v[80:81]
	v_pk_fma_f32 v[14:15], v[2:3], v[14:15], v[82:83]
	v_cvt_pk_bf16_f32 v28, v12, v13
	v_cvt_pk_bf16_f32 v29, v14, v15
	global_store_dwordx2 v[26:27], v[28:29], off sc1
	v_lshl_add_u64 v[26:27], v[26:27], 0, s[46:47]
	s_waitcnt vmcnt(26)
	v_pk_fma_f32 v[12:13], v[4:5], v[12:13], v[84:85]
	v_pk_fma_f32 v[14:15], v[2:3], v[14:15], v[86:87]
	v_cvt_pk_bf16_f32 v22, v12, v13
	v_cvt_pk_bf16_f32 v23, v14, v15
	global_store_dwordx2 v[26:27], v[22:23], off sc1
	v_lshl_add_u64 v[26:27], v[26:27], 0, s[46:47]
	s_waitcnt vmcnt(25)
	v_pk_fma_f32 v[12:13], v[4:5], v[12:13], v[88:89]
	v_pk_fma_f32 v[14:15], v[2:3], v[14:15], v[90:91]
	v_cvt_pk_bf16_f32 v28, v12, v13
	v_cvt_pk_bf16_f32 v29, v14, v15
	global_store_dwordx2 v[26:27], v[28:29], off sc1
	v_lshl_add_u64 v[26:27], v[26:27], 0, s[46:47]
	s_waitcnt vmcnt(24)
	v_pk_fma_f32 v[12:13], v[4:5], v[12:13], v[92:93]
	v_pk_fma_f32 v[14:15], v[2:3], v[14:15], v[94:95]
	v_cvt_pk_bf16_f32 v22, v12, v13
	v_cvt_pk_bf16_f32 v23, v14, v15
	global_store_dwordx2 v[26:27], v[22:23], off sc1
	v_lshl_add_u64 v[26:27], v[26:27], 0, s[46:47]
	s_waitcnt vmcnt(23)
	v_pk_fma_f32 v[12:13], v[4:5], v[12:13], v[96:97]
	v_pk_fma_f32 v[14:15], v[2:3], v[14:15], v[98:99]
	v_cvt_pk_bf16_f32 v28, v12, v13
	v_cvt_pk_bf16_f32 v29, v14, v15
	global_store_dwordx2 v[26:27], v[28:29], off sc1
	v_lshl_add_u64 v[26:27], v[26:27], 0, s[46:47]
	s_waitcnt vmcnt(22)
	v_pk_fma_f32 v[12:13], v[4:5], v[12:13], v[100:101]
	v_pk_fma_f32 v[14:15], v[2:3], v[14:15], v[102:103]
	v_cvt_pk_bf16_f32 v22, v12, v13
	v_cvt_pk_bf16_f32 v23, v14, v15
	global_store_dwordx2 v[26:27], v[22:23], off sc1
	v_lshl_add_u64 v[26:27], v[26:27], 0, s[46:47]
	s_waitcnt vmcnt(21)
	v_pk_fma_f32 v[12:13], v[4:5], v[12:13], v[104:105]
	v_pk_fma_f32 v[14:15], v[2:3], v[14:15], v[106:107]
	v_cvt_pk_bf16_f32 v28, v12, v13
	v_cvt_pk_bf16_f32 v29, v14, v15
	global_store_dwordx2 v[26:27], v[28:29], off sc1
	v_lshl_add_u64 v[26:27], v[26:27], 0, s[46:47]
	s_waitcnt vmcnt(20)
	v_pk_fma_f32 v[12:13], v[4:5], v[12:13], v[108:109]
	v_pk_fma_f32 v[14:15], v[2:3], v[14:15], v[110:111]
	v_cvt_pk_bf16_f32 v22, v12, v13
	v_cvt_pk_bf16_f32 v23, v14, v15
	global_store_dwordx2 v[26:27], v[22:23], off sc1
	v_lshl_add_u64 v[26:27], v[26:27], 0, s[46:47]
	s_waitcnt vmcnt(19)
	v_pk_fma_f32 v[12:13], v[4:5], v[12:13], v[112:113]
	v_pk_fma_f32 v[14:15], v[2:3], v[14:15], v[114:115]
	v_cvt_pk_bf16_f32 v28, v12, v13
	v_cvt_pk_bf16_f32 v29, v14, v15
	global_store_dwordx2 v[26:27], v[28:29], off sc1
	v_lshl_add_u64 v[26:27], v[26:27], 0, s[46:47]
	s_waitcnt vmcnt(18)
	v_pk_fma_f32 v[12:13], v[4:5], v[12:13], v[116:117]
	v_pk_fma_f32 v[14:15], v[2:3], v[14:15], v[118:119]
	v_cvt_pk_bf16_f32 v22, v12, v13
	v_cvt_pk_bf16_f32 v23, v14, v15
	global_store_dwordx2 v[26:27], v[22:23], off sc1
	v_lshl_add_u64 v[26:27], v[26:27], 0, s[46:47]
	s_waitcnt vmcnt(17)
	v_pk_fma_f32 v[12:13], v[4:5], v[12:13], v[120:121]
	v_pk_fma_f32 v[14:15], v[2:3], v[14:15], v[122:123]
	v_cvt_pk_bf16_f32 v28, v12, v13
	v_cvt_pk_bf16_f32 v29, v14, v15
	global_store_dwordx2 v[26:27], v[28:29], off sc1
	v_lshl_add_u64 v[26:27], v[26:27], 0, s[46:47]
	s_waitcnt vmcnt(16)
	v_pk_fma_f32 v[12:13], v[4:5], v[12:13], v[124:125]
	v_pk_fma_f32 v[14:15], v[2:3], v[14:15], v[126:127]
	v_cvt_pk_bf16_f32 v22, v12, v13
	v_cvt_pk_bf16_f32 v23, v14, v15
	global_store_dwordx2 v[26:27], v[22:23], off sc1
	v_lshl_add_u64 v[26:27], v[26:27], 0, s[46:47]
	s_waitcnt vmcnt(15)
	v_pk_fma_f32 v[12:13], v[4:5], v[12:13], v[128:129]
	v_pk_fma_f32 v[14:15], v[2:3], v[14:15], v[130:131]
	v_cvt_pk_bf16_f32 v28, v12, v13
	v_cvt_pk_bf16_f32 v29, v14, v15
	global_store_dwordx2 v[26:27], v[28:29], off sc1
	v_lshl_add_u64 v[26:27], v[26:27], 0, s[46:47]
	s_waitcnt vmcnt(14)
	v_pk_fma_f32 v[12:13], v[4:5], v[12:13], v[132:133]
	v_pk_fma_f32 v[14:15], v[2:3], v[14:15], v[134:135]
	v_cvt_pk_bf16_f32 v22, v12, v13
	v_cvt_pk_bf16_f32 v23, v14, v15
	global_store_dwordx2 v[26:27], v[22:23], off sc1
	v_lshl_add_u64 v[26:27], v[26:27], 0, s[46:47]
	s_waitcnt vmcnt(13)
	v_pk_fma_f32 v[12:13], v[4:5], v[12:13], v[136:137]
	v_pk_fma_f32 v[14:15], v[2:3], v[14:15], v[138:139]
	v_cvt_pk_bf16_f32 v28, v12, v13
	v_cvt_pk_bf16_f32 v29, v14, v15
	global_store_dwordx2 v[26:27], v[28:29], off sc1
	v_lshl_add_u64 v[26:27], v[26:27], 0, s[46:47]
	s_waitcnt vmcnt(12)
	v_pk_fma_f32 v[12:13], v[4:5], v[12:13], v[140:141]
	v_pk_fma_f32 v[14:15], v[2:3], v[14:15], v[142:143]
	v_cvt_pk_bf16_f32 v22, v12, v13
	v_cvt_pk_bf16_f32 v23, v14, v15
	global_store_dwordx2 v[26:27], v[22:23], off sc1
	v_lshl_add_u64 v[26:27], v[26:27], 0, s[46:47]
	s_waitcnt vmcnt(11)
	v_pk_fma_f32 v[12:13], v[4:5], v[12:13], v[144:145]
	v_pk_fma_f32 v[14:15], v[2:3], v[14:15], v[146:147]
	v_cvt_pk_bf16_f32 v28, v12, v13
	v_cvt_pk_bf16_f32 v29, v14, v15
	global_store_dwordx2 v[26:27], v[28:29], off sc1
	v_lshl_add_u64 v[26:27], v[26:27], 0, s[46:47]
	s_waitcnt vmcnt(10)
	v_pk_fma_f32 v[12:13], v[4:5], v[12:13], v[148:149]
	v_pk_fma_f32 v[14:15], v[2:3], v[14:15], v[150:151]
	v_cvt_pk_bf16_f32 v22, v12, v13
	v_cvt_pk_bf16_f32 v23, v14, v15
	global_store_dwordx2 v[26:27], v[22:23], off sc1
	v_lshl_add_u64 v[26:27], v[26:27], 0, s[46:47]
	s_waitcnt vmcnt(9)
; #define LAS __attribute__((address_space(3)))
; __device__ __forceinline__ float fexp2(float x) { return __builtin_amdgcn_exp2f(x); }
; __device__ __forceinline__ float ret_log2gamma(int h) { return log2f(1.f - exp2f(-5.f - (float)h)); }
; template <bool SC> __device__ __forceinline__ void stage_tr(LAS bfu* dst, const bfu* src, int pitch, int tid, float lg) {
; #pragma unroll
;     for (int i = 0; i < 4; ++i) { const int id = tid + NTHR * i, c = id & 127, ch = id >> 7; const v4u v = *(const v4u*)(src + (size_t)c * pitch + ch * 8);
;         const float sc = SC ? fexp2(lg * (float)(127 - c)) : 1.f;
; __device__ __forceinline__ void kv_unit(LAS unsigned char* lds, const bfu* PROJ, float* KVT, int u) {
;     int tid = threadIdx.x; asm volatile("" : "+v"(tid)); const int lane = tid & 63, wid = __builtin_amdgcn_readfirstlane(tid >> 6); (void)lane; (void)wid;
;     const int bh = u >> 6, i = u & 63, b = bh / 6, h = bh % 6; const size_t row0 = (size_t)b * SEQ + (size_t)i * 128; const float lg = ret_log2gamma(h);
;     LAS bfu* Vt = (LAS bfu*)lds; LAS bfu* Kt = (LAS bfu*)(lds + TILE_B);
;     stage_tr<false>(Vt, PROJ + row0 * INW + C_RV + h * 128, INW, tid, 0.f);
;     stage_tr<true>(Kt, PROJ + row0 * INW + C_RK + h * 128, INW, tid, lg);
	v_pk_fma_f32 v[12:13], v[4:5], v[12:13], v[152:153]
	v_pk_fma_f32 v[14:15], v[2:3], v[14:15], v[154:155]
	v_cvt_pk_bf16_f32 v28, v12, v13
	v_cvt_pk_bf16_f32 v29, v14, v15
	global_store_dwordx2 v[26:27], v[28:29], off sc1
	v_lshl_add_u64 v[26:27], v[26:27], 0, s[46:47]
	s_waitcnt vmcnt(8)
	v_pk_fma_f32 v[12:13], v[4:5], v[12:13], v[156:157]
	v_pk_fma_f32 v[14:15], v[2:3], v[14:15], v[158:159]
	v_cvt_pk_bf16_f32 v22, v12, v13
	v_cvt_pk_bf16_f32 v23, v14, v15
	global_store_dwordx2 v[26:27], v[22:23], off sc1
	v_lshl_add_u64 v[26:27], v[26:27], 0, s[46:47]
	s_waitcnt vmcnt(7)
	v_pk_fma_f32 v[12:13], v[4:5], v[12:13], v[160:161]
	v_pk_fma_f32 v[14:15], v[2:3], v[14:15], v[162:163]
	v_cvt_pk_bf16_f32 v28, v12, v13
	v_cvt_pk_bf16_f32 v29, v14, v15
	global_store_dwordx2 v[26:27], v[28:29], off sc1
	v_lshl_add_u64 v[26:27], v[26:27], 0, s[46:47]
	s_waitcnt vmcnt(6)
	v_pk_fma_f32 v[12:13], v[4:5], v[12:13], v[164:165]
	v_pk_fma_f32 v[14:15], v[2:3], v[14:15], v[166:167]
	v_cvt_pk_bf16_f32 v22, v12, v13
	v_cvt_pk_bf16_f32 v23, v14, v15
	global_store_dwordx2 v[26:27], v[22:23], off sc1
	v_lshl_add_u64 v[26:27], v[26:27], 0, s[46:47]
	s_waitcnt vmcnt(5)
	v_pk_fma_f32 v[12:13], v[4:5], v[12:13], v[168:169]
	v_pk_fma_f32 v[14:15], v[2:3], v[14:15], v[170:171]
	v_cvt_pk_bf16_f32 v28, v12, v13
	v_cvt_pk_bf16_f32 v29, v14, v15
	global_store_dwordx2 v[26:27], v[28:29], off sc1
	v_lshl_add_u64 v[26:27], v[26:27], 0, s[46:47]
	s_waitcnt vmcnt(4)
	v_pk_fma_f32 v[12:13], v[4:5], v[12:13], v[172:173]
	v_pk_fma_f32 v[14:15], v[2:3], v[14:15], v[174:175]
	v_cvt_pk_bf16_f32 v22, v12, v13
	v_cvt_pk_bf16_f32 v23, v14, v15
	global_store_dwordx2 v[26:27], v[22:23], off sc1
	v_lshl_add_u64 v[26:27], v[26:27], 0, s[46:47]
	s_waitcnt vmcnt(3)
	v_pk_fma_f32 v[12:13], v[4:5], v[12:13], v[176:177]
	v_pk_fma_f32 v[14:15], v[2:3], v[14:15], v[178:179]
	v_cvt_pk_bf16_f32 v28, v12, v13
	v_cvt_pk_bf16_f32 v29, v14, v15
	global_store_dwordx2 v[26:27], v[28:29], off sc1
	v_lshl_add_u64 v[26:27], v[26:27], 0, s[46:47]
	s_waitcnt vmcnt(2)
	v_pk_fma_f32 v[12:13], v[4:5], v[12:13], v[180:181]
	v_pk_fma_f32 v[14:15], v[2:3], v[14:15], v[182:183]
	v_cvt_pk_bf16_f32 v22, v12, v13
	v_cvt_pk_bf16_f32 v23, v14, v15
	global_store_dwordx2 v[26:27], v[22:23], off sc1
	v_lshl_add_u64 v[26:27], v[26:27], 0, s[46:47]
	s_waitcnt vmcnt(1)
	v_pk_fma_f32 v[12:13], v[4:5], v[12:13], v[184:185]
	v_pk_fma_f32 v[14:15], v[2:3], v[14:15], v[186:187]
	v_cvt_pk_bf16_f32 v28, v12, v13
	v_cvt_pk_bf16_f32 v29, v14, v15
	global_store_dwordx2 v[26:27], v[28:29], off sc1
	v_lshl_add_u64 v[26:27], v[26:27], 0, s[46:47]
	s_waitcnt vmcnt(0)
	v_pk_fma_f32 v[12:13], v[4:5], v[12:13], v[188:189]
	v_pk_fma_f32 v[14:15], v[2:3], v[14:15], v[190:191]
	s_waitcnt vmcnt(0)
	s_mov_b64 s[46:47], 0
	s_mov_b64 s[42:43], 0
	s_barrier
	s_and_saveexec_b64 s[22:23], s[74:75]
	s_xor_b64 s[48:49], exec, s[22:23]
	s_add_u32 s34, s44, 0x300
	s_addc_u32 s35, s45, 0
	s_mov_b64 s[42:43], exec
	s_or_b64 exec, exec, s[48:49]
	s_and_b64 vcc, exec, s[46:47]
	s_cbranch_vccz .LBB0_275
.LBB0_272:
	s_mov_b32 s22, 21
	s_ashr_i32 s23, s22, 31
	s_lshl_b64 s[22:23], s[22:23], 3
	s_add_u32 s22, s0, s22
	s_addc_u32 s23, s1, s23
	s_load_dwordx2 s[34:35], s[22:23], 0x0
	s_mov_b32 s22, 21
	s_ashr_i32 s23, s22, 31
	s_lshl_b64 s[22:23], s[22:23], 3
	s_add_u32 s22, s0, s22
	s_addc_u32 s23, s1, s23
	s_ashr_i32 s44, s40, 6
	s_load_dwordx2 s[46:47], s[22:23], 0x0
	s_mul_hi_i32 s22, s44, 0x2aaaaaab
	s_lshr_b32 s23, s22, 31
	s_add_i32 s22, s22, s23
	s_mul_i32 s23, s22, 6
	s_sub_i32 s41, s44, s23
	v_cvt_f32_i32_e32 v0, s41
	s_ashr_i32 s23, s22, 31
	s_lshl_b32 s45, s40, 7
	s_lshl_b64 s[22:23], s[22:23], 13
	v_sub_f32_e32 v0, 0xc0a00000, v0
	v_cmp_gt_f32_e32 vcc, s64, v0
	s_and_b32 s45, s45, 0x1f80
	s_or_b32 s22, s22, s45
	v_cndmask_b32_e32 v2, 0, v241, vcc
	v_add_f32_e32 v0, v0, v2
	v_exp_f32_e32 v0, v0
	s_and_b64 s[48:49], vcc, exec
	s_cselect_b32 s45, 0xffffffc0, 0
	s_mulk_i32 s23, 0x3200
	v_ldexp_f32 v0, v0, s45
	v_sub_f32_e32 v0, 1.0, v0
	v_cmp_gt_f32_e32 vcc, s52, v0
	s_and_b64 s[48:49], vcc, exec
	s_cselect_b32 s45, 32, 0
	v_ldexp_f32 v0, v0, s45
	s_mul_hi_u32 s45, s22, 0x3200
	s_add_i32 s45, s45, s23
	s_mulk_i32 s22, 0x3200
	v_log_f32_e32 v0, v0
	s_waitcnt lgkmcnt(0)
	s_add_u32 s34, s34, s22
	s_addc_u32 s35, s35, s45
	s_lshl_b32 s22, s41, 7
	v_mov_b32_e32 v8, v232
	s_ashr_i32 s23, s22, 31
	v_cndmask_b32_e32 v2, 0, v242, vcc
	s_lshl_b64 s[22:23], s[22:23], 1
	v_and_b32_e32 v4, 0x7f, v8
	v_sub_f32_e32 v17, v0, v2
	s_add_u32 s22, s34, s22
	v_mul_u32_u24_e32 v0, 0x1900, v4
	s_addc_u32 s23, s35, s23
	v_lshlrev_b32_e32 v0, 1, v0
	v_lshl_add_u64 v[2:3], s[22:23], 0, v[0:1]
	s_mov_b64 s[22:23], 0x1ce00000
	v_ashrrev_i32_e32 v0, 4, v8
	v_lshl_add_u64 v[14:15], v[2:3], 0, s[22:23]
	v_and_b32_e32 v2, -8, v0
	v_ashrrev_i32_e32 v3, 31, v2
	v_lshl_add_u64 v[18:19], v[2:3], 1, v[14:15]
	v_mul_lo_u32 v0, v2, s65
	v_lshlrev_b32_e32 v9, 1, v4
	global_load_dwordx4 v[50:53], v[18:19], off offset:3072 nt
	v_add3_u32 v20, 0, v0, v9
	v_add_u32_e32 v0, 0x200, v8
	v_ashrrev_i32_e32 v0, 4, v0
	s_movk_i32 s22, 0x7f
	v_readfirstlane_b32 s20, v8
	s_ashr_i32 s20, s20, 2
	s_ashr_i32 s41, s40, 31
	v_and_b32_e32 v2, -8, v0
	v_ashrrev_i32_e32 v3, 31, v2
	v_lshl_add_u64 v[6:7], v[2:3], 1, v[14:15]
	v_mul_lo_u32 v0, v2, s65
	global_load_dwordx4 v[54:57], v[6:7], off offset:3072 nt
	v_add3_u32 v21, 0, v0, v9
	v_add_u32_e32 v0, 0x400, v8
	v_ashrrev_i32_e32 v0, 4, v0
	v_and_b32_e32 v2, -8, v0
	v_ashrrev_i32_e32 v3, 31, v2
	v_lshl_add_u64 v[4:5], v[2:3], 1, v[14:15]
	global_load_dwordx4 v[58:61], v[4:5], off offset:3072 nt
	v_mul_lo_u32 v0, v2, s65
	v_add3_u32 v22, 0, v0, v9
	v_add_u32_e32 v0, 0x600, v8
	v_ashrrev_i32_e32 v0, 4, v0
	v_and_b32_e32 v10, -8, v0
	v_ashrrev_i32_e32 v11, 31, v10
	v_lshl_add_u64 v[2:3], v[10:11], 1, v[14:15]
	v_mul_lo_u32 v0, v10, s65
	global_load_dwordx4 v[62:65], v[2:3], off offset:3072 nt
	v_add3_u32 v9, 0, v0, v9
	v_bitop3_b32 v0, v8, s22, v8 bitop3:0xc
	v_cvt_f32_ubyte0_e32 v0, v0
	v_mul_f32_e32 v0, v17, v0
	v_exp_f32_e32 v0, v0
	v_bfi_b32 v17, -16, s20, v8
	s_mov_b32 s20, 0x30600000
	global_load_dwordx4 v[66:69], v[18:19], off offset:1536 nt
	v_mov_b32_e32 v70, v0
	v_mov_b32_e32 v71, v1
	global_load_dwordx4 v[92:95], v[6:7], off offset:1536 nt
	global_load_dwordx4 v[120:123], v[4:5], off offset:1536 nt
	global_load_dwordx4 v[146:149], v[2:3], off offset:1536 nt
	s_waitcnt vmcnt(7)
; #define LAS __attribute__((address_space(3)))
; __device__ __forceinline__ unsigned pk2(float lo, float hi) { return pg8::cvt_pk_bf16(lo, hi); }
; __device__ __forceinline__ float fexp2(float x) { return __builtin_amdgcn_exp2f(x); }
; template <bool SC> __device__ __forceinline__ void stage_tr(LAS bfu* dst, const bfu* src, int pitch, int tid, float lg) {
; #pragma unroll
;     for (int i = 0; i < 4; ++i) { const int id = tid + NTHR * i, c = id & 127, ch = id >> 7; const v4u v = *(const v4u*)(src + (size_t)c * pitch + ch * 8);
;         const float sc = SC ? fexp2(lg * (float)(127 - c)) : 1.f;
; #pragma unroll
;         for (int j = 0; j < 4; ++j) { unsigned w = v[j];
;             if (SC) w = pk2(bflo(w) * sc, bfhi(w) * sc);
;             dst[(ch * 8 + 2 * j) * TS + c] = (bfu)(w & 0xffffu); dst[(ch * 8 + 2 * j + 1) * TS + c] = (bfu)(w >> 16); } }
	ds_write_b16 v20, v50
	ds_write_b16_d16_hi v20, v50 offset:272
	ds_write_b16 v20, v51 offset:544
	ds_write_b16_d16_hi v20, v51 offset:816
	ds_write_b16 v20, v52 offset:1088
	ds_write_b16_d16_hi v20, v52 offset:1360
	ds_write_b16 v20, v53 offset:1632
	ds_write_b16_d16_hi v20, v53 offset:1904
	s_waitcnt vmcnt(6)
	ds_write_b16 v21, v54
	ds_write_b16_d16_hi v21, v54 offset:272
	ds_write_b16 v21, v55 offset:544
	ds_write_b16_d16_hi v21, v55 offset:816
	ds_write_b16 v21, v56 offset:1088
	ds_write_b16_d16_hi v21, v56 offset:1360
	ds_write_b16 v21, v57 offset:1632
	ds_write_b16_d16_hi v21, v57 offset:1904
	s_waitcnt vmcnt(5)
	ds_write_b16 v22, v58
	ds_write_b16_d16_hi v22, v58 offset:272
	ds_write_b16 v22, v59 offset:544
	ds_write_b16_d16_hi v22, v59 offset:816
	ds_write_b16 v22, v60 offset:1088
	ds_write_b16_d16_hi v22, v60 offset:1360
	ds_write_b16 v22, v61 offset:1632
	ds_write_b16_d16_hi v22, v61 offset:1904
	s_waitcnt vmcnt(4)
	ds_write_b16 v9, v62
	ds_write_b16_d16_hi v9, v62 offset:272
	ds_write_b16 v9, v63 offset:544
	ds_write_b16_d16_hi v9, v63 offset:816
	ds_write_b16 v9, v64 offset:1088
	ds_write_b16_d16_hi v9, v64 offset:1360
	ds_write_b16 v9, v65 offset:1632
	ds_write_b16_d16_hi v9, v65 offset:1904
	s_waitcnt vmcnt(3)
	v_lshlrev_b32_e32 v46, 16, v66
	v_and_b32_e32 v47, 0xffff0000, v66
	v_pk_mul_f32 v[72:73], v[70:71], v[46:47] op_sel_hi:[0,1]
	v_cvt_pk_bf16_f32 v49, v72, v73
	ds_write_b16 v20, v49 offset:34816
	ds_write_b16_d16_hi v20, v49 offset:35088
	v_lshlrev_b32_e32 v74, 16, v67
	v_and_b32_e32 v75, 0xffff0000, v67
	v_pk_mul_f32 v[76:77], v[70:71], v[74:75] op_sel_hi:[0,1]
	v_cvt_pk_bf16_f32 v78, v76, v77
	ds_write_b16 v20, v78 offset:35360
	ds_write_b16_d16_hi v20, v78 offset:35632
	v_lshlrev_b32_e32 v80, 16, v68
	v_and_b32_e32 v81, 0xffff0000, v68
	v_pk_mul_f32 v[82:83], v[70:71], v[80:81] op_sel_hi:[0,1]
	v_cvt_pk_bf16_f32 v79, v82, v83
	ds_write_b16 v20, v79 offset:35904
	ds_write_b16_d16_hi v20, v79 offset:36176
	v_lshlrev_b32_e32 v84, 16, v69
	v_and_b32_e32 v85, 0xffff0000, v69
	v_pk_mul_f32 v[86:87], v[70:71], v[84:85] op_sel_hi:[0,1]
	v_cvt_pk_bf16_f32 v88, v86, v87
	ds_write_b16 v20, v88 offset:36448
	ds_write_b16_d16_hi v20, v88 offset:36720
	s_waitcnt vmcnt(2)
	v_lshlrev_b32_e32 v96, 16, v92
	v_and_b32_e32 v97, 0xffff0000, v92
	v_pk_mul_f32 v[98:99], v[70:71], v[96:97] op_sel_hi:[0,1]
	v_cvt_pk_bf16_f32 v100, v98, v99
	ds_write_b16 v21, v100 offset:34816
	ds_write_b16_d16_hi v21, v100 offset:35088
	v_lshlrev_b32_e32 v102, 16, v93
	v_and_b32_e32 v103, 0xffff0000, v93
	v_pk_mul_f32 v[104:105], v[70:71], v[102:103] op_sel_hi:[0,1]
	v_cvt_pk_bf16_f32 v101, v104, v105
	ds_write_b16 v21, v101 offset:35360
	ds_write_b16_d16_hi v21, v101 offset:35632
	v_lshlrev_b32_e32 v106, 16, v94
	v_and_b32_e32 v107, 0xffff0000, v94
	v_pk_mul_f32 v[108:109], v[70:71], v[106:107] op_sel_hi:[0,1]
	v_cvt_pk_bf16_f32 v110, v108, v109
	ds_write_b16 v21, v110 offset:35904
	ds_write_b16_d16_hi v21, v110 offset:36176
	v_lshlrev_b32_e32 v112, 16, v95
	v_and_b32_e32 v113, 0xffff0000, v95
	v_pk_mul_f32 v[114:115], v[70:71], v[112:113] op_sel_hi:[0,1]
	v_cvt_pk_bf16_f32 v118, v114, v115
	ds_write_b16 v21, v118 offset:36448
	ds_write_b16_d16_hi v21, v118 offset:36720
	s_waitcnt vmcnt(1)
	v_lshlrev_b32_e32 v124, 16, v120
	v_and_b32_e32 v125, 0xffff0000, v120
	v_pk_mul_f32 v[126:127], v[70:71], v[124:125] op_sel_hi:[0,1]
	v_cvt_pk_bf16_f32 v116, v126, v127
	ds_write_b16 v22, v116 offset:34816
	ds_write_b16_d16_hi v22, v116 offset:35088
	v_lshlrev_b32_e32 v128, 16, v121
	v_and_b32_e32 v129, 0xffff0000, v121
	v_pk_mul_f32 v[130:131], v[70:71], v[128:129] op_sel_hi:[0,1]
	v_cvt_pk_bf16_f32 v111, v130, v131
	ds_write_b16 v22, v111 offset:35360
	ds_write_b16_d16_hi v22, v111 offset:35632
	v_lshlrev_b32_e32 v132, 16, v122
	v_and_b32_e32 v133, 0xffff0000, v122
	v_pk_mul_f32 v[134:135], v[70:71], v[132:133] op_sel_hi:[0,1]
	v_cvt_pk_bf16_f32 v136, v134, v135
	ds_write_b16 v22, v136 offset:35904
	ds_write_b16_d16_hi v22, v136 offset:36176
	v_lshlrev_b32_e32 v138, 16, v123
	v_and_b32_e32 v139, 0xffff0000, v123
	v_pk_mul_f32 v[140:141], v[70:71], v[138:139] op_sel_hi:[0,1]
	v_cvt_pk_bf16_f32 v144, v140, v141
	ds_write_b16 v22, v144 offset:36448
	ds_write_b16_d16_hi v22, v144 offset:36720
	s_waitcnt vmcnt(0)
	v_lshlrev_b32_e32 v150, 16, v146
	v_and_b32_e32 v151, 0xffff0000, v146
	v_pk_mul_f32 v[152:153], v[70:71], v[150:151] op_sel_hi:[0,1]
	v_cvt_pk_bf16_f32 v142, v152, v153
	ds_write_b16 v9, v142 offset:34816
	ds_write_b16_d16_hi v9, v142 offset:35088
	v_lshlrev_b32_e32 v154, 16, v147
	v_and_b32_e32 v155, 0xffff0000, v147
	v_pk_mul_f32 v[156:157], v[70:71], v[154:155] op_sel_hi:[0,1]
	v_cvt_pk_bf16_f32 v137, v156, v157
	ds_write_b16 v9, v137 offset:35360
	ds_write_b16_d16_hi v9, v137 offset:35632
	v_lshlrev_b32_e32 v158, 16, v148
	v_and_b32_e32 v159, 0xffff0000, v148
	v_pk_mul_f32 v[160:161], v[70:71], v[158:159] op_sel_hi:[0,1]
	v_cvt_pk_bf16_f32 v162, v160, v161
	ds_write_b16 v9, v162 offset:35904
	ds_write_b16_d16_hi v9, v162 offset:36176
	v_lshlrev_b32_e32 v164, 16, v149
	v_and_b32_e32 v165, 0xffff0000, v149
	v_pk_mul_f32 v[166:167], v[70:71], v[164:165] op_sel_hi:[0,1]
	v_cvt_pk_bf16_f32 v163, v166, v167
	ds_write_b16 v9, v163 offset:36448
	ds_write_b16_d16_hi v9, v163 offset:36720
	v_and_b32_e32 v0, 48, v8
	v_and_b32_e32 v9, 15, v8
	v_add_u32_e32 v8, 0, v0
	v_mad_u64_u32 v[2:3], s[22:23], v17, s65, v[8:9]
	v_mad_u32_u24 v3, v9, s65, v8
	s_waitcnt lgkmcnt(0)
	s_barrier
; #define LAS __attribute__((address_space(3)))
; #define ZERO8(a) do { _Pragma("unroll") for (int t_ = 0; t_ < 8; ++t_) a[t_] = (f32x4){0.f, 0.f, 0.f, 0.f}; } while (0)
; __device__ __forceinline__ void st_sc1_x4(float* p, f32x4 v) { st_sc1_u2(p, __float_as_uint(v[0]), __float_as_uint(v[1])); st_sc1_u2(p + 2, __float_as_uint(v[2]), __float_as_uint(v[3])); }
; __device__ __forceinline__ void wave_mma(f32x4 (&acc)[8], const LAS bfu* As, const LAS bfu* Bs, int m0, int fr, int fq) {
; #pragma unroll
;     for (int ks = 0; ks < 4; ++ks) { const bf16x8 a = *(const LAS bf16x8*)(As + (m0 + fr) * TS + ks * 32 + fq * 8);
; #pragma unroll
;         for (int t = 0; t < 8; ++t) { const bf16x8 b = *(const LAS bf16x8*)(Bs + (t * 16 + fr) * TS + ks * 32 + fq * 8); acc[t] = __builtin_amdgcn_mfma_f32_16x16x32_bf16(b, a, acc[t], 0, 0, 0); } }
; }
; __device__ __forceinline__ void kv_unit(LAS unsigned char* lds, const bfu* PROJ, float* KVT, int u) {
;     ...
;     const int fr = lane & 15, fq = lane >> 4, m0 = wid * 16; f32x4 acc[8]; ZERO8(acc);
;     wave_mma(acc, Vt, Kt, m0, fr, fq);
;     float* o = KVT + (size_t)u * 16384 + (m0 + fr) * 128 + 4 * fq;
; #pragma unroll
;     for (int t = 0; t < 8; ++t) st_sc1_x4(o + 16 * t, acc[t]);
	s_waitcnt lgkmcnt(0)
	ds_read_b128 v[52:55], v2
	ds_read_b128 v[56:59], v3 offset:34816
	ds_read_b128 v[60:63], v3 offset:39168
	ds_read_b128 v[64:67], v3 offset:43520
	ds_read_b128 v[68:71], v3 offset:47872
	ds_read_b128 v[72:75], v3 offset:52224
	ds_read_b128 v[76:79], v3 offset:56576
	ds_read_b128 v[80:83], v3 offset:60928
	ds_read_b128 v[84:87], v3 offset:65280
	ds_read_b128 v[88:91], v2 offset:64
	ds_read_b128 v[92:95], v3 offset:34880
	ds_read_b128 v[96:99], v3 offset:39232
	s_waitcnt lgkmcnt(10)
	v_mfma_f32_16x16x32_bf16 v[8:11], v[56:59], v[52:55], 0
	s_lshl_b64 s[22:23], s[40:41], 16
	s_add_u32 s22, s46, s22
	s_addc_u32 s23, s47, s23
	ds_read_b128 v[56:59], v3 offset:43584
	s_waitcnt lgkmcnt(10)
	v_mfma_f32_16x16x32_bf16 v[12:15], v[60:63], v[52:55], 0
	ds_read_b128 v[60:63], v3 offset:47936
	s_waitcnt lgkmcnt(10)
	v_mfma_f32_16x16x32_bf16 v[18:21], v[64:67], v[52:55], 0
	ds_read_b128 v[64:67], v3 offset:52288
	s_waitcnt lgkmcnt(10)
	v_mfma_f32_16x16x32_bf16 v[22:25], v[68:71], v[52:55], 0
	ds_read_b128 v[68:71], v3 offset:56640
	s_waitcnt lgkmcnt(10)
	v_mfma_f32_16x16x32_bf16 v[26:29], v[72:75], v[52:55], 0
	ds_read_b128 v[72:75], v3 offset:60992
	s_waitcnt lgkmcnt(10)
	v_mfma_f32_16x16x32_bf16 v[30:33], v[76:79], v[52:55], 0
	ds_read_b128 v[76:79], v3 offset:65344
	s_waitcnt lgkmcnt(10)
	v_mfma_f32_16x16x32_bf16 v[34:37], v[80:83], v[52:55], 0
	ds_read_b128 v[80:83], v2 offset:128
	s_waitcnt lgkmcnt(10)
	v_mfma_f32_16x16x32_bf16 v[4:7], v[84:87], v[52:55], 0
	ds_read_b128 v[52:55], v3 offset:34944
	ds_read_b128 v[84:87], v3 offset:39296
	s_waitcnt lgkmcnt(10)
	v_mfma_f32_16x16x32_bf16 v[8:11], v[92:95], v[88:91], v[8:11]
	ds_read_b128 v[92:95], v3 offset:43648
	s_waitcnt lgkmcnt(10)
	v_mfma_f32_16x16x32_bf16 v[12:15], v[96:99], v[88:91], v[12:15]
	ds_read_b128 v[96:99], v3 offset:48000
	s_waitcnt lgkmcnt(10)
	v_mfma_f32_16x16x32_bf16 v[18:21], v[56:59], v[88:91], v[18:21]
	ds_read_b128 v[56:59], v3 offset:52352
	s_waitcnt lgkmcnt(10)
	v_mfma_f32_16x16x32_bf16 v[22:25], v[60:63], v[88:91], v[22:25]
	ds_read_b128 v[60:63], v3 offset:56704
	s_waitcnt lgkmcnt(10)
	v_mfma_f32_16x16x32_bf16 v[26:29], v[64:67], v[88:91], v[26:29]
	ds_read_b128 v[64:67], v3 offset:61056
	s_waitcnt lgkmcnt(10)
	v_mfma_f32_16x16x32_bf16 v[30:33], v[68:71], v[88:91], v[30:33]
	ds_read_b128 v[68:71], v3 offset:65408
	s_waitcnt lgkmcnt(10)
	v_mfma_f32_16x16x32_bf16 v[34:37], v[72:75], v[88:91], v[34:37]
	ds_read_b128 v[72:75], v2 offset:192
	s_waitcnt lgkmcnt(10)
	v_mfma_f32_16x16x32_bf16 v[4:7], v[76:79], v[88:91], v[4:7]
	ds_read_b128 v[76:79], v3 offset:35008
	ds_read_b128 v[88:91], v3 offset:39360
	s_waitcnt lgkmcnt(10)
	v_mfma_f32_16x16x32_bf16 v[8:11], v[52:55], v[80:83], v[8:11]
	ds_read_b128 v[52:55], v3 offset:43712
	s_waitcnt lgkmcnt(10)
	v_mfma_f32_16x16x32_bf16 v[12:15], v[84:87], v[80:83], v[12:15]
	ds_read_b128 v[84:87], v3 offset:48064
	s_waitcnt lgkmcnt(10)
	v_mfma_f32_16x16x32_bf16 v[18:21], v[92:95], v[80:83], v[18:21]
	ds_read_b128 v[92:95], v3 offset:52416
	s_waitcnt lgkmcnt(10)
	v_mfma_f32_16x16x32_bf16 v[22:25], v[96:99], v[80:83], v[22:25]
	ds_read_b128 v[96:99], v3 offset:56768
	s_waitcnt lgkmcnt(10)
	v_mfma_f32_16x16x32_bf16 v[26:29], v[56:59], v[80:83], v[26:29]
	ds_read_b128 v[56:59], v3 offset:61120
	s_waitcnt lgkmcnt(10)
	v_mfma_f32_16x16x32_bf16 v[30:33], v[60:63], v[80:83], v[30:33]
	ds_read_b128 v[60:63], v3 offset:65472
	s_waitcnt lgkmcnt(10)
	v_mfma_f32_16x16x32_bf16 v[34:37], v[64:67], v[80:83], v[34:37]
	s_waitcnt lgkmcnt(9)
	v_mfma_f32_16x16x32_bf16 v[4:7], v[68:71], v[80:83], v[4:7]
	s_waitcnt lgkmcnt(7)
	v_mfma_f32_16x16x32_bf16 v[8:11], v[76:79], v[72:75], v[8:11]
	s_waitcnt lgkmcnt(6)
	v_mfma_f32_16x16x32_bf16 v[12:15], v[88:91], v[72:75], v[12:15]
	s_waitcnt lgkmcnt(5)
	v_mfma_f32_16x16x32_bf16 v[18:21], v[52:55], v[72:75], v[18:21]
	s_waitcnt lgkmcnt(4)
	v_mfma_f32_16x16x32_bf16 v[22:25], v[84:87], v[72:75], v[22:25]
	s_waitcnt lgkmcnt(3)
	v_mfma_f32_16x16x32_bf16 v[26:29], v[92:95], v[72:75], v[26:29]
	s_waitcnt lgkmcnt(2)
	v_mfma_f32_16x16x32_bf16 v[30:33], v[96:99], v[72:75], v[30:33]
	s_waitcnt lgkmcnt(1)
	v_mfma_f32_16x16x32_bf16 v[34:37], v[56:59], v[72:75], v[34:37]
	s_waitcnt lgkmcnt(0)
	v_mfma_f32_16x16x32_bf16 v[2:5], v[60:63], v[72:75], v[4:7]
	s_nop 2
	s_waitcnt lgkmcnt(0)
	v_lshlrev_b32_e32 v6, 7, v17
	v_ashrrev_i32_e32 v7, 31, v6
	v_lshl_add_u64 v[6:7], v[6:7], 2, s[22:23]
	v_lshl_add_u64 v[6:7], v[6:7], 0, v[0:1]
	s_mov_b64 s[22:23], 0x30600000
	v_lshl_add_u64 v[38:39], v[6:7], 0, s[22:23]
	v_add_co_u32_e32 v6, vcc, s20, v6
	s_nop 1
	v_addc_co_u32_e32 v7, vcc, 0, v7, vcc
	global_store_dwordx4 v[38:39], v[8:11], off sc1
	global_store_dwordx4 v[38:39], v[12:15], off offset:64 sc1
	global_store_dwordx4 v[38:39], v[18:21], off offset:128 sc1
	global_store_dwordx4 v[38:39], v[22:25], off offset:192 sc1
	global_store_dwordx4 v[38:39], v[26:29], off offset:256 sc1
	global_store_dwordx4 v[38:39], v[30:33], off offset:320 sc1
	global_store_dwordx4 v[38:39], v[34:37], off offset:384 sc1
	global_store_dwordx4 v[38:39], v[2:5], off offset:448 sc1
	s_waitcnt vmcnt(0)
	s_barrier
	s_and_saveexec_b64 s[40:41], s[74:75]
	s_ashr_i32 s45, s44, 31
	s_lshl_b64 s[22:23], s[44:45], 2
	s_add_u32 s20, s4, s22
	s_addc_u32 s22, s5, s23
	s_add_u32 s34, s20, 0x200
	s_addc_u32 s35, s22, 0
	s_or_b64 s[42:43], s[42:43], exec
	s_or_b64 exec, exec, s[40:41]

; #define LAS __attribute__((address_space(3)))
; __device__ __forceinline__ float fexp2(float x) { return __builtin_amdgcn_exp2f(x); }
; __device__ __forceinline__ float ret_log2gamma(int h) { return log2f(1.f - exp2f(-5.f - (float)h)); }
; __device__ __forceinline__ void stage_nat(LAS bfu* dst, const bfu* src, int pitch, int tid) {
; #pragma unroll
;     for (int i = 0; i < 4; ++i) { const int id = tid + NTHR * i, r = id >> 4, ch = id & 15; const v4u v = *(const v4u*)(src + (size_t)r * pitch + ch * 8); *(LAS v4u*)(dst + r * TS + ch * 8) = v; }
; }
; template <bool SC> __device__ __forceinline__ void stage_tr(LAS bfu* dst, const bfu* src, int pitch, int tid, float lg) {
; #pragma unroll
;     for (int i = 0; i < 4; ++i) { const int id = tid + NTHR * i, c = id & 127, ch = id >> 7; const v4u v = *(const v4u*)(src + (size_t)c * pitch + ch * 8);
;         const float sc = SC ? fexp2(lg * (float)(127 - c)) : 1.f;
; __device__ __forceinline__ void ret_unit(LAS unsigned char* lds, const bfu* PROJ, const bfu* RT, const float* gn_g, bfu* CAT, int u) {
;     int tid = threadIdx.x; asm volatile("" : "+v"(tid)); const int lane = tid & 63, wid = __builtin_amdgcn_readfirstlane(tid >> 6); (void)lane; (void)wid;
;     const int bh = u >> 6, i = u & 63, b = bh / 6, h = bh % 6; const size_t row0 = (size_t)b * SEQ + (size_t)i * 128; const float lg = ret_log2gamma(h);
;     LAS bfu* Qs = (LAS bfu*)lds; LAS bfu* Ks = (LAS bfu*)(lds + TILE_B); LAS bfu* Vt = (LAS bfu*)(lds + 2 * TILE_B); LAS bfu* Rt = (LAS bfu*)(lds + 3 * TILE_B);
;     const bfu* P0 = PROJ + row0 * INW + h * 128;
;     stage_nat(Qs, P0 + C_RQ, INW, tid); stage_nat(Ks, P0 + C_RK, INW, tid); stage_tr<false>(Vt, P0 + C_RV, INW, tid, 0.f); stage_nat(Rt, RT + (size_t)u * 16384, 128, tid);
.LBB0_410:
	s_or_b64 exec, exec, s[40:41]
	s_mov_b32 s22, 21
	s_barrier
	s_ashr_i32 s23, s22, 31
	s_lshl_b64 s[22:23], s[22:23], 3
	s_add_u32 s22, s0, s22
	s_addc_u32 s23, s1, s23
	s_load_dwordx2 s[48:49], s[22:23], 0x0
	s_mov_b32 s22, 21
	s_ashr_i32 s23, s22, 31
	s_lshl_b64 s[22:23], s[22:23], 3
	s_add_u32 s22, s0, s22
	s_addc_u32 s23, s1, s23
	s_load_dwordx2 s[40:41], s[22:23], 0x0
	s_mov_b32 s22, 3
	s_ashr_i32 s23, s22, 31
	s_lshl_b64 s[22:23], s[22:23], 3
	s_add_u32 s22, s0, s22
	s_addc_u32 s23, s1, s23
	s_load_dwordx2 s[22:23], s[22:23], 0x0
	v_mov_b32_e32 v10, v232
	v_readlane_b32 s91, v255, 54
	s_waitcnt lgkmcnt(0)
	s_add_u32 s20, s22, s36
	s_mov_b32 s22, 21
	s_addc_u32 s35, s23, s37
	s_ashr_i32 s23, s22, 31
	s_lshl_b64 s[22:23], s[22:23], 3
	s_add_u32 s22, s0, s22
	s_addc_u32 s23, s1, s23
	s_load_dwordx2 s[44:45], s[22:23], 0x0
	s_mul_hi_i32 s23, s34, 0x2aaaaaab
	s_lshr_b32 s46, s23, 31
	s_add_i32 s46, s23, s46
	s_mul_i32 s23, s46, 6
	s_sub_i32 s23, s34, s23
	v_cvt_f32_i32_e32 v0, s23
	s_ashr_i32 s47, s46, 31
	s_lshl_b32 s34, s92, 7
	s_lshl_b64 s[46:47], s[46:47], 13
	v_sub_f32_e32 v0, 0xc0a00000, v0
	v_cmp_gt_f32_e32 vcc, s64, v0
	s_and_b32 s34, s34, 0x1f80
	s_or_b32 s46, s46, s34
	v_cndmask_b32_e32 v2, 0, v241, vcc
	v_add_f32_e32 v0, v0, v2
	v_exp_f32_e32 v0, v0
	s_and_b64 s[50:51], vcc, exec
	s_cselect_b32 s34, 0xffffffc0, 0
	s_mul_hi_u32 s50, s46, 0x3200
	v_ldexp_f32 v0, v0, s34
	s_mul_i32 s34, s47, 0x3200
	s_add_i32 s50, s50, s34
	s_mul_i32 s34, s46, 0x3200
	s_add_u32 s34, s48, s34
	s_addc_u32 s48, s49, s50
	s_lshl_b32 s50, s23, 7
	s_ashr_i32 s51, s50, 31
	s_lshl_b64 s[52:53], s[50:51], 1
	s_add_u32 s23, s34, s52
	s_addc_u32 s34, s48, s53
	v_sub_f32_e32 v11, 1.0, v0
	s_add_u32 s56, s23, 0x1ce00000
	v_lshlrev_b32_e32 v0, 4, v10
	s_addc_u32 s57, s34, 0
	v_and_b32_e32 v0, 0xf0, v0
	v_lshl_add_u64 v[16:17], s[56:57], 0, v[0:1]
	v_ashrrev_i32_e32 v2, 4, v10
	v_mad_i64_i32 v[18:19], s[48:49], v2, s61, v[16:17]
	global_load_dwordx4 v[120:123], v[18:19], off nt
	v_add_u32_e32 v26, 0, v0
	v_mul_lo_u32 v27, v2, s65
	v_add_u32_e32 v28, v26, v27
	s_ashr_i32 s93, s92, 31
	v_ashrrev_i32_e32 v3, 31, v2
	v_readfirstlane_b32 s22, v10
	v_bfe_u32 v71, v10, 4, 2
	v_lshlrev_b32_e32 v69, 4, v71
	v_add_u32_e32 v4, 0x200, v10
	v_ashrrev_i32_e32 v4, 4, v4
	v_mad_i64_i32 v[20:21], s[48:49], v4, s61, v[16:17]
	global_load_dwordx4 v[124:127], v[20:21], off nt
	v_mul_lo_u32 v29, v4, s65
	v_add_u32_e32 v30, v26, v29
	v_ashrrev_i32_e32 v5, 31, v4
	v_add_u32_e32 v6, 0x400, v10
	v_ashrrev_i32_e32 v6, 4, v6
	v_mad_i64_i32 v[22:23], s[48:49], v6, s61, v[16:17]
	global_load_dwordx4 v[128:131], v[22:23], off nt
	v_add_u32_e32 v8, 0x600, v10
	v_mul_lo_u32 v31, v6, s65
	v_ashrrev_i32_e32 v8, 4, v8
	v_add_u32_e32 v32, v26, v31
	v_mad_i64_i32 v[24:25], s[48:49], v8, s61, v[16:17]
	s_lshl_b64 s[48:49], s[92:93], 15
	s_add_u32 s40, s40, s48
	s_addc_u32 s41, s41, s49
	v_ashrrev_i32_e32 v7, 31, v6
	v_ashrrev_i32_e32 v9, 31, v8
	s_ashr_i32 s34, s22, 2
	s_mov_b32 s22, 0x800000
	v_cmp_gt_f32_e32 vcc, s22, v11
	s_and_b64 s[22:23], vcc, exec
	s_cselect_b32 s22, 32, 0
	v_bfi_b32 v66, -16, s34, v10
	global_load_dwordx4 v[132:135], v[24:25], off nt
	v_mul_lo_u32 v12, v8, s65
	v_add_u32_e32 v13, v26, v12
	v_mov_b32_e32 v119, v13
	global_load_dwordx4 v[136:139], v[18:19], off offset:1536 nt
	global_load_dwordx4 v[140:143], v[20:21], off offset:1536 nt
	global_load_dwordx4 v[144:147], v[22:23], off offset:1536 nt
	global_load_dwordx4 v[148:151], v[24:25], off offset:1536 nt
	v_and_b32_e32 v13, 0x7f, v10
	v_mul_u32_u24_e32 v14, 0x1900, v13
	v_lshlrev_b32_e32 v14, 1, v14
	v_mov_b32_e32 v15, v1
	v_lshl_add_u64 v[18:19], s[56:57], 0, v[14:15]
	v_and_b32_e32 v14, -8, v2
	v_ashrrev_i32_e32 v15, 31, v14
	v_lshl_add_u64 v[16:17], v[14:15], 1, v[18:19]
	v_mul_lo_u32 v14, v14, s65
	v_lshlrev_b32_e32 v13, 1, v13
	v_add3_u32 v20, s70, v14, v13
	global_load_dwordx4 v[152:155], v[16:17], off offset:3072 nt
	v_lshlrev_b64 v[2:3], 8, v[2:3]
	v_mov_b32_e32 v156, v20
	v_and_b32_e32 v14, -8, v4
	v_ashrrev_i32_e32 v15, 31, v14
	v_lshl_add_u64 v[16:17], v[14:15], 1, v[18:19]
	v_mul_lo_u32 v14, v14, s65
	v_add3_u32 v20, s70, v14, v13
	global_load_dwordx4 v[158:161], v[16:17], off offset:3072 nt
	v_mov_b32_e32 v157, v20
	v_and_b32_e32 v14, -8, v6
	v_ashrrev_i32_e32 v15, 31, v14
	v_lshl_add_u64 v[16:17], v[14:15], 1, v[18:19]
	v_mul_lo_u32 v14, v14, s65
	v_add3_u32 v20, s70, v14, v13
	global_load_dwordx4 v[162:165], v[16:17], off offset:3072 nt
	v_and_b32_e32 v14, -8, v8
	v_ashrrev_i32_e32 v15, 31, v14
	v_lshl_add_u64 v[16:17], v[14:15], 1, v[18:19]
	v_mul_lo_u32 v14, v14, s65
	v_add3_u32 v13, s70, v14, v13
	global_load_dwordx4 v[166:169], v[16:17], off offset:3072 nt
	v_mov_b32_e32 v170, v13
	v_lshl_add_u64 v[14:15], s[40:41], 0, v[0:1]
	s_mov_b64 s[40:41], 0x33600000
	v_lshl_add_u64 v[18:19], v[14:15], 0, s[40:41]
	v_lshl_add_u64 v[2:3], v[18:19], 0, v[2:3]
	global_load_dwordx4 v[172:175], v[2:3], off nt
	v_readlane_b32 s40, v255, 29
	s_nop 1
	v_add_u32_e32 v0, s40, v0
	v_add_u32_e32 v2, v0, v27
	v_add_u32_e32 v13, v0, v29
	v_mov_b32_e32 v171, v2
	v_lshlrev_b64 v[2:3], 8, v[4:5]
	v_lshl_add_u64 v[2:3], v[18:19], 0, v[2:3]
	global_load_dwordx4 v[176:179], v[2:3], off nt
	v_lshlrev_b64 v[2:3], 8, v[6:7]
	v_lshl_add_u64 v[2:3], v[18:19], 0, v[2:3]
	global_load_dwordx4 v[180:183], v[2:3], off nt
	v_add_u32_e32 v6, v0, v31
	v_add_u32_e32 v0, v0, v12
	v_lshlrev_b64 v[2:3], 8, v[8:9]
	v_lshl_add_u64 v[2:3], v[18:19], 0, v[2:3]
	global_load_dwordx4 v[184:187], v[2:3], off nt
	s_waitcnt vmcnt(15)
	ds_write_b128 v28, v[120:123]
	s_waitcnt vmcnt(14)
	ds_write_b128 v30, v[124:127]
	s_waitcnt vmcnt(13)
; #define LAS __attribute__((address_space(3)))
; #define ZERO8(a) do { _Pragma("unroll") for (int t_ = 0; t_ < 8; ++t_) a[t_] = (f32x4){0.f, 0.f, 0.f, 0.f}; } while (0)
; __device__ __forceinline__ void wave_mma(f32x4 (&acc)[8], const LAS bfu* As, const LAS bfu* Bs, int m0, int fr, int fq) {
; #pragma unroll
;     for (int ks = 0; ks < 4; ++ks) { const bf16x8 a = *(const LAS bf16x8*)(As + (m0 + fr) * TS + ks * 32 + fq * 8);
; #pragma unroll
;         for (int t = 0; t < 8; ++t) { const bf16x8 b = *(const LAS bf16x8*)(Bs + (t * 16 + fr) * TS + ks * 32 + fq * 8); acc[t] = __builtin_amdgcn_mfma_f32_16x16x32_bf16(b, a, acc[t], 0, 0, 0); } }
; }
; __device__ __forceinline__ void ret_unit(LAS unsigned char* lds, const bfu* PROJ, const bfu* RT, const float* gn_g, bfu* CAT, int u) {
;     ...
;     stage_nat(Qs, P0 + C_RQ, INW, tid); stage_nat(Ks, P0 + C_RK, INW, tid); stage_tr<false>(Vt, P0 + C_RV, INW, tid, 0.f); stage_nat(Rt, RT + (size_t)u * 16384, 128, tid);
;     __syncthreads();
;     const int fr = lane & 15, fq = lane >> 4, m0 = wid * 16, c = m0 + fr;
;     f32x4 acc[8], cr[8]; ZERO8(acc); ZERO8(cr);
;     wave_mma(cr, Qs, Rt, m0, fr, fq);
;     wave_mma(acc, Qs, Ks, m0, fr, fq);
	ds_write_b128 v32, v[128:131]
	s_waitcnt vmcnt(12)
	ds_write_b128 v119, v[132:135]
	s_waitcnt vmcnt(11)
	ds_write_b128 v28, v[136:139] offset:34816
	s_waitcnt vmcnt(10)
	ds_write_b128 v30, v[140:143] offset:34816
	s_waitcnt vmcnt(9)
	ds_write_b128 v32, v[144:147] offset:34816
	s_waitcnt vmcnt(8)
	ds_write_b128 v119, v[148:151] offset:34816
	s_waitcnt vmcnt(7)
	ds_write_b16 v156, v152
	ds_write_b16_d16_hi v156, v152 offset:272
	ds_write_b16 v156, v153 offset:544
	ds_write_b16_d16_hi v156, v153 offset:816
	ds_write_b16 v156, v154 offset:1088
	ds_write_b16_d16_hi v156, v154 offset:1360
	ds_write_b16 v156, v155 offset:1632
	ds_write_b16_d16_hi v156, v155 offset:1904
	s_waitcnt vmcnt(6)
	ds_write_b16 v157, v158
	ds_write_b16_d16_hi v157, v158 offset:272
	ds_write_b16 v157, v159 offset:544
	ds_write_b16_d16_hi v157, v159 offset:816
	ds_write_b16 v157, v160 offset:1088
	ds_write_b16_d16_hi v157, v160 offset:1360
	ds_write_b16 v157, v161 offset:1632
	ds_write_b16_d16_hi v157, v161 offset:1904
	s_waitcnt vmcnt(5)
	ds_write_b16 v20, v162
	ds_write_b16_d16_hi v20, v162 offset:272
	ds_write_b16 v20, v163 offset:544
	ds_write_b16_d16_hi v20, v163 offset:816
	ds_write_b16 v20, v164 offset:1088
	ds_write_b16_d16_hi v20, v164 offset:1360
	ds_write_b16 v20, v165 offset:1632
	ds_write_b16_d16_hi v20, v165 offset:1904
	s_waitcnt vmcnt(4)
	ds_write_b16 v170, v166
	ds_write_b16_d16_hi v170, v166 offset:272
	ds_write_b16 v170, v167 offset:544
	ds_write_b16_d16_hi v170, v167 offset:816
	ds_write_b16 v170, v168 offset:1088
	ds_write_b16_d16_hi v170, v168 offset:1360
	ds_write_b16 v170, v169 offset:1632
	ds_write_b16_d16_hi v170, v169 offset:1904
	s_waitcnt vmcnt(3)
	ds_write_b128 v171, v[172:175]
	s_waitcnt vmcnt(2)
	ds_write_b128 v13, v[176:179]
	s_waitcnt vmcnt(1)
	ds_write_b128 v6, v[180:183]
	s_waitcnt vmcnt(0)
	ds_write_b128 v0, v[184:187]
	v_ldexp_f32 v0, v11, s22
	v_log_f32_e32 v0, v0
	v_cndmask_b32_e32 v2, 0, v242, vcc
	s_waitcnt lgkmcnt(0)
	s_barrier
	s_waitcnt lgkmcnt(0)
	v_sub_f32_e32 v67, v0, v2
	v_and_b32_e32 v2, 15, v10
	v_mul_lo_u32 v0, v66, s65
	v_add_u32_e32 v73, 0, v0
	v_mul_u32_u24_e32 v70, 0x110, v2
	v_add_u32_e32 v62, v73, v69
	ds_read_b128 v[96:99], v62
	v_add3_u32 v63, s40, v69, v70
	ds_read_b128 v[100:103], v63
	ds_read_b128 v[104:107], v63 offset:4352
	ds_read_b128 v[108:111], v63 offset:8704
	ds_read_b128 v[112:115], v63 offset:13056
	ds_read_b128 v[116:119], v63 offset:17408
	ds_read_b128 v[120:123], v63 offset:21760
	ds_read_b128 v[124:127], v63 offset:26112
	ds_read_b128 v[128:131], v63 offset:30464
	ds_read_b128 v[132:135], v62 offset:64
	ds_read_b128 v[136:139], v63 offset:64
	ds_read_b128 v[140:143], v63 offset:4416
	s_waitcnt lgkmcnt(10)
	v_mfma_f32_16x16x32_bf16 v[2:5], v[100:103], v[96:99], 0
	v_add3_u32 v72, 0, v69, v70
	v_lshlrev_b32_e32 v0, 3, v71
	ds_read_b128 v[100:103], v63 offset:8768
	ds_read_b128 v[144:147], v63 offset:13120
	ds_read_b128 v[148:151], v63 offset:17472
	s_waitcnt lgkmcnt(4)
	v_mfma_f32_16x16x32_bf16 v[2:5], v[136:139], v[132:135], v[2:5]
	ds_read_b128 v[136:139], v63 offset:21824
	v_mfma_f32_16x16x32_bf16 v[6:9], v[104:107], v[96:99], 0
	ds_read_b128 v[104:107], v63 offset:26176
	s_waitcnt lgkmcnt(5)
	v_mfma_f32_16x16x32_bf16 v[6:9], v[140:143], v[132:135], v[6:9]
	ds_read_b128 v[140:143], v63 offset:30528
	v_mfma_f32_16x16x32_bf16 v[10:13], v[108:111], v[96:99], 0
	ds_read_b128 v[108:111], v62 offset:128
	s_waitcnt lgkmcnt(6)
	v_mfma_f32_16x16x32_bf16 v[10:13], v[100:103], v[132:135], v[10:13]
	ds_read_b128 v[100:103], v63 offset:128
	v_mfma_f32_16x16x32_bf16 v[14:17], v[112:115], v[96:99], 0
	ds_read_b128 v[112:115], v63 offset:4480
	s_waitcnt lgkmcnt(7)
	v_mfma_f32_16x16x32_bf16 v[14:17], v[144:147], v[132:135], v[14:17]
	ds_read_b128 v[144:147], v63 offset:8832
	v_mfma_f32_16x16x32_bf16 v[18:21], v[116:119], v[96:99], 0
	ds_read_b128 v[116:119], v63 offset:13184
	s_waitcnt lgkmcnt(8)
	v_mfma_f32_16x16x32_bf16 v[18:21], v[148:151], v[132:135], v[18:21]
	ds_read_b128 v[148:151], v63 offset:17536
	v_mfma_f32_16x16x32_bf16 v[22:25], v[120:123], v[96:99], 0
	ds_read_b128 v[120:123], v63 offset:21888
	s_waitcnt lgkmcnt(9)
	v_mfma_f32_16x16x32_bf16 v[22:25], v[136:139], v[132:135], v[22:25]
	ds_read_b128 v[136:139], v63 offset:26240
	v_mfma_f32_16x16x32_bf16 v[26:29], v[124:127], v[96:99], 0
	ds_read_b128 v[124:127], v63 offset:30592
	s_waitcnt lgkmcnt(10)
	v_mfma_f32_16x16x32_bf16 v[26:29], v[104:107], v[132:135], v[26:29]
	v_mfma_f32_16x16x32_bf16 v[30:33], v[128:131], v[96:99], 0
	ds_read_b128 v[104:107], v62 offset:192
	s_waitcnt lgkmcnt(10)
	v_mfma_f32_16x16x32_bf16 v[30:33], v[140:143], v[132:135], v[30:33]
	ds_read_b128 v[128:131], v63 offset:192
	ds_read_b128 v[140:143], v72 offset:52224
	s_waitcnt lgkmcnt(10)
	v_mfma_f32_16x16x32_bf16 v[2:5], v[100:103], v[108:111], v[2:5]
	ds_read_b128 v[100:103], v72 offset:56576
	s_waitcnt lgkmcnt(10)
	v_mfma_f32_16x16x32_bf16 v[6:9], v[112:115], v[108:111], v[6:9]
	ds_read_b128 v[112:115], v72 offset:60928
	s_waitcnt lgkmcnt(10)
	v_mfma_f32_16x16x32_bf16 v[50:53], v[144:147], v[108:111], v[10:13]
	s_nop 2
	ds_read_b128 v[144:147], v72 offset:65280
	s_waitcnt lgkmcnt(10)
	v_mfma_f32_16x16x32_bf16 v[14:17], v[116:119], v[108:111], v[14:17]
	ds_read_b128 v[116:119], v63 offset:4544
	s_waitcnt lgkmcnt(10)
	v_mfma_f32_16x16x32_bf16 v[18:21], v[148:151], v[108:111], v[18:21]
	ds_read_b128 v[148:151], v63 offset:8896
	s_waitcnt lgkmcnt(10)
	v_mfma_f32_16x16x32_bf16 v[22:25], v[120:123], v[108:111], v[22:25]
	ds_read_b128 v[120:123], v63 offset:13248
	s_waitcnt lgkmcnt(10)
	v_mfma_f32_16x16x32_bf16 v[54:57], v[136:139], v[108:111], v[26:29]
	ds_read_b128 v[136:139], v63 offset:17600
	s_waitcnt lgkmcnt(10)
; __device__ __forceinline__ float fexp2(float x) { return __builtin_amdgcn_exp2f(x); }
; __device__ __forceinline__ void ret_unit(LAS unsigned char* lds, const bfu* PROJ, const bfu* RT, const float* gn_g, bfu* CAT, int u) {
;     ...
;     wave_mma(cr, Qs, Rt, m0, fr, fq);
;     wave_mma(acc, Qs, Ks, m0, fr, fq);
;     __syncthreads();
; #pragma unroll
;     for (int t = 0; t < 8; ++t) { float p[4];
; #pragma unroll
;         for (int j = 0; j < 4; ++j) { const int e = 16 * t + 4 * fq + j; p[j] = (c >= e) ? acc[t][j] * fexp2(lg * (float)(c - e)) : 0.f; }
	v_mfma_f32_16x16x32_bf16 v[58:61], v[124:127], v[108:111], v[30:33]
	ds_read_b128 v[124:127], v72 offset:34816
	s_waitcnt lgkmcnt(9)
	v_mfma_f32_16x16x32_bf16 v[10:13], v[128:131], v[104:107], v[2:5]
	ds_read_b128 v[128:131], v63 offset:21952
	s_nop 1
	s_waitcnt lgkmcnt(5)
	v_mfma_f32_16x16x32_bf16 v[30:33], v[116:119], v[104:107], v[6:9]
	ds_read_b128 v[116:119], v63 offset:26304
	s_nop 1
	s_waitcnt lgkmcnt(4)
	v_mfma_f32_16x16x32_bf16 v[14:17], v[120:123], v[104:107], v[14:17]
	ds_read_b128 v[120:123], v63 offset:30656
	v_mfma_f32_16x16x32_bf16 v[2:5], v[148:151], v[104:107], v[50:53]
	ds_read_b128 v[148:151], v72 offset:39168
	s_nop 2
	s_waitcnt lgkmcnt(5)
	v_mfma_f32_16x16x32_bf16 v[26:29], v[136:139], v[104:107], v[18:21]
	ds_read_b128 v[136:139], v72 offset:47872
	s_nop 1
	s_waitcnt lgkmcnt(4)
	v_mfma_f32_16x16x32_bf16 v[6:9], v[128:131], v[104:107], v[22:25]
	ds_read_b128 v[128:131], v72 offset:43520
	s_nop 2
	s_waitcnt lgkmcnt(4)
	v_mfma_f32_16x16x32_bf16 v[18:21], v[116:119], v[104:107], v[54:57]
	ds_read_b128 v[116:119], v72 offset:34880
	s_nop 2
	s_waitcnt lgkmcnt(4)
	v_mfma_f32_16x16x32_bf16 v[22:25], v[120:123], v[104:107], v[58:61]
	ds_read_b128 v[120:123], v72 offset:39232
	s_nop 1
	v_mfma_f32_16x16x32_bf16 v[50:53], v[124:127], v[96:99], 0
	ds_read_b128 v[124:127], v72 offset:43584
	s_waitcnt lgkmcnt(5)
	v_mfma_f32_16x16x32_bf16 v[54:57], v[148:151], v[96:99], 0
	ds_read_b128 v[148:151], v72 offset:47936
	s_waitcnt lgkmcnt(4)
	v_mfma_f32_16x16x32_bf16 v[58:61], v[128:131], v[96:99], 0
	ds_read_b128 v[128:131], v72 offset:52288
	v_mfma_f32_16x16x32_bf16 v[62:65], v[136:139], v[96:99], 0
	ds_read_b128 v[136:139], v72 offset:56640
	v_mfma_f32_16x16x32_bf16 v[74:77], v[140:143], v[96:99], 0
	ds_read_b128 v[140:143], v72 offset:60992
	v_mfma_f32_16x16x32_bf16 v[78:81], v[100:103], v[96:99], 0
	ds_read_b128 v[100:103], v72 offset:65344
	v_mfma_f32_16x16x32_bf16 v[82:85], v[112:115], v[96:99], 0
	ds_read_b128 v[112:115], v72 offset:34944
	v_mfma_f32_16x16x32_bf16 v[46:49], v[144:147], v[96:99], 0
	ds_read_b128 v[96:99], v72 offset:39296
	ds_read_b128 v[144:147], v72 offset:43648
	s_waitcnt lgkmcnt(10)
	v_mfma_f32_16x16x32_bf16 v[50:53], v[116:119], v[132:135], v[50:53]
	ds_read_b128 v[116:119], v72 offset:48000
	s_waitcnt lgkmcnt(10)
	v_mfma_f32_16x16x32_bf16 v[54:57], v[120:123], v[132:135], v[54:57]
	ds_read_b128 v[120:123], v72 offset:52352
	s_waitcnt lgkmcnt(10)
	v_mfma_f32_16x16x32_bf16 v[58:61], v[124:127], v[132:135], v[58:61]
	ds_read_b128 v[124:127], v72 offset:56704
	s_waitcnt lgkmcnt(10)
	v_mfma_f32_16x16x32_bf16 v[62:65], v[148:151], v[132:135], v[62:65]
	ds_read_b128 v[148:151], v72 offset:61056
	s_waitcnt lgkmcnt(10)
	v_mfma_f32_16x16x32_bf16 v[74:77], v[128:131], v[132:135], v[74:77]
	ds_read_b128 v[128:131], v72 offset:65408
	s_waitcnt lgkmcnt(10)
	v_mfma_f32_16x16x32_bf16 v[78:81], v[136:139], v[132:135], v[78:81]
	ds_read_b128 v[136:139], v72 offset:35008
	s_waitcnt lgkmcnt(10)
	v_mfma_f32_16x16x32_bf16 v[82:85], v[140:143], v[132:135], v[82:85]
	ds_read_b128 v[140:143], v72 offset:39360
	s_waitcnt lgkmcnt(10)
	v_mfma_f32_16x16x32_bf16 v[38:41], v[100:103], v[132:135], v[46:49]
	s_nop 2
	ds_read_b128 v[100:103], v72 offset:43712
	s_waitcnt lgkmcnt(10)
	v_mfma_f32_16x16x32_bf16 v[46:49], v[112:115], v[108:111], v[50:53]
	s_nop 2
	ds_read_b128 v[112:115], v72 offset:48064
	s_waitcnt lgkmcnt(10)
	v_mfma_f32_16x16x32_bf16 v[50:53], v[96:99], v[108:111], v[54:57]
	s_nop 2
	ds_read_b128 v[96:99], v72 offset:52416
	s_waitcnt lgkmcnt(10)
	v_mfma_f32_16x16x32_bf16 v[54:57], v[144:147], v[108:111], v[58:61]
	s_nop 2
	ds_read_b128 v[132:135], v72 offset:56768
	s_waitcnt lgkmcnt(10)
	v_mfma_f32_16x16x32_bf16 v[86:89], v[116:119], v[108:111], v[62:65]
	ds_read_b128 v[116:119], v72 offset:65472
	s_waitcnt lgkmcnt(10)
	v_mfma_f32_16x16x32_bf16 v[74:77], v[120:123], v[108:111], v[74:77]
	ds_read_b128 v[120:123], v72 offset:61120
	s_waitcnt lgkmcnt(10)
	v_mfma_f32_16x16x32_bf16 v[78:81], v[124:127], v[108:111], v[78:81]
	s_waitcnt lgkmcnt(9)
	v_mfma_f32_16x16x32_bf16 v[82:85], v[148:151], v[108:111], v[82:85]
	s_waitcnt lgkmcnt(8)
	v_mfma_f32_16x16x32_bf16 v[90:93], v[128:131], v[108:111], v[38:41]
	s_nop 2
	s_waitcnt lgkmcnt(7)
	v_mfma_f32_16x16x32_bf16 v[62:65], v[136:139], v[104:107], v[46:49]
	s_waitcnt lgkmcnt(6)
	v_mfma_f32_16x16x32_bf16 v[58:61], v[140:143], v[104:107], v[50:53]
	s_waitcnt lgkmcnt(5)
	v_mfma_f32_16x16x32_bf16 v[54:57], v[100:103], v[104:107], v[54:57]
	s_waitcnt lgkmcnt(4)
	v_mfma_f32_16x16x32_bf16 v[50:53], v[112:115], v[104:107], v[86:89]
	s_waitcnt lgkmcnt(3)
	v_mfma_f32_16x16x32_bf16 v[46:49], v[96:99], v[104:107], v[74:77]
	s_nop 1
	s_waitcnt lgkmcnt(2)
	v_mfma_f32_16x16x32_bf16 v[42:45], v[132:135], v[104:107], v[78:81]
	v_lshlrev_b32_e32 v72, 2, v71
	v_add_u32_e32 v71, v73, v0
	v_sub_u32_e32 v73, v66, v72
	v_cvt_f32_i32_e32 v73, v73
	v_cmp_ge_i32_e32 vcc, v66, v72
	s_waitcnt lgkmcnt(0)
	v_mfma_f32_16x16x32_bf16 v[38:41], v[120:123], v[104:107], v[82:85]
	v_mul_f32_e32 v73, v67, v73
	v_exp_f32_e32 v73, v73
	v_mfma_f32_16x16x32_bf16 v[34:37], v[116:119], v[104:107], v[90:93]
	v_or_b32_e32 v75, 3, v72
	v_mul_f32_e32 v62, v73, v62
	v_cndmask_b32_e32 v73, 0, v62, vcc
	v_xad_u32 v62, v72, -1, v66
	v_cvt_f32_i32_e32 v62, v62
	v_cmp_gt_i32_e32 vcc, v66, v72
	v_or_b32_e32 v76, 2, v72
	s_waitcnt lgkmcnt(0)
	s_barrier
; #define LAS __attribute__((address_space(3)))
; __device__ __forceinline__ unsigned pk2(float lo, float hi) { return pg8::cvt_pk_bf16(lo, hi); }
; __device__ __forceinline__ float fexp2(float x) { return __builtin_amdgcn_exp2f(x); }
; __device__ __forceinline__ void ret_unit(LAS unsigned char* lds, const bfu* PROJ, const bfu* RT, const float* gn_g, bfu* CAT, int u) {
;     ...
;     for (int t = 0; t < 8; ++t) { float p[4];
; #pragma unroll
;         for (int j = 0; j < 4; ++j) { const int e = 16 * t + 4 * fq + j; p[j] = (c >= e) ? acc[t][j] * fexp2(lg * (float)(c - e)) : 0.f; }
;         v2u w; w.x = pk2(p[0], p[1]); w.y = pk2(p[2], p[3]); *(LAS v2u*)(Ks + c * TS + 16 * t + 4 * fq) = w; }
	v_mul_f32_e32 v62, v67, v62
	v_exp_f32_e32 v62, v62
	v_add_u32_e32 v78, v71, v0
	v_add3_u32 v82, s70, v69, v70
	v_mul_f32_e32 v62, v62, v63
	v_cndmask_b32_e32 v74, 0, v62, vcc
	v_sub_u32_e32 v62, v66, v76
	v_sub_u32_e32 v63, v66, v75
	v_cvt_f32_i32_e32 v62, v62
	v_cvt_f32_i32_e32 v63, v63
	v_cmp_ge_i32_e32 vcc, v66, v76
	v_or_b32_e32 v76, 18, v72
	v_mul_f32_e32 v62, v67, v62
	v_mul_f32_e32 v63, v67, v63
	v_exp_f32_e32 v62, v62
	v_exp_f32_e32 v63, v63
	s_nop 0
	v_pk_mul_f32 v[62:63], v[62:63], v[64:65]
	s_nop 0
	v_cvt_pk_bf16_f32 v62, v62, v63
	v_cndmask_b32_e32 v63, 0, v62, vcc
	v_lshrrev_b32_e32 v62, 16, v62
	v_cmp_ge_i32_e32 vcc, v66, v75
	v_cvt_pk_bf16_f32 v64, v73, v74
	v_or_b32_e32 v73, 17, v72
	v_cndmask_b32_e32 v62, 0, v62, vcc
	v_or_b32_e32 v74, 16, v72
	v_perm_b32 v65, v62, v63, s72
	v_sub_u32_e32 v62, v66, v74
	v_sub_u32_e32 v63, v66, v73
	v_cvt_f32_i32_e32 v62, v62
	v_cvt_f32_i32_e32 v63, v63
	v_or_b32_e32 v75, 19, v72
	v_cmp_ge_i32_e32 vcc, v66, v74
	v_mul_f32_e32 v62, v67, v62
	v_mul_f32_e32 v63, v67, v63
	v_exp_f32_e32 v62, v62
	v_exp_f32_e32 v63, v63
	s_nop 0
	v_pk_mul_f32 v[58:59], v[62:63], v[58:59]
	v_sub_u32_e32 v62, v66, v76
	v_sub_u32_e32 v63, v66, v75
	v_cvt_f32_i32_e32 v62, v62
	v_cvt_f32_i32_e32 v63, v63
	v_cvt_pk_bf16_f32 v58, v58, v59
	v_cndmask_b32_e32 v59, 0, v58, vcc
	v_mul_f32_e32 v62, v67, v62
	v_mul_f32_e32 v63, v67, v63
	v_exp_f32_e32 v62, v62
	v_exp_f32_e32 v63, v63
	v_lshrrev_b32_e32 v58, 16, v58
	v_cmp_ge_i32_e32 vcc, v66, v73
	v_pk_mul_f32 v[60:61], v[62:63], v[60:61]
	s_nop 0
	v_cndmask_b32_e32 v58, 0, v58, vcc
	v_perm_b32 v62, v58, v59, s72
	v_cvt_pk_bf16_f32 v58, v60, v61
	v_cmp_ge_i32_e32 vcc, v66, v76
	s_nop 1
	v_cndmask_b32_e32 v59, 0, v58, vcc
	v_lshrrev_b32_e32 v58, 16, v58
	v_cmp_ge_i32_e32 vcc, v66, v75
	s_nop 1
	v_cndmask_b32_e32 v58, 0, v58, vcc
	v_perm_b32 v63, v58, v59, s72
	v_add_u32_e32 v58, 0x8800, v71
	ds_write2_b64 v58, v[64:65], v[62:63] offset1:4
	v_or_b32_e32 v59, 33, v72
	v_or_b32_e32 v62, 32, v72
	v_sub_u32_e32 v60, v66, v62
	v_sub_u32_e32 v61, v66, v59
	v_cvt_f32_i32_e32 v60, v60
	v_cvt_f32_i32_e32 v61, v61
	v_or_b32_e32 v63, 35, v72
	v_or_b32_e32 v64, 34, v72
	v_mul_f32_e32 v60, v67, v60
	v_mul_f32_e32 v61, v67, v61
	v_exp_f32_e32 v60, v60
	v_exp_f32_e32 v61, v61
	v_cmp_ge_i32_e32 vcc, v66, v62
	v_or_b32_e32 v62, 50, v72
	v_pk_mul_f32 v[54:55], v[60:61], v[54:55]
	v_sub_u32_e32 v60, v66, v64
	v_sub_u32_e32 v61, v66, v63
	v_cvt_f32_i32_e32 v60, v60
	v_cvt_f32_i32_e32 v61, v61
	v_cvt_pk_bf16_f32 v54, v54, v55
	v_cndmask_b32_e32 v55, 0, v54, vcc
	v_mul_f32_e32 v60, v67, v60
	v_mul_f32_e32 v61, v67, v61
	v_exp_f32_e32 v60, v60
	v_exp_f32_e32 v61, v61
	v_lshrrev_b32_e32 v54, 16, v54
	v_cmp_ge_i32_e32 vcc, v66, v59
	v_or_b32_e32 v59, 49, v72
	v_pk_mul_f32 v[56:57], v[60:61], v[56:57]
	v_cndmask_b32_e32 v54, 0, v54, vcc
	v_perm_b32 v54, v54, v55, s72
	v_cvt_pk_bf16_f32 v55, v56, v57
	v_cmp_ge_i32_e32 vcc, v66, v64
	v_or_b32_e32 v60, 48, v72
	v_sub_u32_e32 v57, v66, v59
	v_cndmask_b32_e32 v56, 0, v55, vcc
	v_lshrrev_b32_e32 v55, 16, v55
	v_cmp_ge_i32_e32 vcc, v66, v63
	v_cvt_f32_i32_e32 v57, v57
	v_or_b32_e32 v61, 51, v72
	v_cndmask_b32_e32 v55, 0, v55, vcc
	v_perm_b32 v55, v55, v56, s72
	v_sub_u32_e32 v56, v66, v60
	v_cvt_f32_i32_e32 v56, v56
	v_mul_f32_e32 v57, v67, v57
	v_exp_f32_e32 v57, v57
	v_cmp_ge_i32_e32 vcc, v66, v60
	v_mul_f32_e32 v56, v67, v56
	v_exp_f32_e32 v56, v56
	s_nop 0
	v_pk_mul_f32 v[50:51], v[56:57], v[50:51]
	v_sub_u32_e32 v56, v66, v62
	v_sub_u32_e32 v57, v66, v61
	v_cvt_f32_i32_e32 v56, v56
	v_cvt_f32_i32_e32 v57, v57
	v_cvt_pk_bf16_f32 v50, v50, v51
	v_cndmask_b32_e32 v51, 0, v50, vcc
	v_mul_f32_e32 v56, v67, v56
	v_mul_f32_e32 v57, v67, v57
	v_exp_f32_e32 v56, v56
	v_exp_f32_e32 v57, v57
	v_lshrrev_b32_e32 v50, 16, v50
	v_cmp_ge_i32_e32 vcc, v66, v59
	v_pk_mul_f32 v[52:53], v[56:57], v[52:53]
	s_nop 0
	v_cndmask_b32_e32 v50, 0, v50, vcc
	v_perm_b32 v50, v50, v51, s72
	v_cvt_pk_bf16_f32 v51, v52, v53
	v_cmp_ge_i32_e32 vcc, v66, v62
	v_or_b32_e32 v53, 64, v72
	s_nop 0
	v_cndmask_b32_e32 v52, 0, v51, vcc
	v_lshrrev_b32_e32 v51, 16, v51
	v_cmp_ge_i32_e32 vcc, v66, v61
	s_nop 1
	v_cndmask_b32_e32 v51, 0, v51, vcc
	v_perm_b32 v51, v51, v52, s72
	v_or_b32_e32 v52, 0x41, v72
	ds_write2_b64 v58, v[54:55], v[50:51] offset0:8 offset1:12
	v_sub_u32_e32 v50, v66, v53
	v_sub_u32_e32 v51, v66, v52
	v_cvt_f32_i32_e32 v50, v50
	v_cvt_f32_i32_e32 v51, v51
	v_or_b32_e32 v54, 0x43, v72
	v_or_b32_e32 v55, 0x42, v72
	v_mul_f32_e32 v50, v67, v50
	v_mul_f32_e32 v51, v67, v51
	v_exp_f32_e32 v50, v50
	v_exp_f32_e32 v51, v51
	v_cmp_ge_i32_e32 vcc, v66, v53
	v_or_b32_e32 v53, 0x52, v72
	v_pk_mul_f32 v[46:47], v[50:51], v[46:47]
	v_sub_u32_e32 v50, v66, v55
	v_sub_u32_e32 v51, v66, v54
	v_cvt_f32_i32_e32 v50, v50
	v_cvt_f32_i32_e32 v51, v51
	v_cvt_pk_bf16_f32 v46, v46, v47
	v_cndmask_b32_e32 v47, 0, v46, vcc
	v_mul_f32_e32 v50, v67, v50
	v_mul_f32_e32 v51, v67, v51
	v_exp_f32_e32 v50, v50
	v_exp_f32_e32 v51, v51
	v_lshrrev_b32_e32 v46, 16, v46
	v_cmp_ge_i32_e32 vcc, v66, v52
	v_or_b32_e32 v52, 0x53, v72
	v_pk_mul_f32 v[48:49], v[50:51], v[48:49]
	v_cndmask_b32_e32 v46, 0, v46, vcc
	v_perm_b32 v46, v46, v47, s72
	v_cvt_pk_bf16_f32 v47, v48, v49
	v_cmp_ge_i32_e32 vcc, v66, v55
	v_or_b32_e32 v50, 0x51, v72
	v_or_b32_e32 v51, 0x50, v72
	v_cndmask_b32_e32 v48, 0, v47, vcc
	v_lshrrev_b32_e32 v47, 16, v47
	v_cmp_ge_i32_e32 vcc, v66, v54
	v_sub_u32_e32 v49, v66, v50
	v_cvt_f32_i32_e32 v49, v49
	v_cndmask_b32_e32 v47, 0, v47, vcc
	v_perm_b32 v47, v47, v48, s72
	v_sub_u32_e32 v48, v66, v51
	v_cvt_f32_i32_e32 v48, v48
	v_mul_f32_e32 v49, v67, v49
	v_exp_f32_e32 v49, v49
	v_cmp_ge_i32_e32 vcc, v66, v51
; #define LAS __attribute__((address_space(3)))
; #define LDS_WAIT() asm volatile("s_waitcnt lgkmcnt(0)" ::: "memory")
; __device__ __forceinline__ unsigned pk2(float lo, float hi) { return pg8::cvt_pk_bf16(lo, hi); }
; #define ZERO8(a) do { _Pragma("unroll") for (int t_ = 0; t_ < 8; ++t_) a[t_] = (f32x4){0.f, 0.f, 0.f, 0.f}; } while (0)
; __device__ __forceinline__ void ret_unit(LAS unsigned char* lds, const bfu* PROJ, const bfu* RT, const float* gn_g, bfu* CAT, int u) {
;     ...
;         v2u w; w.x = pk2(p[0], p[1]); w.y = pk2(p[2], p[3]); *(LAS v2u*)(Ks + c * TS + 16 * t + 4 * fq) = w; }
;     LDS_WAIT(); asm volatile("" ::: "memory");
;     ZERO8(acc);
;     wave_mma(acc, Ks, Vt, m0, fr, fq);
	v_mul_f32_e32 v48, v67, v48
	v_exp_f32_e32 v48, v48
	s_nop 0
	v_pk_mul_f32 v[42:43], v[48:49], v[42:43]
	v_sub_u32_e32 v48, v66, v53
	v_sub_u32_e32 v49, v66, v52
	v_cvt_f32_i32_e32 v48, v48
	v_cvt_f32_i32_e32 v49, v49
	v_cvt_pk_bf16_f32 v42, v42, v43
	v_cndmask_b32_e32 v43, 0, v42, vcc
	v_mul_f32_e32 v48, v67, v48
	v_mul_f32_e32 v49, v67, v49
	v_exp_f32_e32 v48, v48
	v_exp_f32_e32 v49, v49
	v_lshrrev_b32_e32 v42, 16, v42
	v_cmp_ge_i32_e32 vcc, v66, v50
	v_pk_mul_f32 v[44:45], v[48:49], v[44:45]
	s_nop 0
	v_cndmask_b32_e32 v42, 0, v42, vcc
	v_perm_b32 v42, v42, v43, s72
	v_cvt_pk_bf16_f32 v43, v44, v45
	v_cmp_ge_i32_e32 vcc, v66, v53
	v_or_b32_e32 v45, 0x60, v72
	s_nop 0
	v_cndmask_b32_e32 v44, 0, v43, vcc
	v_lshrrev_b32_e32 v43, 16, v43
	v_cmp_ge_i32_e32 vcc, v66, v52
	s_nop 1
	v_cndmask_b32_e32 v43, 0, v43, vcc
	v_perm_b32 v43, v43, v44, s72
	v_or_b32_e32 v44, 0x61, v72
	ds_write2_b64 v58, v[46:47], v[42:43] offset0:16 offset1:20
	v_sub_u32_e32 v42, v66, v45
	v_sub_u32_e32 v43, v66, v44
	v_cvt_f32_i32_e32 v42, v42
	v_cvt_f32_i32_e32 v43, v43
	v_or_b32_e32 v46, 0x63, v72
	v_or_b32_e32 v47, 0x62, v72
	v_mul_f32_e32 v42, v67, v42
	v_mul_f32_e32 v43, v67, v43
	v_exp_f32_e32 v42, v42
	v_exp_f32_e32 v43, v43
	v_cmp_ge_i32_e32 vcc, v66, v45
	v_or_b32_e32 v45, 0x72, v72
	v_pk_mul_f32 v[38:39], v[42:43], v[38:39]
	v_sub_u32_e32 v42, v66, v47
	v_sub_u32_e32 v43, v66, v46
	v_cvt_f32_i32_e32 v42, v42
	v_cvt_f32_i32_e32 v43, v43
	v_cvt_pk_bf16_f32 v38, v38, v39
	v_cndmask_b32_e32 v39, 0, v38, vcc
	v_mul_f32_e32 v42, v67, v42
	v_mul_f32_e32 v43, v67, v43
	v_exp_f32_e32 v42, v42
	v_exp_f32_e32 v43, v43
	v_lshrrev_b32_e32 v38, 16, v38
	v_cmp_ge_i32_e32 vcc, v66, v44
	v_or_b32_e32 v44, 0x73, v72
	v_pk_mul_f32 v[40:41], v[42:43], v[40:41]
	v_cndmask_b32_e32 v38, 0, v38, vcc
	v_perm_b32 v38, v38, v39, s72
	v_cvt_pk_bf16_f32 v39, v40, v41
	v_cmp_ge_i32_e32 vcc, v66, v47
	v_or_b32_e32 v42, 0x71, v72
	v_or_b32_e32 v43, 0x70, v72
	v_cndmask_b32_e32 v40, 0, v39, vcc
	v_lshrrev_b32_e32 v39, 16, v39
	v_cmp_ge_i32_e32 vcc, v66, v46
	v_sub_u32_e32 v41, v66, v42
	v_cvt_f32_i32_e32 v41, v41
	v_cndmask_b32_e32 v39, 0, v39, vcc
	v_perm_b32 v39, v39, v40, s72
	v_sub_u32_e32 v40, v66, v43
	v_cvt_f32_i32_e32 v40, v40
	v_mul_f32_e32 v41, v67, v41
	v_exp_f32_e32 v41, v41
	v_cmp_ge_i32_e32 vcc, v66, v43
	v_mul_f32_e32 v40, v67, v40
	v_exp_f32_e32 v40, v40
	s_nop 0
	v_pk_mul_f32 v[34:35], v[40:41], v[34:35]
	v_sub_u32_e32 v40, v66, v45
	v_sub_u32_e32 v41, v66, v44
	v_cvt_f32_i32_e32 v40, v40
	v_cvt_f32_i32_e32 v41, v41
	v_cvt_pk_bf16_f32 v34, v34, v35
	v_cndmask_b32_e32 v35, 0, v34, vcc
	v_mul_f32_e32 v40, v67, v40
	v_mul_f32_e32 v41, v67, v41
	v_exp_f32_e32 v40, v40
	v_exp_f32_e32 v41, v41
	v_lshrrev_b32_e32 v34, 16, v34
	v_cmp_ge_i32_e32 vcc, v66, v42
	v_pk_mul_f32 v[36:37], v[40:41], v[36:37]
	s_nop 0
	v_cndmask_b32_e32 v34, 0, v34, vcc
	v_perm_b32 v34, v34, v35, s72
	v_cvt_pk_bf16_f32 v35, v36, v37
	v_cmp_ge_i32_e32 vcc, v66, v45
	s_nop 1
	v_cndmask_b32_e32 v36, 0, v35, vcc
	v_lshrrev_b32_e32 v35, 16, v35
	v_cmp_ge_i32_e32 vcc, v66, v44
	s_nop 1
	v_cndmask_b32_e32 v35, 0, v35, vcc
	v_perm_b32 v35, v35, v36, s72
	ds_write2_b64 v58, v[38:39], v[34:35] offset0:24 offset1:28
	s_waitcnt lgkmcnt(0)
	s_waitcnt lgkmcnt(0)
	ds_read_b128 v[84:87], v78 offset:34816
	ds_read_b128 v[88:91], v82
	ds_read_b128 v[92:95], v82 offset:4352
	ds_read_b128 v[96:99], v82 offset:8704
	ds_read_b128 v[100:103], v82 offset:13056
	ds_read_b128 v[104:107], v82 offset:17408
	ds_read_b128 v[108:111], v82 offset:21760
	ds_read_b128 v[112:115], v82 offset:26112
	ds_read_b128 v[116:119], v82 offset:30464
	ds_read_b128 v[120:123], v78 offset:34880
	ds_read_b128 v[124:127], v82 offset:64
	ds_read_b128 v[128:131], v82 offset:4416
	s_waitcnt lgkmcnt(10)
	v_mfma_f32_16x16x32_bf16 v[38:41], v[88:91], v[84:87], 0
	ds_read_b128 v[88:91], v82 offset:8768
	s_waitcnt lgkmcnt(10)
	v_mfma_f32_16x16x32_bf16 v[42:45], v[92:95], v[84:87], 0
	ds_read_b128 v[92:95], v82 offset:13120
	s_waitcnt lgkmcnt(10)
	v_mfma_f32_16x16x32_bf16 v[46:49], v[96:99], v[84:87], 0
	ds_read_b128 v[96:99], v82 offset:17472
	s_waitcnt lgkmcnt(10)
	v_mfma_f32_16x16x32_bf16 v[50:53], v[100:103], v[84:87], 0
	ds_read_b128 v[100:103], v82 offset:21824
	s_waitcnt lgkmcnt(10)
	v_mfma_f32_16x16x32_bf16 v[54:57], v[104:107], v[84:87], 0
	ds_read_b128 v[104:107], v82 offset:26176
	s_waitcnt lgkmcnt(10)
	v_mfma_f32_16x16x32_bf16 v[58:61], v[108:111], v[84:87], 0
	ds_read_b128 v[108:111], v82 offset:30528
	s_waitcnt lgkmcnt(10)
	v_mfma_f32_16x16x32_bf16 v[62:65], v[112:115], v[84:87], 0
	ds_read_b128 v[112:115], v78 offset:34944
	s_waitcnt lgkmcnt(10)
	v_mfma_f32_16x16x32_bf16 v[34:37], v[116:119], v[84:87], 0
	ds_read_b128 v[84:87], v82 offset:128
	ds_read_b128 v[116:119], v82 offset:4480
	s_waitcnt lgkmcnt(10)
	v_mfma_f32_16x16x32_bf16 v[38:41], v[124:127], v[120:123], v[38:41]
	ds_read_b128 v[124:127], v82 offset:8832
	s_waitcnt lgkmcnt(10)
	v_mfma_f32_16x16x32_bf16 v[42:45], v[128:131], v[120:123], v[42:45]
	ds_read_b128 v[128:131], v82 offset:13184
	s_waitcnt lgkmcnt(10)
	v_mfma_f32_16x16x32_bf16 v[46:49], v[88:91], v[120:123], v[46:49]
	ds_read_b128 v[88:91], v82 offset:17536
	s_waitcnt lgkmcnt(10)
	v_mfma_f32_16x16x32_bf16 v[50:53], v[92:95], v[120:123], v[50:53]
	ds_read_b128 v[92:95], v82 offset:21888
	s_waitcnt lgkmcnt(10)
	v_mfma_f32_16x16x32_bf16 v[54:57], v[96:99], v[120:123], v[54:57]
	ds_read_b128 v[96:99], v82 offset:26240
	s_waitcnt lgkmcnt(10)
	v_mfma_f32_16x16x32_bf16 v[58:61], v[100:103], v[120:123], v[58:61]
	ds_read_b128 v[100:103], v82 offset:30592
	s_waitcnt lgkmcnt(10)
; __device__ __forceinline__ float fexp2(float x) { return __builtin_amdgcn_exp2f(x); }
; __device__ __forceinline__ void ret_unit(LAS unsigned char* lds, const bfu* PROJ, const bfu* RT, const float* gn_g, bfu* CAT, int u) {
;     ...
;     wave_mma(acc, Ks, Vt, m0, fr, fq);
;     const float xi = fexp2(lg * (float)(c + 1)); float s = 0.f;
; #pragma unroll
;     for (int t = 0; t < 8; ++t) { acc[t] = acc[t] + cr[t] * xi; s += (acc[t][0] + acc[t][1]) + (acc[t][2] + acc[t][3]); }
;     s += __shfl_xor(s, 16); s += __shfl_xor(s, 32); const float mu = s * (1.f / 128.f); float q = 0.f;
	v_mfma_f32_16x16x32_bf16 v[62:65], v[104:107], v[120:123], v[62:65]
	ds_read_b128 v[104:107], v78 offset:35008
	s_waitcnt lgkmcnt(10)
	v_mfma_f32_16x16x32_bf16 v[34:37], v[108:111], v[120:123], v[34:37]
	ds_read_b128 v[108:111], v82 offset:192
	ds_read_b128 v[120:123], v82 offset:4544
	s_waitcnt lgkmcnt(10)
	v_mfma_f32_16x16x32_bf16 v[38:41], v[84:87], v[112:115], v[38:41]
	ds_read_b128 v[84:87], v82 offset:8896
	s_waitcnt lgkmcnt(10)
	v_mfma_f32_16x16x32_bf16 v[42:45], v[116:119], v[112:115], v[42:45]
	ds_read_b128 v[116:119], v82 offset:13248
	s_waitcnt lgkmcnt(10)
	v_mfma_f32_16x16x32_bf16 v[46:49], v[124:127], v[112:115], v[46:49]
	ds_read_b128 v[124:127], v82 offset:17600
	s_waitcnt lgkmcnt(10)
	v_mfma_f32_16x16x32_bf16 v[50:53], v[128:131], v[112:115], v[50:53]
	ds_read_b128 v[128:131], v82 offset:21952
	s_waitcnt lgkmcnt(10)
	v_mfma_f32_16x16x32_bf16 v[54:57], v[88:91], v[112:115], v[54:57]
	ds_read_b128 v[88:91], v82 offset:26304
	s_waitcnt lgkmcnt(10)
	v_mfma_f32_16x16x32_bf16 v[58:61], v[92:95], v[112:115], v[58:61]
	ds_read_b128 v[92:95], v82 offset:30656
	s_waitcnt lgkmcnt(10)
	v_mfma_f32_16x16x32_bf16 v[62:65], v[96:99], v[112:115], v[62:65]
	s_waitcnt lgkmcnt(9)
	v_mfma_f32_16x16x32_bf16 v[34:37], v[100:103], v[112:115], v[34:37]
	s_waitcnt lgkmcnt(7)
	v_mfma_f32_16x16x32_bf16 v[38:41], v[108:111], v[104:107], v[38:41]
	s_waitcnt lgkmcnt(6)
	v_mfma_f32_16x16x32_bf16 v[74:77], v[120:123], v[104:107], v[42:45]
	s_nop 2
	s_waitcnt lgkmcnt(5)
	v_mfma_f32_16x16x32_bf16 v[78:81], v[84:87], v[104:107], v[46:49]
	s_waitcnt lgkmcnt(4)
	v_mfma_f32_16x16x32_bf16 v[48:51], v[116:119], v[104:107], v[50:53]
	s_waitcnt lgkmcnt(3)
	v_mfma_f32_16x16x32_bf16 v[52:55], v[124:127], v[104:107], v[54:57]
	s_waitcnt lgkmcnt(2)
	v_mfma_f32_16x16x32_bf16 v[56:59], v[128:131], v[104:107], v[58:61]
	s_waitcnt lgkmcnt(1)
	v_mfma_f32_16x16x32_bf16 v[60:63], v[88:91], v[104:107], v[62:65]
	s_waitcnt lgkmcnt(0)
	v_mfma_f32_16x16x32_bf16 v[70:73], v[92:95], v[104:107], v[34:37]
	s_nop 2
	s_waitcnt lgkmcnt(0)
	v_add_u32_e32 v34, 1, v66
	v_cvt_f32_i32_e32 v34, v34
	v_mul_f32_e32 v34, v67, v34
	v_exp_f32_e32 v64, v34
	v_ashrrev_i32_e32 v67, 31, v66
	v_pk_fma_f32 v[46:47], v[64:65], v[10:11], v[38:39] op_sel_hi:[0,1,1]
	v_pk_fma_f32 v[42:43], v[64:65], v[30:31], v[74:75] op_sel_hi:[0,1,1]
	v_pk_fma_f32 v[44:45], v[64:65], v[12:13], v[40:41] op_sel_hi:[0,1,1]
	v_pk_fma_f32 v[40:41], v[64:65], v[32:33], v[76:77] op_sel_hi:[0,1,1]
	v_mov_b32_e32 v10, v46
	v_mov_b32_e32 v11, v42
	v_mov_b32_e32 v12, v47
	v_mov_b32_e32 v13, v43
	v_pk_add_f32 v[10:11], v[10:11], v[12:13]
	v_mov_b32_e32 v12, v44
	v_mov_b32_e32 v13, v40
	v_mov_b32_e32 v30, v45
	v_mov_b32_e32 v31, v41
	v_pk_fma_f32 v[38:39], v[64:65], v[2:3], v[78:79] op_sel_hi:[0,1,1]
	v_pk_fma_f32 v[36:37], v[64:65], v[4:5], v[80:81] op_sel_hi:[0,1,1]
	v_pk_add_f32 v[12:13], v[12:13], v[30:31]
	v_pk_mov_b32 v[2:3], v[38:39], v[36:37] op_sel:[1,0]
	v_mov_b32_e32 v4, v38
	v_mov_b32_e32 v5, v37
	v_pk_add_f32 v[10:11], v[10:11], v[12:13]
	v_pk_add_f32 v[2:3], v[2:3], v[4:5]
	v_add_f32_e32 v10, 0, v10
	v_pk_add_f32 v[2:3], v[2:3], v[2:3] op_sel:[0,1] op_sel_hi:[1,0]
	v_pk_fma_f32 v[32:33], v[64:65], v[16:17], v[50:51] op_sel_hi:[0,1,1]
	v_pk_fma_f32 v[34:35], v[64:65], v[14:15], v[48:49] op_sel_hi:[0,1,1]
	v_pk_fma_f32 v[28:29], v[64:65], v[28:29], v[54:55] op_sel_hi:[0,1,1]
	v_pk_fma_f32 v[30:31], v[64:65], v[26:27], v[52:53] op_sel_hi:[0,1,1]
	v_add_f32_e32 v10, v10, v11
	v_add_f32_e32 v4, v34, v35
	v_add_f32_e32 v12, v32, v33
	v_mov_b32_e32 v11, v30
	v_mov_b32_e32 v3, v31
	v_mov_b32_e32 v5, v28
	v_mov_b32_e32 v13, v29
	v_pk_add_f32 v[2:3], v[10:11], v[2:3]
	v_pk_add_f32 v[4:5], v[4:5], v[12:13]
	v_pk_fma_f32 v[26:27], v[64:65], v[6:7], v[56:57] op_sel_hi:[0,1,1]
	v_pk_fma_f32 v[16:17], v[64:65], v[8:9], v[58:59] op_sel_hi:[0,1,1]
	v_pk_add_f32 v[2:3], v[2:3], v[4:5]
	v_pk_mov_b32 v[4:5], v[26:27], v[16:17] op_sel:[1,0]
	v_mov_b32_e32 v6, v26
	v_mov_b32_e32 v7, v17
	v_pk_add_f32 v[4:5], v[4:5], v[6:7]
	v_pk_add_f32 v[2:3], v[2:3], v[2:3] op_sel:[0,1] op_sel_hi:[1,0]
	v_pk_add_f32 v[4:5], v[4:5], v[4:5] op_sel:[0,1] op_sel_hi:[1,0]
	v_pk_fma_f32 v[10:11], v[64:65], v[20:21], v[62:63] op_sel_hi:[0,1,1]
	v_pk_fma_f32 v[12:13], v[64:65], v[18:19], v[60:61] op_sel_hi:[0,1,1]
	v_pk_fma_f32 v[6:7], v[64:65], v[24:25], v[72:73] op_sel_hi:[0,1,1]
	v_pk_fma_f32 v[8:9], v[64:65], v[22:23], v[70:71] op_sel_hi:[0,1,1]
	v_add_f32_e32 v14, v12, v13
	v_add_f32_e32 v18, v10, v11
	v_mov_b32_e32 v3, v8
	v_mov_b32_e32 v5, v9
	v_mov_b32_e32 v15, v6
	v_mov_b32_e32 v19, v7
	v_pk_add_f32 v[2:3], v[2:3], v[4:5]
	v_pk_add_f32 v[4:5], v[14:15], v[18:19]
	s_nop 0
	v_pk_add_f32 v[2:3], v[2:3], v[4:5]
	v_and_b32_e32 v4, 64, v240
	v_add_f32_e32 v2, v2, v3
	v_xor_b32_e32 v3, 16, v240
	v_add_u32_e32 v4, 64, v4
	v_cmp_lt_i32_e32 vcc, v3, v4
	s_nop 1
	v_cndmask_b32_e32 v3, v240, v3, vcc
	v_lshlrev_b32_e32 v20, 2, v3
	s_waitcnt lgkmcnt(0)
	v_mov_b32_e32 v3, v2
	s_nop 1
	v_permlane16_swap_b32_e32 v2, v3
	v_add_f32_e32 v2, v2, v3
	v_xor_b32_e32 v3, 32, v240
	v_cmp_lt_i32_e32 vcc, v3, v4
	s_nop 1
	v_cndmask_b32_e32 v3, v240, v3, vcc
	v_lshlrev_b32_e32 v21, 2, v3
	s_waitcnt lgkmcnt(0)
; __device__ __forceinline__ void ret_unit(LAS unsigned char* lds, const bfu* PROJ, const bfu* RT, const float* gn_g, bfu* CAT, int u) {
;     ...
;     s += __shfl_xor(s, 16); s += __shfl_xor(s, 32); const float mu = s * (1.f / 128.f); float q = 0.f;
; #pragma unroll
;     for (int t = 0; t < 8; ++t) { acc[t] = acc[t] - mu; q += (acc[t][0] * acc[t][0] + acc[t][1] * acc[t][1]) + (acc[t][2] * acc[t][2] + acc[t][3] * acc[t][3]); }
;     q += __shfl_xor(q, 16); q += __shfl_xor(q, 32); const float rstd = 1.f / sqrtf(q * (1.f / 128.f) + EPS);
;     const bfu* gp = P0 + (size_t)c * INW + C_RG + 4 * fq; bfu* op = CAT + (row0 + c) * DM + h * 128 + 4 * fq; const float* gg = gn_g + h * 128 + 4 * fq;
; #pragma unroll
;     for (int t = 0; t < 8; ++t) { const v2u gw = *(const v2u*)(gp + 16 * t); const f32x4 g4 = *(const f32x4*)(gg + 16 * t);
	v_mov_b32_e32 v3, v2
	v_mov_b32_e32 v22, v2
	s_nop 1
	v_permlane32_swap_b32_e32 v22, v3
	v_add_f32_e32 v22, v22, v3
	v_fmamk_f32 v47, v22, 0xbc000000, v47
	v_fmamk_f32 v43, v22, 0xbc000000, v43
	v_fmamk_f32 v45, v22, 0xbc000000, v45
	v_fmac_f32_e32 v46, 0xbc000000, v22
	v_fmamk_f32 v41, v22, 0xbc000000, v41
	v_fmac_f32_e32 v42, 0xbc000000, v22
	v_mov_b32_e32 v4, v47
	v_mov_b32_e32 v5, v43
	v_fmac_f32_e32 v44, 0xbc000000, v22
	v_fmac_f32_e32 v40, 0xbc000000, v22
	v_mov_b32_e32 v2, v46
	v_mov_b32_e32 v3, v42
	v_pk_mul_f32 v[4:5], v[4:5], v[4:5]
	v_mov_b32_e32 v14, v45
	v_mov_b32_e32 v15, v41
	v_pk_fma_f32 v[2:3], v[2:3], v[2:3], v[4:5]
	v_mov_b32_e32 v4, v44
	v_mov_b32_e32 v5, v40
	v_pk_mul_f32 v[14:15], v[14:15], v[14:15]
	v_fmamk_f32 v39, v22, 0xbc000000, v39
	v_pk_fma_f32 v[4:5], v[4:5], v[4:5], v[14:15]
	v_fmac_f32_e32 v38, 0xbc000000, v22
	v_pk_add_f32 v[2:3], v[2:3], v[4:5]
	v_fmamk_f32 v37, v22, 0xbc000000, v37
	v_fmac_f32_e32 v36, 0xbc000000, v22
	v_pk_add_f32 v[2:3], v[2:3], v[2:3] op_sel_hi:[0,1]
	v_pk_mul_f32 v[4:5], v[36:37], v[36:37]
	v_pk_mul_f32 v[14:15], v[38:39], v[38:39]
	v_fmac_f32_e32 v34, 0xbc000000, v22
	v_pk_mov_b32 v[18:19], v[14:15], v[4:5] op_sel:[1,0]
	v_mov_b32_e32 v15, v5
	v_fmac_f32_e32 v32, 0xbc000000, v22
	v_fmamk_f32 v35, v22, 0xbc000000, v35
	v_mul_f32_e32 v2, v34, v34
	v_pk_add_f32 v[4:5], v[18:19], v[14:15]
	v_fmamk_f32 v33, v22, 0xbc000000, v33
	v_pk_fma_f32 v[14:15], v[34:35], v[34:35], v[2:3] op_sel_hi:[1,1,0]
	v_mul_f32_e32 v2, v32, v32
	v_pk_add_f32 v[4:5], v[4:5], v[4:5] op_sel_hi:[0,1]
	v_pk_fma_f32 v[18:19], v[32:33], v[32:33], v[2:3] op_sel_hi:[1,1,0]
	v_fmamk_f32 v29, v22, 0xbc000000, v29
	v_fmac_f32_e32 v28, 0xbc000000, v22
	v_fmamk_f32 v31, v22, 0xbc000000, v31
	v_fmac_f32_e32 v30, 0xbc000000, v22
	v_mul_f32_e32 v14, v30, v30
	v_mul_f32_e32 v18, v31, v31
	v_mul_f32_e32 v4, v28, v28
	v_mul_f32_e32 v2, v29, v29
	v_pk_add_f32 v[14:15], v[14:15], v[18:19]
	v_pk_add_f32 v[2:3], v[4:5], v[2:3]
	v_fmamk_f32 v27, v22, 0xbc000000, v27
	v_pk_add_f32 v[2:3], v[14:15], v[2:3]
	v_fmac_f32_e32 v26, 0xbc000000, v22
	v_fmamk_f32 v17, v22, 0xbc000000, v17
	v_fmac_f32_e32 v16, 0xbc000000, v22
	v_pk_add_f32 v[2:3], v[2:3], v[2:3] op_sel_hi:[0,1]
	v_pk_mul_f32 v[4:5], v[16:17], v[16:17]
	v_pk_mul_f32 v[14:15], v[26:27], v[26:27]
	v_fmac_f32_e32 v12, 0xbc000000, v22
	v_pk_mov_b32 v[18:19], v[14:15], v[4:5] op_sel:[1,0]
	v_mov_b32_e32 v15, v5
	v_fmac_f32_e32 v10, 0xbc000000, v22
	v_fmamk_f32 v13, v22, 0xbc000000, v13
	v_mul_f32_e32 v2, v12, v12
	v_pk_add_f32 v[4:5], v[18:19], v[14:15]
	v_fmamk_f32 v11, v22, 0xbc000000, v11
	v_pk_fma_f32 v[14:15], v[12:13], v[12:13], v[2:3] op_sel_hi:[1,1,0]
	v_mul_f32_e32 v2, v10, v10
	v_pk_add_f32 v[4:5], v[4:5], v[4:5] op_sel_hi:[0,1]
	v_pk_fma_f32 v[18:19], v[10:11], v[10:11], v[2:3] op_sel_hi:[1,1,0]
	v_fmamk_f32 v7, v22, 0xbc000000, v7
	v_fmac_f32_e32 v6, 0xbc000000, v22
	v_fmamk_f32 v9, v22, 0xbc000000, v9
	v_fmac_f32_e32 v8, 0xbc000000, v22
	v_mul_f32_e32 v14, v8, v8
	v_mul_f32_e32 v18, v9, v9
	v_mul_f32_e32 v4, v6, v6
	v_mul_f32_e32 v2, v7, v7
	v_pk_add_f32 v[14:15], v[14:15], v[18:19]
	v_pk_add_f32 v[2:3], v[4:5], v[2:3]
	s_nop 0
	v_pk_add_f32 v[2:3], v[14:15], v[2:3]
	s_nop 0
	v_add_f32_e32 v2, v2, v3
	s_waitcnt lgkmcnt(0)
	v_mov_b32_e32 v3, v2
	s_nop 1
	v_permlane16_swap_b32_e32 v2, v3
	v_add_f32_e32 v2, v2, v3
	v_mov_b32_e32 v3, v2
	s_nop 1
	v_permlane32_swap_b32_e32 v2, v3
	v_add_f32_e32 v2, v2, v3
	v_fmamk_f32 v2, v2, 0x3c000000, v236
	v_cmp_gt_f32_e32 vcc, s68, v2
	v_mul_f32_e32 v3, 0x4f800000, v2
	s_nop 0
	v_cndmask_b32_e32 v2, v2, v3, vcc
	v_sqrt_f32_e32 v3, v2
	s_nop 0
	v_add_u32_e32 v4, -1, v3
	v_fma_f32 v5, -v4, v3, v2
	v_cmp_ge_f32_e64 s[40:41], 0, v5
	v_add_u32_e32 v5, 1, v3
	s_nop 0
	v_cndmask_b32_e64 v4, v3, v4, s[40:41]
	v_fma_f32 v3, -v5, v3, v2
	v_cmp_lt_f32_e64 s[40:41], 0, v3
	s_nop 1
	v_cndmask_b32_e64 v3, v4, v5, s[40:41]
	v_mul_f32_e32 v4, 0x37800000, v3
	v_cndmask_b32_e32 v3, v3, v4, vcc
	v_cmp_class_f32_e32 vcc, v2, v234
	s_nop 1
	v_cndmask_b32_e32 v2, v3, v2, vcc
	v_div_scale_f32 v3, s[22:23], v2, v2, 1.0
	v_rcp_f32_e32 v4, v3
	s_nop 0
	v_fma_f32 v5, -v3, v4, 1.0
	v_fmac_f32_e32 v4, v5, v4
	v_div_scale_f32 v5, vcc, 1.0, v2, 1.0
	v_mul_f32_e32 v14, v5, v4
	v_fma_f32 v15, -v3, v14, v5
	v_fmac_f32_e32 v14, v15, v4
	v_fma_f32 v3, -v3, v14, v5
	v_div_fmas_f32 v3, v3, v4, v14
	v_lshl_add_u64 v[4:5], s[46:47], 0, v[66:67]
	v_div_fixup_f32 v14, v3, v2, 1.0
	v_mov_b64_e32 v[2:3], s[56:57]
	v_lshlrev_b64 v[4:5], 12, v[4:5]
	v_mad_i64_i32 v[2:3], s[22:23], v66, s61, v[2:3]
	v_lshl_add_u64 v[4:5], s[44:45], 0, v[4:5]
	v_lshl_add_u64 v[2:3], v[2:3], 0, v[0:1]
	s_mov_b64 s[22:23], 0x1200
	v_lshl_add_u64 v[4:5], v[4:5], 0, s[52:53]
	v_lshl_add_u64 v[20:21], v[2:3], 0, s[22:23]
	v_lshl_add_u64 v[22:23], v[4:5], 0, v[0:1]
	s_mov_b64 s[22:23], 0x29600000
	v_lshl_add_u64 v[18:19], v[22:23], 0, s[22:23]
	s_lshl_b64 s[22:23], s[50:51], 2
	v_add_co_u32_e32 v2, vcc, s62, v2
	s_add_u32 s40, s20, s22
	s_nop 0
	v_addc_co_u32_e32 v3, vcc, 0, v3, vcc
	s_addc_u32 s41, s35, s23
	global_load_dwordx2 v[120:121], v[2:3], off offset:512 nt
	global_load_dwordx4 v[122:125], v69, s[40:41]
	global_load_dwordx2 v[126:127], v[20:21], off offset:32 nt
	global_load_dwordx4 v[128:131], v69, s[40:41] offset:64
	global_load_dwordx2 v[132:133], v[20:21], off offset:64 nt
	global_load_dwordx4 v[134:137], v69, s[40:41] offset:128
	global_load_dwordx2 v[138:139], v[20:21], off offset:96 nt
	global_load_dwordx4 v[140:143], v69, s[40:41] offset:192
	global_load_dwordx2 v[144:145], v[20:21], off offset:128 nt
	global_load_dwordx4 v[146:149], v69, s[40:41] offset:256
	global_load_dwordx2 v[150:151], v[20:21], off offset:160 nt
	global_load_dwordx4 v[152:155], v69, s[40:41] offset:320
	global_load_dwordx2 v[156:157], v[20:21], off offset:192 nt
	global_load_dwordx4 v[158:161], v69, s[40:41] offset:384
	global_load_dwordx2 v[162:163], v[20:21], off offset:224 nt
	global_load_dwordx4 v[164:167], v69, s[40:41] offset:448
	s_nop 0
	s_mov_b32 s20, 0x29600000
	s_waitcnt vmcnt(0)
; __device__ __forceinline__ unsigned pk2(float lo, float hi) { return pg8::cvt_pk_bf16(lo, hi); }
; __device__ __forceinline__ float silu_f(float g) { return g * frcp(1.f + fexp2(-LOG2E * g)); }
; __device__ __forceinline__ void ret_unit(LAS unsigned char* lds, const bfu* PROJ, const bfu* RT, const float* gn_g, bfu* CAT, int u) {
;     ...
;     for (int t = 0; t < 8; ++t) { const v2u gw = *(const v2u*)(gp + 16 * t); const f32x4 g4 = *(const f32x4*)(gg + 16 * t);
;         const float o0 = silu_f(bflo(gw.x)) * acc[t][0] * rstd * g4.x, o1 = silu_f(bfhi(gw.x)) * acc[t][1] * rstd * g4.y, o2 = silu_f(bflo(gw.y)) * acc[t][2] * rstd * g4.z, o3 = silu_f(bfhi(gw.y)) * acc[t][3] * rstd * g4.w;
;         v2u w; w.x = pk2(o0, o1); w.y = pk2(o2, o3); *(v2u*)(op + 16 * t) = w; }
	v_lshlrev_b32_e32 v48, 16, v120
	v_mul_f32_e32 v0, 0xbfb8aa3b, v48
	v_exp_f32_e32 v0, v0
	v_and_b32_e32 v49, 0xffff0000, v120
	v_lshlrev_b32_e32 v24, 16, v121
	v_and_b32_e32 v25, 0xffff0000, v121
	v_add_f32_e32 v0, 1.0, v0
	v_rcp_f32_e32 v50, v0
	v_mul_f32_e32 v0, 0xbfb8aa3b, v49
	v_exp_f32_e32 v0, v0
	s_nop 0
	v_add_f32_e32 v0, 1.0, v0
	v_rcp_f32_e32 v51, v0
	v_mul_f32_e32 v0, 0xbfb8aa3b, v24
	v_exp_f32_e32 v0, v0
	v_pk_mul_f32 v[48:49], v[50:51], v[48:49]
	s_nop 0
	v_pk_mul_f32 v[46:47], v[46:47], v[48:49]
	v_add_f32_e32 v0, 1.0, v0
	v_pk_mul_f32 v[46:47], v[46:47], v[14:15] op_sel_hi:[1,0]
	v_pk_mul_f32 v[2:3], v[122:123], v[46:47]
	v_rcp_f32_e32 v46, v0
	v_mul_f32_e32 v0, 0xbfb8aa3b, v25
	v_exp_f32_e32 v0, v0
	v_cvt_pk_bf16_f32 v2, v2, v3
	v_add_f32_e32 v0, 1.0, v0
	v_rcp_f32_e32 v47, v0
	s_nop 0
	v_pk_mul_f32 v[24:25], v[46:47], v[24:25]
	s_nop 0
	v_pk_mul_f32 v[24:25], v[44:45], v[24:25]
	s_nop 0
	v_pk_mul_f32 v[24:25], v[24:25], v[14:15] op_sel_hi:[1,0]
	s_nop 0
	v_pk_mul_f32 v[4:5], v[124:125], v[24:25]
	s_nop 0
	v_cvt_pk_bf16_f32 v3, v4, v5
	v_add_co_u32_e32 v4, vcc, s20, v22
	s_nop 1
	v_addc_co_u32_e32 v5, vcc, 0, v23, vcc
	global_store_dwordx2 v[4:5], v[2:3], off
	s_nop 0
	v_lshlrev_b32_e32 v24, 16, v126
	v_mul_f32_e32 v0, 0xbfb8aa3b, v24
	v_exp_f32_e32 v0, v0
	v_and_b32_e32 v25, 0xffff0000, v126
	v_lshlrev_b32_e32 v22, 16, v127
	v_and_b32_e32 v23, 0xffff0000, v127
	v_add_f32_e32 v0, 1.0, v0
	v_rcp_f32_e32 v44, v0
	v_mul_f32_e32 v0, 0xbfb8aa3b, v25
	v_exp_f32_e32 v0, v0
	s_nop 0
	v_add_f32_e32 v0, 1.0, v0
	v_rcp_f32_e32 v45, v0
	v_mul_f32_e32 v0, 0xbfb8aa3b, v22
	v_exp_f32_e32 v0, v0
	v_pk_mul_f32 v[24:25], v[44:45], v[24:25]
	s_nop 0
	v_pk_mul_f32 v[24:25], v[42:43], v[24:25]
	v_add_f32_e32 v0, 1.0, v0
	v_pk_mul_f32 v[24:25], v[24:25], v[14:15] op_sel_hi:[1,0]
	v_pk_mul_f32 v[2:3], v[128:129], v[24:25]
	v_rcp_f32_e32 v24, v0
	v_mul_f32_e32 v0, 0xbfb8aa3b, v23
	v_exp_f32_e32 v0, v0
	v_cvt_pk_bf16_f32 v2, v2, v3
	v_add_f32_e32 v0, 1.0, v0
	v_rcp_f32_e32 v25, v0
	s_nop 0
	v_pk_mul_f32 v[22:23], v[24:25], v[22:23]
	s_nop 0
	v_pk_mul_f32 v[22:23], v[40:41], v[22:23]
	s_nop 0
	v_pk_mul_f32 v[22:23], v[22:23], v[14:15] op_sel_hi:[1,0]
	s_nop 0
	v_pk_mul_f32 v[4:5], v[130:131], v[22:23]
	s_nop 0
	v_cvt_pk_bf16_f32 v3, v4, v5
	global_store_dwordx2 v[18:19], v[2:3], off offset:32
	s_nop 0
	v_lshlrev_b32_e32 v24, 16, v132
	v_mul_f32_e32 v0, 0xbfb8aa3b, v24
	v_exp_f32_e32 v0, v0
	v_and_b32_e32 v25, 0xffff0000, v132
	v_lshlrev_b32_e32 v22, 16, v133
	v_and_b32_e32 v23, 0xffff0000, v133
	v_add_f32_e32 v0, 1.0, v0
	v_rcp_f32_e32 v40, v0
	v_mul_f32_e32 v0, 0xbfb8aa3b, v25
	v_exp_f32_e32 v0, v0
	s_nop 0
	v_add_f32_e32 v0, 1.0, v0
	v_rcp_f32_e32 v41, v0
	v_mul_f32_e32 v0, 0xbfb8aa3b, v22
	v_exp_f32_e32 v0, v0
	v_pk_mul_f32 v[24:25], v[40:41], v[24:25]
	s_nop 0
	v_pk_mul_f32 v[24:25], v[38:39], v[24:25]
	v_add_f32_e32 v0, 1.0, v0
	v_pk_mul_f32 v[24:25], v[24:25], v[14:15] op_sel_hi:[1,0]
	v_pk_mul_f32 v[2:3], v[134:135], v[24:25]
	v_rcp_f32_e32 v24, v0
	v_mul_f32_e32 v0, 0xbfb8aa3b, v23
	v_exp_f32_e32 v0, v0
	v_cvt_pk_bf16_f32 v2, v2, v3
	v_add_f32_e32 v0, 1.0, v0
	v_rcp_f32_e32 v25, v0
	s_nop 0
	v_pk_mul_f32 v[22:23], v[24:25], v[22:23]
	s_nop 0
	v_pk_mul_f32 v[22:23], v[36:37], v[22:23]
	s_nop 0
	v_pk_mul_f32 v[22:23], v[22:23], v[14:15] op_sel_hi:[1,0]
	s_nop 0
	v_pk_mul_f32 v[4:5], v[136:137], v[22:23]
	s_nop 0
	v_cvt_pk_bf16_f32 v3, v4, v5
	global_store_dwordx2 v[18:19], v[2:3], off offset:64
	s_nop 0
	v_lshlrev_b32_e32 v24, 16, v138
	v_mul_f32_e32 v0, 0xbfb8aa3b, v24
	v_exp_f32_e32 v0, v0
	v_and_b32_e32 v25, 0xffff0000, v138
	v_lshlrev_b32_e32 v22, 16, v139
	v_and_b32_e32 v23, 0xffff0000, v139
	v_add_f32_e32 v0, 1.0, v0
	v_rcp_f32_e32 v36, v0
	v_mul_f32_e32 v0, 0xbfb8aa3b, v25
	v_exp_f32_e32 v0, v0
	s_nop 0
	v_add_f32_e32 v0, 1.0, v0
	v_rcp_f32_e32 v37, v0
	v_mul_f32_e32 v0, 0xbfb8aa3b, v22
	v_exp_f32_e32 v0, v0
	v_pk_mul_f32 v[24:25], v[36:37], v[24:25]
	s_nop 0
	v_pk_mul_f32 v[24:25], v[34:35], v[24:25]
	v_add_f32_e32 v0, 1.0, v0
	v_pk_mul_f32 v[24:25], v[24:25], v[14:15] op_sel_hi:[1,0]
	v_pk_mul_f32 v[2:3], v[140:141], v[24:25]
	v_rcp_f32_e32 v24, v0
	v_mul_f32_e32 v0, 0xbfb8aa3b, v23
	v_exp_f32_e32 v0, v0
	v_cvt_pk_bf16_f32 v2, v2, v3
	v_add_f32_e32 v0, 1.0, v0
	v_rcp_f32_e32 v25, v0
	s_nop 0
	v_pk_mul_f32 v[22:23], v[24:25], v[22:23]
	s_nop 0
	v_pk_mul_f32 v[22:23], v[32:33], v[22:23]
	s_nop 0
	v_pk_mul_f32 v[22:23], v[22:23], v[14:15] op_sel_hi:[1,0]
	s_nop 0
	v_pk_mul_f32 v[4:5], v[142:143], v[22:23]
	s_nop 0
	v_cvt_pk_bf16_f32 v3, v4, v5
	global_store_dwordx2 v[18:19], v[2:3], off offset:96
; __device__ __forceinline__ unsigned pk2(float lo, float hi) { return pg8::cvt_pk_bf16(lo, hi); }
; __device__ __forceinline__ float silu_f(float g) { return g * frcp(1.f + fexp2(-LOG2E * g)); }
; __device__ __forceinline__ void ret_unit(LAS unsigned char* lds, const bfu* PROJ, const bfu* RT, const float* gn_g, bfu* CAT, int u) {
;     ...
;     for (int t = 0; t < 8; ++t) { const v2u gw = *(const v2u*)(gp + 16 * t); const f32x4 g4 = *(const f32x4*)(gg + 16 * t);
;         const float o0 = silu_f(bflo(gw.x)) * acc[t][0] * rstd * g4.x, o1 = silu_f(bfhi(gw.x)) * acc[t][1] * rstd * g4.y, o2 = silu_f(bflo(gw.y)) * acc[t][2] * rstd * g4.z, o3 = silu_f(bfhi(gw.y)) * acc[t][3] * rstd * g4.w;
;         v2u w; w.x = pk2(o0, o1); w.y = pk2(o2, o3); *(v2u*)(op + 16 * t) = w; }
;     __syncthreads();
	s_nop 0
	v_lshlrev_b32_e32 v24, 16, v144
	v_mul_f32_e32 v0, 0xbfb8aa3b, v24
	v_exp_f32_e32 v0, v0
	v_and_b32_e32 v25, 0xffff0000, v144
	v_lshlrev_b32_e32 v22, 16, v145
	v_and_b32_e32 v23, 0xffff0000, v145
	v_add_f32_e32 v0, 1.0, v0
	v_rcp_f32_e32 v32, v0
	v_mul_f32_e32 v0, 0xbfb8aa3b, v25
	v_exp_f32_e32 v0, v0
	s_nop 0
	v_add_f32_e32 v0, 1.0, v0
	v_rcp_f32_e32 v33, v0
	v_mul_f32_e32 v0, 0xbfb8aa3b, v22
	v_exp_f32_e32 v0, v0
	v_pk_mul_f32 v[24:25], v[32:33], v[24:25]
	s_nop 0
	v_pk_mul_f32 v[24:25], v[30:31], v[24:25]
	v_add_f32_e32 v0, 1.0, v0
	v_pk_mul_f32 v[24:25], v[24:25], v[14:15] op_sel_hi:[1,0]
	v_pk_mul_f32 v[2:3], v[146:147], v[24:25]
	v_rcp_f32_e32 v24, v0
	v_mul_f32_e32 v0, 0xbfb8aa3b, v23
	v_exp_f32_e32 v0, v0
	v_cvt_pk_bf16_f32 v2, v2, v3
	v_add_f32_e32 v0, 1.0, v0
	v_rcp_f32_e32 v25, v0
	s_nop 0
	v_pk_mul_f32 v[22:23], v[24:25], v[22:23]
	s_nop 0
	v_pk_mul_f32 v[22:23], v[28:29], v[22:23]
	s_nop 0
	v_pk_mul_f32 v[22:23], v[22:23], v[14:15] op_sel_hi:[1,0]
	s_nop 0
	v_pk_mul_f32 v[4:5], v[148:149], v[22:23]
	s_nop 0
	v_cvt_pk_bf16_f32 v3, v4, v5
	global_store_dwordx2 v[18:19], v[2:3], off offset:128
	s_nop 0
	v_lshlrev_b32_e32 v24, 16, v150
	v_mul_f32_e32 v0, 0xbfb8aa3b, v24
	v_exp_f32_e32 v0, v0
	v_and_b32_e32 v25, 0xffff0000, v150
	v_lshlrev_b32_e32 v22, 16, v151
	v_and_b32_e32 v23, 0xffff0000, v151
	v_add_f32_e32 v0, 1.0, v0
	v_rcp_f32_e32 v28, v0
	v_mul_f32_e32 v0, 0xbfb8aa3b, v25
	v_exp_f32_e32 v0, v0
	s_nop 0
	v_add_f32_e32 v0, 1.0, v0
	v_rcp_f32_e32 v29, v0
	v_mul_f32_e32 v0, 0xbfb8aa3b, v22
	v_exp_f32_e32 v0, v0
	v_pk_mul_f32 v[24:25], v[28:29], v[24:25]
	s_nop 0
	v_pk_mul_f32 v[24:25], v[26:27], v[24:25]
	v_add_f32_e32 v0, 1.0, v0
	v_pk_mul_f32 v[24:25], v[14:15], v[24:25] op_sel_hi:[0,1]
	v_pk_mul_f32 v[2:3], v[152:153], v[24:25]
	v_rcp_f32_e32 v24, v0
	v_mul_f32_e32 v0, 0xbfb8aa3b, v23
	v_exp_f32_e32 v0, v0
	v_cvt_pk_bf16_f32 v2, v2, v3
	v_add_f32_e32 v0, 1.0, v0
	v_rcp_f32_e32 v25, v0
	s_nop 0
	v_pk_mul_f32 v[22:23], v[24:25], v[22:23]
	s_nop 0
	v_pk_mul_f32 v[16:17], v[16:17], v[22:23]
	s_nop 0
	v_pk_mul_f32 v[16:17], v[14:15], v[16:17] op_sel_hi:[0,1]
	v_pk_mul_f32 v[4:5], v[154:155], v[16:17]
	s_nop 0
	v_cvt_pk_bf16_f32 v3, v4, v5
	global_store_dwordx2 v[18:19], v[2:3], off offset:160
	s_nop 0
	v_lshlrev_b32_e32 v22, 16, v156
	v_mul_f32_e32 v0, 0xbfb8aa3b, v22
	v_exp_f32_e32 v0, v0
	v_and_b32_e32 v23, 0xffff0000, v156
	v_add_f32_e32 v0, 1.0, v0
	v_rcp_f32_e32 v24, v0
	v_mul_f32_e32 v0, 0xbfb8aa3b, v23
	v_exp_f32_e32 v0, v0
	s_nop 0
	v_add_f32_e32 v0, 1.0, v0
	v_rcp_f32_e32 v25, v0
	s_nop 0
	v_pk_mul_f32 v[22:23], v[24:25], v[22:23]
	s_nop 0
	v_pk_mul_f32 v[12:13], v[12:13], v[22:23]
	s_nop 0
	v_pk_mul_f32 v[12:13], v[14:15], v[12:13] op_sel_hi:[0,1]
	v_pk_mul_f32 v[2:3], v[158:159], v[12:13]
	v_lshlrev_b32_e32 v12, 16, v157
	v_mul_f32_e32 v0, 0xbfb8aa3b, v12
	v_exp_f32_e32 v0, v0
	v_and_b32_e32 v13, 0xffff0000, v157
	v_cvt_pk_bf16_f32 v2, v2, v3
	v_add_f32_e32 v0, 1.0, v0
	v_rcp_f32_e32 v16, v0
	v_mul_f32_e32 v0, 0xbfb8aa3b, v13
	v_exp_f32_e32 v0, v0
	s_nop 0
	v_add_f32_e32 v0, 1.0, v0
	v_rcp_f32_e32 v17, v0
	s_nop 0
	v_pk_mul_f32 v[12:13], v[16:17], v[12:13]
	s_nop 0
	v_pk_mul_f32 v[10:11], v[10:11], v[12:13]
	s_nop 0
	v_pk_mul_f32 v[10:11], v[14:15], v[10:11] op_sel_hi:[0,1]
	v_pk_mul_f32 v[4:5], v[160:161], v[10:11]
	s_nop 0
	v_cvt_pk_bf16_f32 v3, v4, v5
	global_store_dwordx2 v[18:19], v[2:3], off offset:192
	s_nop 0
	v_lshlrev_b32_e32 v12, 16, v162
	v_mul_f32_e32 v0, 0xbfb8aa3b, v12
	v_exp_f32_e32 v0, v0
	v_and_b32_e32 v13, 0xffff0000, v162
	v_add_f32_e32 v0, 1.0, v0
	v_rcp_f32_e32 v16, v0
	v_mul_f32_e32 v0, 0xbfb8aa3b, v13
	v_exp_f32_e32 v0, v0
	s_nop 0
	v_add_f32_e32 v0, 1.0, v0
	v_rcp_f32_e32 v17, v0
	s_nop 0
	v_pk_mul_f32 v[12:13], v[16:17], v[12:13]
	s_nop 0
	v_pk_mul_f32 v[8:9], v[8:9], v[12:13]
	s_nop 0
	v_pk_mul_f32 v[8:9], v[14:15], v[8:9] op_sel_hi:[0,1]
	v_pk_mul_f32 v[2:3], v[164:165], v[8:9]
	v_lshlrev_b32_e32 v8, 16, v163
	v_mul_f32_e32 v0, 0xbfb8aa3b, v8
	v_exp_f32_e32 v0, v0
	v_and_b32_e32 v9, 0xffff0000, v163
	v_cvt_pk_bf16_f32 v2, v2, v3
	v_add_f32_e32 v0, 1.0, v0
	v_rcp_f32_e32 v10, v0
	v_mul_f32_e32 v0, 0xbfb8aa3b, v9
	v_exp_f32_e32 v0, v0
	s_nop 0
	v_add_f32_e32 v0, 1.0, v0
	v_rcp_f32_e32 v11, v0
	s_nop 0
	v_pk_mul_f32 v[8:9], v[10:11], v[8:9]
	s_nop 0
	v_pk_mul_f32 v[6:7], v[6:7], v[8:9]
	s_nop 0
	v_pk_mul_f32 v[6:7], v[14:15], v[6:7] op_sel_hi:[0,1]
	v_pk_mul_f32 v[4:5], v[166:167], v[6:7]
	s_nop 0
	v_cvt_pk_bf16_f32 v3, v4, v5
	global_store_dwordx2 v[18:19], v[2:3], off offset:224
	s_barrier

; #define LAS __attribute__((address_space(3)))
; __device__ __forceinline__ float gelu_tanh(float x) { const float z = 0.7978845608028654f * (x + 0.044715f * x * x * x); return x * frcp(1.f + fexp2(-2.f * LOG2E * z)); }
; __device__ __forceinline__ void sgu_unit(LAS unsigned char* lds, const bfu* PROJ, const bfu* SW  , const float* ln_g, const float* ln_b, const float* sb, bfu* CAT, int s) {
;     int tid = threadIdx.x; asm volatile("" : "+v"(tid)); const int lane = tid & 63, wid = __builtin_amdgcn_readfirstlane(tid >> 6); (void)lane; (void)wid;
;     const int chunk = s >> 2, g = s & 3; const size_t row0 = (size_t)chunk * 128;
;     LAS bfu* Ws = (LAS bfu*)lds; LAS bfu* Vt = (LAS bfu*)(lds + TILE_B); LAS float* red = (LAS float*)(lds + 2 * TILE_B);
;     stage_nat(Ws, SW + (size_t)g * 16384, 128, tid);
;     const int sr = tid & 127, qd = tid >> 7;
;     const bfu* vp = PROJ + (row0 + sr) * INW + C_SV + g * 128 + qd * 32; float v[32]; float a = 0.f, a2 = 0.f;
; #pragma unroll
;     for (int k = 0; k < 4; ++k) { const v4u w = *(const v4u*)(vp + 8 * k);
; #pragma unroll
;         for (int j = 0; j < 4; ++j) { const float x0 = gelu_tanh(bflo(w[j])), x1 = gelu_tanh(bfhi(w[j])); v[8 * k + 2 * j] = x0; v[8 * k + 2 * j + 1] = x1; a += x0 + x1; a2 += x0 * x0 + x1 * x1; } }
.LBB0_422:
	s_mov_b32 s22, 21
	s_ashr_i32 s23, s22, 31
	s_lshl_b64 s[22:23], s[22:23], 3
	s_add_u32 s22, s0, s22
	s_addc_u32 s23, s1, s23
	s_load_dwordx2 s[22:23], s[22:23], 0x0
	s_mov_b32 s34, 21
	s_mov_b32 s46, 12
	s_mov_b32 s48, 21
	s_waitcnt lgkmcnt(0)
	s_add_u32 s44, s22, 0x1ce00000
	s_addc_u32 s45, s23, 0
	s_ashr_i32 s35, s34, 31
	s_lshl_b64 s[22:23], s[34:35], 3
	s_add_u32 s22, s0, s22
	s_addc_u32 s23, s1, s23
	s_load_dwordx2 s[22:23], s[22:23], 0x0
	s_mov_b32 s34, 9
	v_mov_b32_e32 v16, v232
	s_movk_i32 s56, 0x2000
	s_waitcnt lgkmcnt(0)
	s_add_u32 s20, s22, s55
	s_addc_u32 s53, s23, 0
	s_ashr_i32 s35, s34, 31
	s_lshl_b64 s[22:23], s[34:35], 3
	s_add_u32 s22, s0, s22
	s_addc_u32 s23, s1, s23
	s_load_dwordx2 s[22:23], s[22:23], 0x0
	s_mov_b32 s34, 10
	s_waitcnt lgkmcnt(0)
	s_add_u32 s22, s22, s26
	s_addc_u32 s23, s23, s27
	s_ashr_i32 s35, s34, 31
	s_lshl_b64 s[34:35], s[34:35], 3
	s_add_u32 s34, s0, s34
	s_addc_u32 s35, s1, s35
	s_load_dwordx2 s[40:41], s[34:35], 0x0
	s_waitcnt lgkmcnt(0)
	s_add_u32 s35, s40, s26
	s_addc_u32 s40, s41, s27
	s_ashr_i32 s47, s46, 31
	s_lshl_b64 s[46:47], s[46:47], 3
	s_add_u32 s46, s0, s46
	s_addc_u32 s47, s1, s47
	s_load_dwordx2 s[46:47], s[46:47], 0x0
	s_waitcnt lgkmcnt(0)
	s_add_u32 s50, s46, s26
	s_addc_u32 s51, s47, s27
	s_ashr_i32 s49, s48, 31
	s_lshl_b64 s[46:47], s[48:49], 3
	s_add_u32 s46, s0, s46
	s_addc_u32 s47, s1, s47
	s_lshl_b32 s41, s92, 5
	s_and_b32 s34, s92, 3
	s_and_b32 s41, s41, 0x3f80
	s_xor_b32 s52, s41, 0x2000
	s_lshl_b32 s41, s34, 15
	s_load_dwordx2 s[46:47], s[46:47], 0x0
	s_add_u32 s48, s20, s41
	v_lshlrev_b32_e32 v0, 4, v16
	s_addc_u32 s49, s53, 0
	v_and_b32_e32 v0, 0xf0, v0
	v_lshl_add_u64 v[2:3], s[48:49], 0, v[0:1]
	v_add_u32_e32 v4, 0, v0
	v_ashrrev_i32_e32 v6, 4, v16
	v_add_u32_e32 v0, 0x200, v16
	s_mov_b64 s[48:49], 0x100000
	v_ashrrev_i32_e32 v7, 31, v6
	v_ashrrev_i32_e32 v10, 4, v0
	v_lshl_add_u64 v[2:3], v[2:3], 0, s[48:49]
	v_lshlrev_b64 v[8:9], 8, v[6:7]
	v_ashrrev_i32_e32 v11, 31, v10
	v_lshl_add_u64 v[8:9], v[2:3], 0, v[8:9]
	v_lshlrev_b64 v[12:13], 8, v[10:11]
	v_add_u32_e32 v0, 0x400, v16
	v_lshl_add_u64 v[12:13], v[2:3], 0, v[12:13]
	global_load_dwordx4 v[20:23], v[8:9], off
	global_load_dwordx4 v[24:27], v[12:13], off
	v_ashrrev_i32_e32 v8, 4, v0
	v_add_u32_e32 v0, 0x600, v16
	v_ashrrev_i32_e32 v36, 4, v0
	v_ashrrev_i32_e32 v9, 31, v8
	v_ashrrev_i32_e32 v37, 31, v36
	v_and_b32_e32 v18, 0x7f, v16
	v_lshlrev_b64 v[12:13], 8, v[8:9]
	v_lshlrev_b64 v[14:15], 8, v[36:37]
	v_or_b32_e32 v0, s52, v18
	v_lshl_add_u64 v[12:13], v[2:3], 0, v[12:13]
	v_lshl_add_u64 v[2:3], v[2:3], 0, v[14:15]
	v_mul_u32_u24_e32 v0, 0x3200, v0
	v_ashrrev_i32_e32 v17, 2, v16
	global_load_dwordx4 v[28:31], v[12:13], off
	global_load_dwordx4 v[32:35], v[2:3], off
	v_lshl_add_u64 v[2:3], s[44:45], 0, v[0:1]
	s_lshl_b32 s20, s34, 8
	v_and_b32_e32 v14, 0xffffffe0, v17
	v_lshl_add_u64 v[2:3], v[2:3], 0, s[20:21]
	v_ashrrev_i32_e32 v15, 31, v14
	v_lshl_add_u64 v[2:3], v[14:15], 1, v[2:3]
	v_add_co_u32_e32 v12, vcc, s56, v2
	v_mad_u64_u32 v[38:39], s[48:49], v6, s65, v[4:5]
	s_nop 0
	v_addc_co_u32_e32 v13, vcc, 0, v3, vcc
	global_load_dwordx4 v[40:43], v[12:13], off offset:3584
	v_mad_u64_u32 v[44:45], s[48:49], v10, s65, v[4:5]
	v_mad_u64_u32 v[46:47], s[48:49], v8, s65, v[4:5]
	v_mad_u64_u32 v[36:37], s[48:49], v36, s65, v[4:5]
	s_mov_b64 s[48:49], 0x2e00
	s_nop 0
	v_lshl_add_u64 v[10:11], v[2:3], 0, s[48:49]
	global_load_dwordx4 v[2:5], v[10:11], off offset:48
	global_load_dwordx4 v[6:9], v[10:11], off offset:32
	s_nop 0
	global_load_dwordx4 v[10:13], v[10:11], off offset:16
	s_lshl_b32 s41, s34, 9
	s_add_u32 s22, s22, s41
	s_addc_u32 s23, s23, 0
	s_mov_b32 s53, s21
	s_waitcnt vmcnt(0)
	ds_write_b128 v38, v[20:23]
	s_waitcnt vmcnt(6)
	ds_write_b128 v44, v[24:27]
	s_waitcnt vmcnt(5)
	ds_write_b128 v46, v[28:31]
	s_waitcnt vmcnt(4)
	ds_write_b128 v36, v[32:35]
	s_waitcnt vmcnt(3)
	v_and_b32_e32 v26, 0xffff0000, v40
	v_lshlrev_b32_e32 v25, 16, v40
	v_and_b32_e32 v31, 0xffff0000, v41
	v_mul_f32_e32 v19, 0x3d372713, v26
	v_lshlrev_b32_e32 v28, 16, v41
	v_mul_f32_e32 v0, 0x3d372713, v25
	v_mul_f32_e32 v21, 0x3d372713, v31
	v_mul_f32_e32 v19, v19, v26
	v_mul_f32_e32 v20, 0x3d372713, v28
	v_mul_f32_e32 v0, v0, v25
	v_mul_f32_e32 v21, v21, v31
	v_fma_f32 v19, v19, v26, v26
	v_mul_f32_e32 v20, v20, v28
	v_fma_f32 v0, v0, v25, v25
	v_fma_f32 v21, v21, v31, v31
	v_mul_f32_e32 v19, 0x3f4c422a, v19
	v_fma_f32 v20, v20, v28, v28
	v_mul_f32_e32 v0, 0x3f4c422a, v0
	v_mul_f32_e32 v21, 0x3f4c422a, v21
	v_mul_f32_e32 v19, 0xc038aa3b, v19
	v_mul_f32_e32 v20, 0x3f4c422a, v20
	v_mul_f32_e32 v0, 0xc038aa3b, v0
	v_mul_f32_e32 v21, 0xc038aa3b, v21
	v_exp_f32_e32 v19, v19
	v_mul_f32_e32 v20, 0xc038aa3b, v20
	v_exp_f32_e32 v0, v0
	v_exp_f32_e32 v21, v21
	v_exp_f32_e32 v20, v20
	v_add_f32_e32 v19, 1.0, v19
	v_add_f32_e32 v0, 1.0, v0
	v_add_f32_e32 v21, 1.0, v21
	v_rcp_f32_e32 v40, v19
	v_add_f32_e32 v20, 1.0, v20
	v_rcp_f32_e32 v41, v0
	v_rcp_f32_e32 v35, v21
	v_rcp_f32_e32 v38, v20
	v_mul_f32_e32 v19, v40, v26
	v_mul_f32_e32 v0, v41, v25
	v_mul_f32_e32 v21, v35, v31
	v_fma_f32 v20, v41, v25, v19
	v_mul_f32_e32 v24, v19, v19
	v_add_f32_e32 v19, 0, v20
	v_fmac_f32_e32 v24, v0, v0
	v_fma_f32 v0, v38, v28, v21
	v_add_f32_e32 v0, v0, v19
	v_lshlrev_b32_e32 v19, 16, v42
	v_mul_f32_e32 v20, 0x3d372713, v19
	v_mul_f32_e32 v20, v20, v19
	v_fma_f32 v20, v20, v19, v19
	v_mul_f32_e32 v20, 0x3f4c422a, v20
	v_mul_f32_e32 v20, 0xc038aa3b, v20
	v_exp_f32_e32 v22, v20
	v_and_b32_e32 v20, 0xffff0000, v42
	v_mul_f32_e32 v27, 0x3d372713, v20
	v_mul_f32_e32 v27, v27, v20
	v_fma_f32 v27, v27, v20, v20
	v_mul_f32_e32 v27, 0x3f4c422a, v27
	v_mul_f32_e32 v27, 0xc038aa3b, v27
	v_exp_f32_e32 v27, v27
	v_mul_f32_e32 v29, v21, v21
	v_add_f32_e32 v21, 1.0, v22
	v_rcp_f32_e32 v22, v21
	v_add_f32_e32 v21, 1.0, v27
	v_rcp_f32_e32 v21, v21
	v_mul_f32_e32 v23, v38, v28
	v_fmac_f32_e32 v29, v23, v23
	v_add_f32_e32 v30, v24, v29
	v_mul_f32_e32 v27, v21, v20
	v_fma_f32 v23, v22, v19, v27
	v_add_f32_e32 v0, v23, v0
	v_lshlrev_b32_e32 v23, 16, v43
	v_mul_f32_e32 v24, 0x3d372713, v23
	v_mul_f32_e32 v24, v24, v23
	v_fma_f32 v24, v24, v23, v23
	v_mul_f32_e32 v24, 0x3f4c422a, v24
	v_mul_f32_e32 v24, 0xc038aa3b, v24
	v_exp_f32_e32 v29, v24
	v_and_b32_e32 v24, 0xffff0000, v43
	v_mul_f32_e32 v33, 0x3d372713, v24
	v_mul_f32_e32 v33, v33, v24
	v_fma_f32 v33, v33, v24, v24
	v_mul_f32_e32 v33, 0x3f4c422a, v33
	v_mul_f32_e32 v33, 0xc038aa3b, v33
	v_exp_f32_e32 v33, v33
	v_mul_f32_e32 v34, v27, v27
	v_add_f32_e32 v27, 1.0, v29
	v_rcp_f32_e32 v29, v27
	v_add_f32_e32 v27, 1.0, v33
	v_rcp_f32_e32 v27, v27
	v_mul_f32_e32 v32, v22, v19
	v_fmac_f32_e32 v34, v32, v32
	v_add_f32_e32 v34, v34, v30
	v_mul_f32_e32 v32, v27, v24
	v_fma_f32 v30, v29, v23, v32
	v_add_f32_e32 v0, v30, v0
	s_waitcnt vmcnt(0)
; __device__ __forceinline__ float gelu_tanh(float x) { const float z = 0.7978845608028654f * (x + 0.044715f * x * x * x); return x * frcp(1.f + fexp2(-2.f * LOG2E * z)); }
; __device__ __forceinline__ void sgu_unit(LAS unsigned char* lds, const bfu* PROJ, const bfu* SW  , const float* ln_g, const float* ln_b, const float* sb, bfu* CAT, int s) {
;     ...
;     for (int k = 0; k < 4; ++k) { const v4u w = *(const v4u*)(vp + 8 * k);
; #pragma unroll
;         for (int j = 0; j < 4; ++j) { const float x0 = gelu_tanh(bflo(w[j])), x1 = gelu_tanh(bfhi(w[j])); v[8 * k + 2 * j] = x0; v[8 * k + 2 * j + 1] = x1; a += x0 + x1; a2 += x0 * x0 + x1 * x1; } }
	v_lshlrev_b32_e32 v30, 16, v10
	v_mul_f32_e32 v33, 0x3d372713, v30
	v_and_b32_e32 v10, 0xffff0000, v10
	v_mul_f32_e32 v33, v33, v30
	v_mul_f32_e32 v37, 0x3d372713, v10
	v_fma_f32 v33, v33, v30, v30
	v_mul_f32_e32 v37, v37, v10
	v_mul_f32_e32 v33, 0x3f4c422a, v33
	v_fma_f32 v37, v37, v10, v10
	v_mul_f32_e32 v33, 0xc038aa3b, v33
	v_mul_f32_e32 v37, 0x3f4c422a, v37
	v_exp_f32_e32 v33, v33
	v_mul_f32_e32 v37, 0xc038aa3b, v37
	v_exp_f32_e32 v37, v37
	v_mul_f32_e32 v39, v32, v32
	v_add_f32_e32 v32, 1.0, v33
	v_rcp_f32_e32 v33, v32
	v_add_f32_e32 v32, 1.0, v37
	v_rcp_f32_e32 v32, v32
	v_mul_f32_e32 v36, v29, v23
	v_fmac_f32_e32 v39, v36, v36
	v_add_f32_e32 v37, v39, v34
	v_mul_f32_e32 v36, v32, v10
	v_fma_f32 v34, v33, v30, v36
	v_add_f32_e32 v0, v34, v0
	v_lshlrev_b32_e32 v34, 16, v11
	v_mul_f32_e32 v39, 0x3d372713, v34
	v_and_b32_e32 v11, 0xffff0000, v11
	v_mul_f32_e32 v39, v39, v34
	v_mul_f32_e32 v43, 0x3d372713, v11
	v_fma_f32 v39, v39, v34, v34
	v_mul_f32_e32 v43, v43, v11
	v_mul_f32_e32 v39, 0x3f4c422a, v39
	v_fma_f32 v43, v43, v11, v11
	v_mul_f32_e32 v39, 0xc038aa3b, v39
	v_mul_f32_e32 v43, 0x3f4c422a, v43
	v_exp_f32_e32 v39, v39
	v_mul_f32_e32 v43, 0xc038aa3b, v43
	v_exp_f32_e32 v43, v43
	v_mul_f32_e32 v44, v36, v36
	v_add_f32_e32 v36, 1.0, v39
	v_rcp_f32_e32 v39, v36
	v_add_f32_e32 v36, 1.0, v43
	v_rcp_f32_e32 v36, v36
	v_mul_f32_e32 v42, v33, v30
	v_fmac_f32_e32 v44, v42, v42
	v_add_f32_e32 v44, v44, v37
	v_mul_f32_e32 v42, v36, v11
	v_fma_f32 v37, v39, v34, v42
	v_add_f32_e32 v0, v37, v0
	v_lshlrev_b32_e32 v37, 16, v12
	v_mul_f32_e32 v43, 0x3d372713, v37
	v_and_b32_e32 v12, 0xffff0000, v12
	v_mul_f32_e32 v43, v43, v37
	v_mul_f32_e32 v46, 0x3d372713, v12
	v_fma_f32 v43, v43, v37, v37
	v_mul_f32_e32 v46, v46, v12
	v_mul_f32_e32 v43, 0x3f4c422a, v43
	v_fma_f32 v46, v46, v12, v12
	v_mul_f32_e32 v43, 0xc038aa3b, v43
	v_mul_f32_e32 v46, 0x3f4c422a, v46
	v_exp_f32_e32 v43, v43
	v_mul_f32_e32 v46, 0xc038aa3b, v46
	v_exp_f32_e32 v46, v46
	v_mul_f32_e32 v47, v42, v42
	v_add_f32_e32 v42, 1.0, v43
	v_rcp_f32_e32 v43, v42
	v_add_f32_e32 v42, 1.0, v46
	v_rcp_f32_e32 v42, v42
	v_mul_f32_e32 v45, v39, v34
	v_fmac_f32_e32 v47, v45, v45
	v_add_f32_e32 v47, v47, v44
	v_mul_f32_e32 v45, v42, v12
	v_fma_f32 v44, v43, v37, v45
	v_add_f32_e32 v0, v44, v0
	v_lshlrev_b32_e32 v44, 16, v13
	v_mul_f32_e32 v46, 0x3d372713, v44
	v_and_b32_e32 v13, 0xffff0000, v13
	v_mul_f32_e32 v46, v46, v44
	v_mul_f32_e32 v49, 0x3d372713, v13
	v_fma_f32 v46, v46, v44, v44
	v_mul_f32_e32 v49, v49, v13
	v_mul_f32_e32 v46, 0x3f4c422a, v46
	v_fma_f32 v49, v49, v13, v13
	v_mul_f32_e32 v46, 0xc038aa3b, v46
	v_mul_f32_e32 v49, 0x3f4c422a, v49
	v_exp_f32_e32 v46, v46
	v_mul_f32_e32 v49, 0xc038aa3b, v49
	v_exp_f32_e32 v49, v49
	v_mul_f32_e32 v50, v45, v45
	v_add_f32_e32 v45, 1.0, v46
	v_rcp_f32_e32 v46, v45
	v_add_f32_e32 v45, 1.0, v49
	v_rcp_f32_e32 v45, v45
	v_mul_f32_e32 v48, v43, v37
	v_fmac_f32_e32 v50, v48, v48
	v_add_f32_e32 v50, v50, v47
	v_mul_f32_e32 v48, v45, v13
	v_fma_f32 v47, v46, v44, v48
	v_add_f32_e32 v0, v47, v0
	v_lshlrev_b32_e32 v47, 16, v6
	v_mul_f32_e32 v49, 0x3d372713, v47
	v_and_b32_e32 v6, 0xffff0000, v6
	v_mul_f32_e32 v49, v49, v47
	v_mul_f32_e32 v52, 0x3d372713, v6
	v_fma_f32 v49, v49, v47, v47
	v_mul_f32_e32 v52, v52, v6
	v_mul_f32_e32 v49, 0x3f4c422a, v49
	v_fma_f32 v52, v52, v6, v6
	v_mul_f32_e32 v49, 0xc038aa3b, v49
	v_mul_f32_e32 v52, 0x3f4c422a, v52
	v_exp_f32_e32 v49, v49
	v_mul_f32_e32 v52, 0xc038aa3b, v52
	v_exp_f32_e32 v52, v52
	v_mul_f32_e32 v53, v48, v48
	v_add_f32_e32 v48, 1.0, v49
	v_rcp_f32_e32 v49, v48
	v_add_f32_e32 v48, 1.0, v52
	v_rcp_f32_e32 v48, v48
	v_mul_f32_e32 v51, v46, v44
	v_fmac_f32_e32 v53, v51, v51
	v_add_f32_e32 v53, v53, v50
	v_mul_f32_e32 v51, v48, v6
	v_fma_f32 v50, v49, v47, v51
	v_add_f32_e32 v0, v50, v0
	v_lshlrev_b32_e32 v50, 16, v7
	v_mul_f32_e32 v52, 0x3d372713, v50
	v_and_b32_e32 v7, 0xffff0000, v7
	v_mul_f32_e32 v52, v52, v50
	v_mul_f32_e32 v55, 0x3d372713, v7
	v_fma_f32 v52, v52, v50, v50
	v_mul_f32_e32 v55, v55, v7
	v_mul_f32_e32 v52, 0x3f4c422a, v52
	v_fma_f32 v55, v55, v7, v7
	v_mul_f32_e32 v52, 0xc038aa3b, v52
	v_mul_f32_e32 v55, 0x3f4c422a, v55
	v_exp_f32_e32 v52, v52
	v_mul_f32_e32 v55, 0xc038aa3b, v55
	v_exp_f32_e32 v55, v55
	v_mul_f32_e32 v56, v51, v51
	v_add_f32_e32 v51, 1.0, v52
	v_rcp_f32_e32 v52, v51
	v_add_f32_e32 v51, 1.0, v55
	v_rcp_f32_e32 v51, v51
	v_mul_f32_e32 v54, v49, v47
	v_fmac_f32_e32 v56, v54, v54
	v_add_f32_e32 v56, v56, v53
	v_mul_f32_e32 v54, v51, v7
	v_fma_f32 v53, v52, v50, v54
	v_add_f32_e32 v0, v53, v0
	v_lshlrev_b32_e32 v53, 16, v8
	v_mul_f32_e32 v55, 0x3d372713, v53
	v_and_b32_e32 v8, 0xffff0000, v8
	v_mul_f32_e32 v55, v55, v53
	v_mul_f32_e32 v58, 0x3d372713, v8
	v_fma_f32 v55, v55, v53, v53
	v_mul_f32_e32 v58, v58, v8
	v_mul_f32_e32 v55, 0x3f4c422a, v55
	v_fma_f32 v58, v58, v8, v8
	v_mul_f32_e32 v55, 0xc038aa3b, v55
	v_mul_f32_e32 v58, 0x3f4c422a, v58
	v_exp_f32_e32 v55, v55
	v_mul_f32_e32 v58, 0xc038aa3b, v58
	v_exp_f32_e32 v58, v58
	v_mul_f32_e32 v59, v54, v54
	v_add_f32_e32 v54, 1.0, v55
	v_rcp_f32_e32 v55, v54
	v_add_f32_e32 v54, 1.0, v58
	v_rcp_f32_e32 v54, v54
	v_mul_f32_e32 v57, v52, v50
	v_fmac_f32_e32 v59, v57, v57
	v_add_f32_e32 v57, v59, v56
	v_mul_f32_e32 v59, v54, v8
	v_fma_f32 v56, v55, v53, v59
	v_add_f32_e32 v0, v56, v0
	v_lshlrev_b32_e32 v56, 16, v9
	v_mul_f32_e32 v60, 0x3d372713, v56
	v_and_b32_e32 v9, 0xffff0000, v9
	v_mul_f32_e32 v60, v60, v56
	v_mul_f32_e32 v61, 0x3d372713, v9
	v_fma_f32 v60, v60, v56, v56
	v_mul_f32_e32 v61, v61, v9
	v_mul_f32_e32 v60, 0x3f4c422a, v60
	v_fma_f32 v61, v61, v9, v9
	v_mul_f32_e32 v60, 0xc038aa3b, v60
	v_mul_f32_e32 v61, 0x3f4c422a, v61
; __device__ __forceinline__ float gelu_tanh(float x) { const float z = 0.7978845608028654f * (x + 0.044715f * x * x * x); return x * frcp(1.f + fexp2(-2.f * LOG2E * z)); }
; __device__ __forceinline__ void sgu_unit(LAS unsigned char* lds, const bfu* PROJ, const bfu* SW  , const float* ln_g, const float* ln_b, const float* sb, bfu* CAT, int s) {
;     ...
;         for (int j = 0; j < 4; ++j) { const float x0 = gelu_tanh(bflo(w[j])), x1 = gelu_tanh(bfhi(w[j])); v[8 * k + 2 * j] = x0; v[8 * k + 2 * j + 1] = x1; a += x0 + x1; a2 += x0 * x0 + x1 * x1; } }
;     red[qd * 128 + sr] = a; red[512 + qd * 128 + sr] = a2;
;     __syncthreads();
;     { const float sm = (red[sr] + red[128 + sr]) + (red[256 + sr] + red[384 + sr]), sq = (red[512 + sr] + red[640 + sr]) + (red[768 + sr] + red[896 + sr]);
;       const float mu = sm * (1.f / 128.f), var = fmaxf(sq * (1.f / 128.f) - mu * mu, 0.f), rstd = 1.f / sqrtf(var + EPS);
	v_exp_f32_e32 v60, v60
	v_mul_f32_e32 v61, 0xc038aa3b, v61
	v_exp_f32_e32 v61, v61
	v_mul_f32_e32 v58, v55, v53
	v_add_f32_e32 v60, 1.0, v60
	v_rcp_f32_e32 v69, v60
	v_add_f32_e32 v60, 1.0, v61
	v_rcp_f32_e32 v102, v60
	v_mul_f32_e32 v59, v59, v59
	v_fmac_f32_e32 v59, v58, v58
	v_add_f32_e32 v57, v59, v57
	v_mul_f32_e32 v59, v102, v9
	v_and_b32_e32 v104, 0xffff0000, v2
	v_fma_f32 v60, v69, v56, v59
	v_lshlrev_b32_e32 v103, 16, v2
	v_mul_f32_e32 v2, 0x3d372713, v104
	v_add_f32_e32 v0, v60, v0
	v_mul_f32_e32 v60, 0x3d372713, v103
	v_mul_f32_e32 v2, v2, v104
	v_mul_f32_e32 v60, v60, v103
	v_fma_f32 v2, v2, v104, v104
	v_fma_f32 v60, v60, v103, v103
	v_mul_f32_e32 v2, 0x3f4c422a, v2
	v_mul_f32_e32 v60, 0x3f4c422a, v60
	v_mul_f32_e32 v2, 0xc038aa3b, v2
	v_mul_f32_e32 v60, 0xc038aa3b, v60
	v_exp_f32_e32 v2, v2
	v_exp_f32_e32 v60, v60
	v_mul_f32_e32 v58, v69, v56
	v_mul_f32_e32 v59, v59, v59
	v_add_f32_e32 v2, 1.0, v2
	v_add_f32_e32 v60, 1.0, v60
	v_rcp_f32_e32 v106, v2
	v_rcp_f32_e32 v105, v60
	v_fmac_f32_e32 v59, v58, v58
	v_and_b32_e32 v108, 0xffff0000, v3
	v_mul_f32_e32 v58, v106, v104
	v_add_f32_e32 v2, v59, v57
	v_fma_f32 v59, v105, v103, v58
	v_lshlrev_b32_e32 v107, 16, v3
	v_mul_f32_e32 v3, 0x3d372713, v108
	v_add_f32_e32 v0, v59, v0
	v_mul_f32_e32 v59, 0x3d372713, v107
	v_mul_f32_e32 v3, v3, v108
	v_mul_f32_e32 v59, v59, v107
	v_fma_f32 v3, v3, v108, v108
	v_fma_f32 v59, v59, v107, v107
	v_mul_f32_e32 v3, 0x3f4c422a, v3
	v_mul_f32_e32 v59, 0x3f4c422a, v59
	v_mul_f32_e32 v3, 0xc038aa3b, v3
	v_mul_f32_e32 v59, 0xc038aa3b, v59
	v_exp_f32_e32 v3, v3
	v_exp_f32_e32 v59, v59
	v_mul_f32_e32 v57, v105, v103
	v_mul_f32_e32 v58, v58, v58
	v_add_f32_e32 v3, 1.0, v3
	v_add_f32_e32 v59, 1.0, v59
	v_rcp_f32_e32 v110, v3
	v_rcp_f32_e32 v109, v59
	v_fmac_f32_e32 v58, v57, v57
	v_and_b32_e32 v112, 0xffff0000, v4
	v_mul_f32_e32 v57, v110, v108
	v_add_f32_e32 v2, v58, v2
	v_fma_f32 v58, v109, v107, v57
	v_lshlrev_b32_e32 v111, 16, v4
	v_mul_f32_e32 v4, 0x3d372713, v112
	v_add_f32_e32 v0, v58, v0
	v_mul_f32_e32 v58, 0x3d372713, v111
	v_mul_f32_e32 v4, v4, v112
	v_mul_f32_e32 v58, v58, v111
	v_fma_f32 v4, v4, v112, v112
	v_fma_f32 v58, v58, v111, v111
	v_mul_f32_e32 v4, 0x3f4c422a, v4
	v_mul_f32_e32 v58, 0x3f4c422a, v58
	v_mul_f32_e32 v4, 0xc038aa3b, v4
	v_mul_f32_e32 v58, 0xc038aa3b, v58
	v_exp_f32_e32 v4, v4
	v_exp_f32_e32 v58, v58
	v_mul_f32_e32 v3, v109, v107
	v_mul_f32_e32 v57, v57, v57
	v_add_f32_e32 v4, 1.0, v4
	v_add_f32_e32 v58, 1.0, v58
	v_rcp_f32_e32 v114, v4
	v_rcp_f32_e32 v113, v58
	v_fmac_f32_e32 v57, v3, v3
	v_add_f32_e32 v2, v57, v2
	v_mul_f32_e32 v4, v114, v112
	v_fma_f32 v57, v113, v111, v4
	v_and_b32_e32 v115, 0xffff0000, v5
	v_add_f32_e32 v0, v57, v0
	v_lshlrev_b32_e32 v57, 16, v5
	v_mul_f32_e32 v5, 0x3d372713, v115
	v_mul_f32_e32 v58, 0x3d372713, v57
	v_mul_f32_e32 v5, v5, v115
	v_mul_f32_e32 v58, v58, v57
	v_fma_f32 v5, v5, v115, v115
	v_fma_f32 v58, v58, v57, v57
	v_mul_f32_e32 v5, 0x3f4c422a, v5
	v_mul_f32_e32 v58, 0x3f4c422a, v58
	v_mul_f32_e32 v5, 0xc038aa3b, v5
	v_mul_f32_e32 v58, 0xc038aa3b, v58
	v_exp_f32_e32 v5, v5
	v_exp_f32_e32 v58, v58
	v_mul_f32_e32 v3, v113, v111
	v_mul_f32_e32 v4, v4, v4
	v_add_f32_e32 v5, 1.0, v5
	v_add_f32_e32 v58, 1.0, v58
	v_rcp_f32_e32 v117, v5
	v_rcp_f32_e32 v116, v58
	v_fmac_f32_e32 v4, v3, v3
	v_add_f32_e32 v2, v4, v2
	v_mul_f32_e32 v4, v117, v115
	v_mul_f32_e32 v3, v116, v57
	v_fma_f32 v5, v116, v57, v4
	v_mul_f32_e32 v4, v4, v4
	v_fmac_f32_e32 v4, v3, v3
	v_add_f32_e32 v0, v5, v0
	v_add_f32_e32 v2, v4, v2
	v_lshl_add_u32 v4, v16, 2, s70
	v_and_b32_e32 v3, 0x3fffff80, v16
	ds_write_b32 v4, v0
	v_lshl_add_u32 v0, v18, 2, s70
	v_lshl_add_u32 v3, v3, 2, v0
	ds_write_b32 v3, v2 offset:2048
	v_lshlrev_b64 v[2:3], 2, v[14:15]
	v_lshl_add_u64 v[4:5], s[22:23], 0, v[2:3]
	s_add_u32 s22, s35, s41
	s_addc_u32 s23, s40, 0
	v_lshl_add_u64 v[66:67], s[22:23], 0, v[2:3]
	s_waitcnt lgkmcnt(0)
	s_barrier
	global_load_dwordx4 v[58:61], v[66:67], off
	global_load_dwordx4 v[62:65], v[4:5], off
	global_load_dwordx4 v[70:73], v[4:5], off offset:16
	ds_read2st64_b32 v[2:3], v0 offset1:2
	ds_read2st64_b32 v[78:79], v0 offset0:4 offset1:6
	global_load_dwordx4 v[74:77], v[66:67], off offset:16
	ds_read2st64_b32 v[80:81], v0 offset0:8 offset1:10
	ds_read2st64_b32 v[82:83], v0 offset0:12 offset1:14
	s_brev_b32 s22, 60
	s_waitcnt lgkmcnt(3)
	v_add_f32_e32 v0, v2, v3
	s_waitcnt lgkmcnt(2)
	v_add_f32_e32 v2, v78, v79
	v_add_f32_e32 v0, v0, v2
	s_waitcnt lgkmcnt(1)
	v_add_f32_e32 v2, v80, v81
	s_waitcnt lgkmcnt(0)
	v_add_f32_e32 v3, v82, v83
	v_mul_f32_e32 v15, 0x3c000000, v0
	v_add_f32_e32 v2, v2, v3
	v_mul_f32_e32 v0, v15, v15
	v_fma_f32 v0, v2, s22, -v0
	v_max_f32_e32 v0, 0, v0
	v_add_f32_e32 v0, 0x358637bd, v0
	v_mul_f32_e32 v2, 0x4f800000, v0
	v_cmp_gt_f32_e32 vcc, s68, v0
	s_nop 1
	v_cndmask_b32_e32 v0, v0, v2, vcc
	v_sqrt_f32_e32 v2, v0
	s_nop 0
	v_add_u32_e32 v3, -1, v2
	v_fma_f32 v78, -v3, v2, v0
	v_cmp_ge_f32_e64 s[40:41], 0, v78
	global_load_dwordx4 v[78:81], v[4:5], off offset:32
	global_load_dwordx4 v[82:85], v[66:67], off offset:32
	v_add_u32_e32 v86, 1, v2
	v_cndmask_b32_e64 v3, v2, v3, s[40:41]
	v_fma_f32 v2, -v86, v2, v0
	v_cmp_lt_f32_e64 s[40:41], 0, v2
	s_nop 1
	v_cndmask_b32_e64 v2, v3, v86, s[40:41]
	v_mul_f32_e32 v3, 0x37800000, v2
	v_cndmask_b32_e32 v2, v2, v3, vcc
	v_cmp_class_f32_e32 vcc, v0, v234
	global_load_dwordx4 v[86:89], v[4:5], off offset:48
	global_load_dwordx4 v[90:93], v[66:67], off offset:48
	v_cndmask_b32_e32 v0, v2, v0, vcc
	v_div_scale_f32 v2, s[22:23], v0, v0, 1.0
	v_rcp_f32_e32 v3, v2
	v_readfirstlane_b32 s22, v16
	s_ashr_i32 s22, s22, 2
	v_fma_f32 v94, -v2, v3, 1.0
	v_fmac_f32_e32 v3, v94, v3
	v_div_scale_f32 v94, vcc, 1.0, v0, 1.0
	v_mul_f32_e32 v95, v94, v3
	v_fma_f32 v96, -v2, v95, v94
	v_fmac_f32_e32 v95, v96, v3
	v_fma_f32 v2, -v2, v95, v94
	v_div_fmas_f32 v2, v2, v3, v95
	v_div_fixup_f32 v118, v2, v0, 1.0
	v_fma_f32 v2, v41, v25, -v15
	v_mul_f32_e32 v2, v2, v118
	v_lshl_add_u32 v0, v18, 1, 0
	s_waitcnt vmcnt(6)
; __device__ __forceinline__ unsigned f2bf(float f) { unsigned u = __builtin_bit_cast(unsigned, f); return (u + 0x7fffu + ((u >> 16) & 1u)) >> 16; }
; __device__ __forceinline__ void sgu_unit(LAS unsigned char* lds, const bfu* PROJ, const bfu* SW  , const float* ln_g, const float* ln_b, const float* sb, bfu* CAT, int s) {
;     ...
;     { const float sm = (red[sr] + red[128 + sr]) + (red[256 + sr] + red[384 + sr]), sq = (red[512 + sr] + red[640 + sr]) + (red[768 + sr] + red[896 + sr]);
;       const float mu = sm * (1.f / 128.f), var = fmaxf(sq * (1.f / 128.f) - mu * mu, 0.f), rstd = 1.f / sqrtf(var + EPS);
;       const float* lg_ = ln_g + g * 128 + qd * 32; const float* lb_ = ln_b + g * 128 + qd * 32;
; #pragma unroll
;       for (int k = 0; k < 32; ++k) Vt[(qd * 32 + k) * TS + sr] = (bfu)f2bf((v[k] - mu) * rstd * lg_[k] + lb_[k]); }
;     __syncthreads();
	v_fma_f32 v2, v62, v2, v58
	v_bfe_u32 v3, v2, 16, 1
	v_add3_u32 v18, v2, v3, s71
	v_mad_u64_u32 v[2:3], s[40:41], v14, s65, v[0:1]
	v_fma_f32 v3, v40, v26, -v15
	v_mul_f32_e32 v3, v3, v118
	v_fma_f32 v3, v63, v3, v59
	v_bfe_u32 v14, v3, 16, 1
	v_add3_u32 v3, v3, v14, s71
	ds_write_b16_d16_hi v2, v3 offset:35088
	v_fma_f32 v3, v38, v28, -v15
	v_mul_f32_e32 v3, v3, v118
	v_fma_f32 v3, v64, v3, v60
	v_bfe_u32 v14, v3, 16, 1
	v_add3_u32 v3, v3, v14, s71
	ds_write_b16_d16_hi v2, v3 offset:35360
	v_fma_f32 v3, v35, v31, -v15
	v_mul_f32_e32 v3, v3, v118
	v_fmac_f32_e32 v61, v3, v65
	ds_write_b16_d16_hi v2, v18 offset:34816
	v_bfe_u32 v3, v61, 16, 1
	v_add3_u32 v3, v61, v3, s71
	global_load_dwordx4 v[58:61], v[4:5], off offset:80
	global_load_dwordx4 v[62:65], v[4:5], off offset:64
	global_load_dwordx4 v[94:97], v[66:67], off offset:80
	global_load_dwordx4 v[98:101], v[66:67], off offset:64
	ds_write_b16_d16_hi v2, v3 offset:35632
	v_fma_f32 v3, v22, v19, -v15
	v_mul_f32_e32 v3, v3, v118
	s_waitcnt vmcnt(8)
	v_fma_f32 v3, v3, v70, v74
	v_bfe_u32 v14, v3, 16, 1
	v_add3_u32 v3, v3, v14, s71
	ds_write_b16_d16_hi v2, v3 offset:35904
	v_fma_f32 v3, v21, v20, -v15
	v_mul_f32_e32 v3, v3, v118
	v_fma_f32 v3, v3, v71, v75
	v_bfe_u32 v14, v3, 16, 1
	v_add3_u32 v3, v3, v14, s71
	ds_write_b16_d16_hi v2, v3 offset:36176
	v_fma_f32 v3, v29, v23, -v15
	v_mul_f32_e32 v3, v3, v118
	v_fma_f32 v3, v3, v72, v76
	v_bfe_u32 v14, v3, 16, 1
	v_add3_u32 v3, v3, v14, s71
	ds_write_b16_d16_hi v2, v3 offset:36448
	v_fma_f32 v3, v27, v24, -v15
	v_mul_f32_e32 v3, v3, v118
	v_fmac_f32_e32 v77, v3, v73
	v_bfe_u32 v3, v77, 16, 1
	v_add3_u32 v3, v77, v3, s71
	ds_write_b16_d16_hi v2, v3 offset:36720
	v_fma_f32 v3, v33, v30, -v15
	v_mul_f32_e32 v3, v3, v118
	s_waitcnt vmcnt(6)
	v_fma_f32 v3, v3, v78, v82
	v_bfe_u32 v14, v3, 16, 1
	v_add3_u32 v3, v3, v14, s71
	ds_write_b16_d16_hi v2, v3 offset:36992
	v_fma_f32 v3, v32, v10, -v15
	v_mul_f32_e32 v3, v3, v118
	v_fma_f32 v3, v3, v79, v83
	v_bfe_u32 v10, v3, 16, 1
	v_add3_u32 v3, v3, v10, s71
	ds_write_b16_d16_hi v2, v3 offset:37264
	v_fma_f32 v3, v39, v34, -v15
	v_mul_f32_e32 v3, v3, v118
	v_fma_f32 v3, v3, v80, v84
	v_bfe_u32 v10, v3, 16, 1
	v_add3_u32 v3, v3, v10, s71
	ds_write_b16_d16_hi v2, v3 offset:37536
	global_load_dwordx4 v[18:21], v[4:5], off offset:112
	global_load_dwordx4 v[22:25], v[4:5], off offset:96
	global_load_dwordx4 v[26:29], v[66:67], off offset:112
	global_load_dwordx4 v[30:33], v[66:67], off offset:96
	v_fma_f32 v3, v36, v11, -v15
	v_mul_f32_e32 v3, v3, v118
	v_fmac_f32_e32 v85, v3, v81
	v_bfe_u32 v3, v85, 16, 1
	v_add3_u32 v3, v85, v3, s71
	ds_write_b16_d16_hi v2, v3 offset:37808
	v_fma_f32 v3, v43, v37, -v15
	v_mul_f32_e32 v3, v3, v118
	s_waitcnt vmcnt(8)
	v_fma_f32 v3, v3, v86, v90
	v_bfe_u32 v4, v3, 16, 1
	v_add3_u32 v3, v3, v4, s71
	ds_write_b16_d16_hi v2, v3 offset:38080
	v_fma_f32 v3, v42, v12, -v15
	v_mul_f32_e32 v3, v3, v118
	v_fma_f32 v3, v3, v87, v91
	v_bfe_u32 v4, v3, 16, 1
	v_add3_u32 v3, v3, v4, s71
	ds_write_b16_d16_hi v2, v3 offset:38352
	v_fma_f32 v3, v46, v44, -v15
	v_mul_f32_e32 v3, v3, v118
	v_fma_f32 v3, v3, v88, v92
	v_bfe_u32 v4, v3, 16, 1
	v_add3_u32 v3, v3, v4, s71
	ds_write_b16_d16_hi v2, v3 offset:38624
	v_fma_f32 v3, v45, v13, -v15
	v_mul_f32_e32 v3, v3, v118
	v_fmac_f32_e32 v93, v3, v89
	v_bfe_u32 v3, v93, 16, 1
	v_add3_u32 v3, v93, v3, s71
	ds_write_b16_d16_hi v2, v3 offset:38896
	v_fma_f32 v3, v49, v47, -v15
	v_mul_f32_e32 v3, v3, v118
	v_bfi_b32 v14, -16, s22, v16
	s_waitcnt vmcnt(4)
	v_fma_f32 v3, v3, v62, v98
	v_bfe_u32 v4, v3, 16, 1
	v_add3_u32 v3, v3, v4, s71
	ds_write_b16_d16_hi v2, v3 offset:39168
	v_fma_f32 v3, v48, v6, -v15
	v_mul_f32_e32 v3, v3, v118
	v_fma_f32 v3, v3, v63, v99
	v_bfe_u32 v4, v3, 16, 1
	v_add3_u32 v3, v3, v4, s71
	ds_write_b16_d16_hi v2, v3 offset:39440
	v_fma_f32 v3, v52, v50, -v15
	v_mul_f32_e32 v3, v3, v118
	v_fma_f32 v3, v3, v64, v100
	v_bfe_u32 v4, v3, 16, 1
	v_add3_u32 v3, v3, v4, s71
	ds_write_b16_d16_hi v2, v3 offset:39712
	v_fma_f32 v3, v51, v7, -v15
	v_mul_f32_e32 v3, v3, v118
	v_fmac_f32_e32 v101, v3, v65
	v_bfe_u32 v3, v101, 16, 1
	v_add3_u32 v3, v101, v3, s71
	ds_write_b16_d16_hi v2, v3 offset:39984
	v_fma_f32 v3, v55, v53, -v15
	v_mul_f32_e32 v3, v3, v118
	v_fma_f32 v3, v3, v58, v94
	v_bfe_u32 v4, v3, 16, 1
	v_add3_u32 v3, v3, v4, s71
	ds_write_b16_d16_hi v2, v3 offset:40256
	v_fma_f32 v3, v54, v8, -v15
	v_mul_f32_e32 v3, v3, v118
	v_fma_f32 v3, v3, v59, v95
	v_bfe_u32 v4, v3, 16, 1
	v_add3_u32 v3, v3, v4, s71
	ds_write_b16_d16_hi v2, v3 offset:40528
	v_fma_f32 v3, v69, v56, -v15
	v_mul_f32_e32 v3, v3, v118
	v_fma_f32 v3, v3, v60, v96
	v_bfe_u32 v4, v3, 16, 1
	v_add3_u32 v3, v3, v4, s71
	ds_write_b16_d16_hi v2, v3 offset:40800
	v_fma_f32 v3, v102, v9, -v15
	v_mul_f32_e32 v3, v3, v118
	v_fmac_f32_e32 v97, v3, v61
	v_bfe_u32 v3, v97, 16, 1
	v_add3_u32 v3, v97, v3, s71
	ds_write_b16_d16_hi v2, v3 offset:41072
	v_fma_f32 v3, v105, v103, -v15
	v_mul_f32_e32 v3, v3, v118
	s_waitcnt vmcnt(0)
	v_fma_f32 v3, v3, v22, v30
	v_bfe_u32 v4, v3, 16, 1
	v_add3_u32 v3, v3, v4, s71
	ds_write_b16_d16_hi v2, v3 offset:41344
	v_fma_f32 v3, v106, v104, -v15
	v_mul_f32_e32 v3, v3, v118
	v_fma_f32 v3, v3, v23, v31
	v_bfe_u32 v4, v3, 16, 1
	v_add3_u32 v3, v3, v4, s71
	ds_write_b16_d16_hi v2, v3 offset:41616
	v_fma_f32 v3, v109, v107, -v15
	v_mul_f32_e32 v3, v3, v118
	v_fma_f32 v3, v3, v24, v32
	v_bfe_u32 v4, v3, 16, 1
	v_add3_u32 v3, v3, v4, s71
	ds_write_b16_d16_hi v2, v3 offset:41888
	v_fma_f32 v3, v110, v108, -v15
	v_mul_f32_e32 v3, v3, v118
	v_fmac_f32_e32 v33, v3, v25
	v_bfe_u32 v3, v33, 16, 1
	v_add3_u32 v3, v33, v3, s71
	ds_write_b16_d16_hi v2, v3 offset:42160
	v_fma_f32 v3, v113, v111, -v15
	v_mul_f32_e32 v3, v3, v118
	v_fma_f32 v3, v3, v18, v26
	v_bfe_u32 v4, v3, 16, 1
	v_add3_u32 v3, v3, v4, s71
	ds_write_b16_d16_hi v2, v3 offset:42432
	v_fma_f32 v3, v114, v112, -v15
	v_mul_f32_e32 v3, v3, v118
	v_fma_f32 v3, v3, v19, v27
	v_bfe_u32 v4, v3, 16, 1
	v_add3_u32 v3, v3, v4, s71
	ds_write_b16_d16_hi v2, v3 offset:42704
	v_fma_f32 v3, v116, v57, -v15
	v_mul_f32_e32 v3, v3, v118
	v_fma_f32 v3, v3, v20, v28
	v_bfe_u32 v4, v3, 16, 1
	v_add3_u32 v3, v3, v4, s71
	ds_write_b16_d16_hi v2, v3 offset:42976
	v_fma_f32 v2, v117, v115, -v15
	v_mul_f32_e32 v2, v2, v118
	v_fmac_f32_e32 v29, v2, v21
	v_bfe_u32 v2, v29, 16, 1
	v_add3_u32 v4, v29, v2, s71
	v_or_b32_e32 v2, 31, v17
	v_mad_u64_u32 v[2:3], s[40:41], v2, s65, v[0:1]
	v_ashrrev_i32_e32 v15, 31, v14
	ds_write_b16_d16_hi v2, v4 offset:34816
	v_lshl_add_u64 v[32:33], v[14:15], 0, s[52:53]
	v_mov_b64_e32 v[2:3], s[44:45]
	v_bfe_u32 v4, v16, 4, 2
	v_mad_i64_i32 v[2:3], s[22:23], v32, s61, v[2:3]
	v_lshlrev_b32_e32 v0, 3, v4
	v_lshl_add_u64 v[2:3], v[2:3], 0, s[20:21]
	v_lshl_add_u64 v[34:35], v[2:3], 0, v[0:1]
	v_add_co_u32_e32 v2, vcc, s56, v34
	s_waitcnt lgkmcnt(0)
	s_nop 0
	v_addc_co_u32_e32 v3, vcc, 0, v35, vcc
	s_barrier
; __device__ __forceinline__ unsigned pk2(float lo, float hi) { return pg8::cvt_pk_bf16(lo, hi); }
; __device__ __forceinline__ float gelu_tanh(float x) { const float z = 0.7978845608028654f * (x + 0.044715f * x * x * x); return x * frcp(1.f + fexp2(-2.f * LOG2E * z)); }
; #define ZERO8(a) do { _Pragma("unroll") for (int t_ = 0; t_ < 8; ++t_) a[t_] = (f32x4){0.f, 0.f, 0.f, 0.f}; } while (0)
; __device__ __forceinline__ void sgu_unit(LAS unsigned char* lds, const bfu* PROJ, const bfu* SW  , const float* ln_g, const float* ln_b, const float* sb, bfu* CAT, int s) {
;     ...
;     const int fr = lane & 15, fq = lane >> 4, m0 = wid * 16, t_ = m0 + fr; f32x4 acc[8]; ZERO8(acc);
;     wave_mma(acc, Ws, Vt, m0, fr, fq);
;     const float bias = sb[g * 128 + t_];
;     const bfu* up = PROJ + (row0 + t_) * INW + C_SU + g * 128 + 4 * fq; bfu* op = CAT + (row0 + t_) * DM + 1536 + g * 128 + 4 * fq;
; #pragma unroll
;     for (int t = 0; t < 8; ++t) { const v2u uw = *(const v2u*)(up + 16 * t);
;         v2u w; w.x = pk2(gelu_tanh(bflo(uw.x)) * (acc[t][0] + bias), gelu_tanh(bfhi(uw.x)) * (acc[t][1] + bias)); w.y = pk2(gelu_tanh(bflo(uw.y)) * (acc[t][2] + bias), gelu_tanh(bfhi(uw.y)) * (acc[t][3] + bias));
;         *(v2u*)(op + 16 * t) = w; }
	global_load_dwordx2 v[170:171], v[2:3], off offset:2560 nt
	s_waitcnt lgkmcnt(0)
	v_and_b32_e32 v2, 15, v16
	v_lshl_add_u32 v6, v4, 4, 0
	v_mad_u32_u24 v19, v2, s65, v6
	ds_read_b128 v[44:47], v19 offset:34816
	ds_read_b128 v[48:51], v19 offset:34880
	v_mad_u64_u32 v[38:39], s[22:23], v14, s65, v[6:7]
	ds_read_b128 v[52:55], v38
	ds_read_b128 v[56:59], v38 offset:64
	ds_read_b128 v[60:63], v19 offset:34944
	ds_read_b128 v[64:67], v38 offset:128
	ds_read_b128 v[72:75], v19 offset:35008
	ds_read_b128 v[76:79], v38 offset:192
	ds_read_b128 v[80:83], v19 offset:39168
	ds_read_b128 v[84:87], v19 offset:39232
	ds_read_b128 v[88:91], v19 offset:39296
	ds_read_b128 v[92:95], v19 offset:39360
	ds_read_b128 v[96:99], v19 offset:43520
	s_waitcnt lgkmcnt(10)
	v_mfma_f32_16x16x32_bf16 v[2:5], v[44:47], v[52:55], 0
	v_lshl_add_u32 v28, s34, 7, v14
	v_ashrrev_i32_e32 v29, 31, v28
	v_lshl_add_u64 v[40:41], v[28:29], 2, s[50:51]
	ds_read_b128 v[44:47], v19 offset:43584
	s_waitcnt lgkmcnt(10)
	v_mfma_f32_16x16x32_bf16 v[20:23], v[48:51], v[56:59], v[2:5]
	s_nop 1
	global_load_dword v18, v[40:41], off
	s_mov_b64 s[22:23], 0x2a00
	ds_read_b128 v[48:51], v19 offset:43648
	ds_read_b128 v[100:103], v19 offset:43712
	s_waitcnt lgkmcnt(10)
	v_mfma_f32_16x16x32_bf16 v[20:23], v[60:63], v[64:67], v[20:23]
	v_lshlrev_b64 v[26:27], 12, v[32:33]
	v_lshl_add_u64 v[26:27], s[46:47], 0, v[26:27]
	v_lshl_add_u64 v[26:27], v[26:27], 0, s[20:21]
	ds_read_b128 v[60:63], v19 offset:47872
	s_waitcnt lgkmcnt(9)
	v_mfma_f32_16x16x32_bf16 v[22:25], v[72:75], v[76:79], v[20:23]
	ds_read_b128 v[72:75], v19 offset:47936
	s_mov_b32 s20, 0x29600000
	s_waitcnt vmcnt(1)
	v_lshlrev_b32_e32 v28, 16, v170
	v_mul_f32_e32 v30, 0x3d372713, v28
	v_mul_f32_e32 v30, v30, v28
	v_mov_b32_e32 v31, v28
	v_and_b32_e32 v29, 0xffff0000, v170
	v_fmac_f32_e32 v31, v30, v31
	v_mul_f32_e32 v30, 0x3f4c422a, v31
	v_mul_f32_e32 v31, 0x3d372713, v29
	v_mul_f32_e32 v31, v31, v29
	v_mov_b32_e32 v32, v29
	v_fmac_f32_e32 v32, v31, v32
	v_mul_f32_e32 v30, 0xc038aa3b, v30
	v_mul_f32_e32 v31, 0x3f4c422a, v32
	v_exp_f32_e32 v30, v30
	v_mul_f32_e32 v31, 0xc038aa3b, v31
	v_exp_f32_e32 v31, v31
	v_lshl_add_u64 v[20:21], v[34:35], 0, s[22:23]
	global_load_dwordx2 v[172:173], v[20:21], off offset:32 nt
	global_load_dwordx2 v[174:175], v[20:21], off offset:64 nt
	global_load_dwordx2 v[176:177], v[20:21], off offset:96 nt
	global_load_dwordx2 v[178:179], v[20:21], off offset:128 nt
	global_load_dwordx2 v[180:181], v[20:21], off offset:160 nt
	global_load_dwordx2 v[182:183], v[20:21], off offset:192 nt
	global_load_dwordx2 v[184:185], v[20:21], off offset:224 nt
	v_lshl_add_u64 v[34:35], v[26:27], 0, v[0:1]
	v_add_f32_e32 v0, 1.0, v30
	v_rcp_f32_e32 v26, v0
	v_add_f32_e32 v0, 1.0, v31
	v_lshlrev_b32_e32 v36, 16, v171
	v_rcp_f32_e32 v27, v0
	v_mul_f32_e32 v0, 0x3d372713, v36
	v_mul_f32_e32 v0, v0, v36
	v_mov_b32_e32 v30, v36
	v_and_b32_e32 v37, 0xffff0000, v171
	v_fmac_f32_e32 v30, v0, v30
	v_mul_f32_e32 v0, 0x3f4c422a, v30
	v_mul_f32_e32 v30, 0x3d372713, v37
	v_mul_f32_e32 v30, v30, v37
	v_mov_b32_e32 v31, v37
	v_fmac_f32_e32 v31, v30, v31
	v_mul_f32_e32 v0, 0xc038aa3b, v0
	v_mul_f32_e32 v30, 0x3f4c422a, v31
	v_exp_f32_e32 v0, v0
	v_mul_f32_e32 v30, 0xc038aa3b, v30
	v_exp_f32_e32 v30, v30
	v_pk_mul_f32 v[38:39], v[26:27], v[28:29]
	v_add_f32_e32 v0, 1.0, v0
	v_rcp_f32_e32 v40, v0
	v_add_f32_e32 v0, 1.0, v30
	v_rcp_f32_e32 v41, v0
	s_waitcnt vmcnt(0)
	v_pk_add_f32 v[22:23], v[22:23], v[18:19] op_sel_hi:[1,0]
	s_mov_b64 s[22:23], 0x29600c00
	v_pk_mul_f32 v[22:23], v[22:23], v[38:39]
	v_pk_mul_f32 v[36:37], v[40:41], v[36:37]
	v_cvt_pk_bf16_f32 v38, v22, v23
	v_pk_add_f32 v[40:41], v[24:25], v[18:19] op_sel_hi:[1,0]
	s_waitcnt lgkmcnt(9)
	v_mfma_f32_16x16x32_bf16 v[22:25], v[80:83], v[52:55], 0
	ds_read_b128 v[80:83], v19 offset:48000
	v_pk_mul_f32 v[36:37], v[40:41], v[36:37]
	s_waitcnt lgkmcnt(9)
	v_mfma_f32_16x16x32_bf16 v[22:25], v[84:87], v[56:59], v[22:25]
	ds_read_b128 v[84:87], v19 offset:48064
	v_add_co_u32_e32 v30, vcc, s20, v34
	v_cvt_pk_bf16_f32 v39, v36, v37
	s_nop 0
	v_addc_co_u32_e32 v31, vcc, 0, v35, vcc
	global_store_dwordx2 v[30:31], v[38:39], off offset:3072
	s_waitcnt lgkmcnt(9)
	v_mfma_f32_16x16x32_bf16 v[22:25], v[88:91], v[64:67], v[22:25]
	ds_read_b128 v[88:91], v19 offset:52224
	s_waitcnt lgkmcnt(9)
	v_mfma_f32_16x16x32_bf16 v[24:27], v[92:95], v[76:79], v[22:25]
	ds_read_b128 v[92:95], v19 offset:52288
	s_waitcnt vmcnt(0)
	v_lshlrev_b32_e32 v30, 16, v172
	v_mul_f32_e32 v0, 0x3d372713, v30
	v_mul_f32_e32 v0, v0, v30
	s_nop 0
	v_mov_b32_e32 v22, v30
	v_and_b32_e32 v31, 0xffff0000, v172
	v_fmac_f32_e32 v22, v0, v22
	v_mul_f32_e32 v0, 0x3f4c422a, v22
	v_mul_f32_e32 v22, 0x3d372713, v31
	v_mul_f32_e32 v22, v22, v31
	v_mov_b32_e32 v23, v31
	v_fmac_f32_e32 v23, v22, v23
	v_mul_f32_e32 v0, 0xc038aa3b, v0
	v_mul_f32_e32 v22, 0x3f4c422a, v23
	v_exp_f32_e32 v0, v0
	v_mul_f32_e32 v22, 0xc038aa3b, v22
	v_exp_f32_e32 v28, v22
	v_lshl_add_u64 v[22:23], v[34:35], 0, s[22:23]
	v_add_f32_e32 v0, 1.0, v0
	v_rcp_f32_e32 v32, v0
	v_add_f32_e32 v0, 1.0, v28
	v_lshlrev_b32_e32 v34, 16, v173
	v_rcp_f32_e32 v33, v0
	v_mul_f32_e32 v0, 0x3d372713, v34
	v_mul_f32_e32 v0, v0, v34
	v_mov_b32_e32 v28, v34
	v_and_b32_e32 v35, 0xffff0000, v173
	v_fmac_f32_e32 v28, v0, v28
	v_mul_f32_e32 v0, 0x3f4c422a, v28
	v_mul_f32_e32 v28, 0x3d372713, v35
	v_mul_f32_e32 v28, v28, v35
	v_mov_b32_e32 v29, v35
	v_fmac_f32_e32 v29, v28, v29
	v_mul_f32_e32 v0, 0xc038aa3b, v0
	v_mul_f32_e32 v28, 0x3f4c422a, v29
	v_exp_f32_e32 v0, v0
	v_mul_f32_e32 v28, 0xc038aa3b, v28
	v_exp_f32_e32 v28, v28
	v_pk_mul_f32 v[32:33], v[32:33], v[30:31]
	v_add_f32_e32 v0, 1.0, v0
	v_rcp_f32_e32 v36, v0
	v_add_f32_e32 v0, 1.0, v28
	v_rcp_f32_e32 v37, v0
	v_pk_add_f32 v[24:25], v[24:25], v[18:19] op_sel_hi:[1,0]
	v_pk_add_f32 v[26:27], v[26:27], v[18:19] op_sel_hi:[1,0]
	v_pk_mul_f32 v[24:25], v[24:25], v[32:33]
	v_pk_mul_f32 v[32:33], v[36:37], v[34:35]
	v_cvt_pk_bf16_f32 v24, v24, v25
	v_pk_mul_f32 v[26:27], v[26:27], v[32:33]
	v_cvt_pk_bf16_f32 v25, v26, v27
	global_store_dwordx2 v[22:23], v[24:25], off offset:32
	s_waitcnt lgkmcnt(9)
; __device__ __forceinline__ unsigned pk2(float lo, float hi) { return pg8::cvt_pk_bf16(lo, hi); }
; __device__ __forceinline__ float gelu_tanh(float x) { const float z = 0.7978845608028654f * (x + 0.044715f * x * x * x); return x * frcp(1.f + fexp2(-2.f * LOG2E * z)); }
; __device__ __forceinline__ void sgu_unit(LAS unsigned char* lds, const bfu* PROJ, const bfu* SW  , const float* ln_g, const float* ln_b, const float* sb, bfu* CAT, int s) {
;     ...
;     wave_mma(acc, Ws, Vt, m0, fr, fq);
;     const float bias = sb[g * 128 + t_];
;     const bfu* up = PROJ + (row0 + t_) * INW + C_SU + g * 128 + 4 * fq; bfu* op = CAT + (row0 + t_) * DM + 1536 + g * 128 + 4 * fq;
; #pragma unroll
;     for (int t = 0; t < 8; ++t) { const v2u uw = *(const v2u*)(up + 16 * t);
;         v2u w; w.x = pk2(gelu_tanh(bflo(uw.x)) * (acc[t][0] + bias), gelu_tanh(bfhi(uw.x)) * (acc[t][1] + bias)); w.y = pk2(gelu_tanh(bflo(uw.y)) * (acc[t][2] + bias), gelu_tanh(bfhi(uw.y)) * (acc[t][3] + bias));
;         *(v2u*)(op + 16 * t) = w; }
	v_mfma_f32_16x16x32_bf16 v[28:31], v[96:99], v[52:55], 0
	ds_read_b128 v[96:99], v19 offset:52352
	s_waitcnt lgkmcnt(9)
	v_mfma_f32_16x16x32_bf16 v[24:27], v[44:47], v[56:59], v[28:31]
	ds_read_b128 v[44:47], v19 offset:52416
	s_nop 5
	s_waitcnt lgkmcnt(9)
	v_mfma_f32_16x16x32_bf16 v[24:27], v[48:51], v[64:67], v[24:27]
	ds_read_b128 v[48:51], v19 offset:56576
	s_waitcnt vmcnt(0)
	v_lshlrev_b32_e32 v28, 16, v174
	v_mul_f32_e32 v0, 0x3d372713, v28
	v_mul_f32_e32 v0, v0, v28
	v_mov_b32_e32 v30, v28
	v_and_b32_e32 v29, 0xffff0000, v174
	v_fmac_f32_e32 v30, v0, v30
	v_mul_f32_e32 v0, 0x3f4c422a, v30
	v_mul_f32_e32 v30, 0x3d372713, v29
	v_mul_f32_e32 v30, v30, v29
	v_mov_b32_e32 v31, v29
	v_fmac_f32_e32 v31, v30, v31
	v_mul_f32_e32 v0, 0xc038aa3b, v0
	v_mul_f32_e32 v30, 0x3f4c422a, v31
	v_exp_f32_e32 v0, v0
	v_mul_f32_e32 v30, 0xc038aa3b, v30
	v_exp_f32_e32 v31, v30
	s_waitcnt lgkmcnt(9)
	v_mfma_f32_16x16x32_bf16 v[24:27], v[100:103], v[76:79], v[24:27]
	ds_read_b128 v[100:103], v19 offset:56640
	v_add_f32_e32 v0, 1.0, v0
	v_rcp_f32_e32 v30, v0
	v_add_f32_e32 v0, 1.0, v31
	v_lshlrev_b32_e32 v32, 16, v175
	v_rcp_f32_e32 v31, v0
	v_mul_f32_e32 v0, 0x3d372713, v32
	v_mul_f32_e32 v0, v0, v32
	v_mov_b32_e32 v34, v32
	v_and_b32_e32 v33, 0xffff0000, v175
	v_fmac_f32_e32 v34, v0, v34
	v_mul_f32_e32 v0, 0x3f4c422a, v34
	v_mul_f32_e32 v34, 0x3d372713, v33
	v_mul_f32_e32 v34, v34, v33
	v_mov_b32_e32 v35, v33
	v_fmac_f32_e32 v35, v34, v35
	v_mul_f32_e32 v0, 0xc038aa3b, v0
	v_mul_f32_e32 v34, 0x3f4c422a, v35
	v_exp_f32_e32 v0, v0
	v_mul_f32_e32 v34, 0xc038aa3b, v34
	v_exp_f32_e32 v37, v34
	v_pk_mul_f32 v[34:35], v[30:31], v[28:29]
	v_add_f32_e32 v0, 1.0, v0
	v_rcp_f32_e32 v36, v0
	v_add_f32_e32 v0, 1.0, v37
	v_rcp_f32_e32 v37, v0
	v_pk_add_f32 v[24:25], v[24:25], v[18:19] op_sel_hi:[1,0]
	v_pk_add_f32 v[26:27], v[26:27], v[18:19] op_sel_hi:[1,0]
	v_pk_mul_f32 v[24:25], v[24:25], v[34:35]
	v_pk_mul_f32 v[32:33], v[36:37], v[32:33]
	v_cvt_pk_bf16_f32 v24, v24, v25
	v_pk_mul_f32 v[26:27], v[26:27], v[32:33]
	v_cvt_pk_bf16_f32 v25, v26, v27
	global_store_dwordx2 v[22:23], v[24:25], off offset:64
	s_waitcnt lgkmcnt(9)
	v_mfma_f32_16x16x32_bf16 v[28:31], v[60:63], v[52:55], 0
	ds_read_b128 v[60:63], v19 offset:56704
	s_waitcnt lgkmcnt(9)
	v_mfma_f32_16x16x32_bf16 v[24:27], v[72:75], v[56:59], v[28:31]
	ds_read_b128 v[72:75], v19 offset:56768
	s_nop 5
	s_waitcnt lgkmcnt(9)
	v_mfma_f32_16x16x32_bf16 v[24:27], v[80:83], v[64:67], v[24:27]
	ds_read_b128 v[80:83], v19 offset:60928
	s_waitcnt vmcnt(0)
	v_lshlrev_b32_e32 v28, 16, v176
	v_mul_f32_e32 v0, 0x3d372713, v28
	v_mul_f32_e32 v0, v0, v28
	v_mov_b32_e32 v30, v28
	v_and_b32_e32 v29, 0xffff0000, v176
	v_fmac_f32_e32 v30, v0, v30
	v_mul_f32_e32 v0, 0x3f4c422a, v30
	v_mul_f32_e32 v30, 0x3d372713, v29
	v_mul_f32_e32 v30, v30, v29
	v_mov_b32_e32 v31, v29
	v_fmac_f32_e32 v31, v30, v31
	v_mul_f32_e32 v0, 0xc038aa3b, v0
	v_mul_f32_e32 v30, 0x3f4c422a, v31
	v_exp_f32_e32 v0, v0
	v_mul_f32_e32 v30, 0xc038aa3b, v30
	v_exp_f32_e32 v31, v30
	s_waitcnt lgkmcnt(9)
	v_mfma_f32_16x16x32_bf16 v[24:27], v[84:87], v[76:79], v[24:27]
	ds_read_b128 v[84:87], v19 offset:60992
	v_add_f32_e32 v0, 1.0, v0
	v_rcp_f32_e32 v30, v0
	v_add_f32_e32 v0, 1.0, v31
	v_lshlrev_b32_e32 v32, 16, v177
	v_rcp_f32_e32 v31, v0
	v_mul_f32_e32 v0, 0x3d372713, v32
	v_mul_f32_e32 v0, v0, v32
	v_mov_b32_e32 v34, v32
	v_and_b32_e32 v33, 0xffff0000, v177
	v_fmac_f32_e32 v34, v0, v34
	v_mul_f32_e32 v0, 0x3f4c422a, v34
	v_mul_f32_e32 v34, 0x3d372713, v33
	v_mul_f32_e32 v34, v34, v33
	v_mov_b32_e32 v35, v33
	v_fmac_f32_e32 v35, v34, v35
	v_mul_f32_e32 v0, 0xc038aa3b, v0
	v_mul_f32_e32 v34, 0x3f4c422a, v35
	v_exp_f32_e32 v0, v0
	v_mul_f32_e32 v34, 0xc038aa3b, v34
	v_exp_f32_e32 v37, v34
	v_pk_mul_f32 v[34:35], v[30:31], v[28:29]
	v_add_f32_e32 v0, 1.0, v0
	v_rcp_f32_e32 v36, v0
	v_add_f32_e32 v0, 1.0, v37
	v_rcp_f32_e32 v37, v0
	v_pk_add_f32 v[24:25], v[24:25], v[18:19] op_sel_hi:[1,0]
	v_pk_add_f32 v[26:27], v[26:27], v[18:19] op_sel_hi:[1,0]
	v_pk_mul_f32 v[24:25], v[24:25], v[34:35]
	v_pk_mul_f32 v[32:33], v[36:37], v[32:33]
	v_cvt_pk_bf16_f32 v24, v24, v25
	v_pk_mul_f32 v[26:27], v[26:27], v[32:33]
	v_cvt_pk_bf16_f32 v25, v26, v27
	global_store_dwordx2 v[22:23], v[24:25], off offset:96
	s_waitcnt lgkmcnt(9)
	v_mfma_f32_16x16x32_bf16 v[28:31], v[88:91], v[52:55], 0
	ds_read_b128 v[88:91], v19 offset:61056
	s_waitcnt lgkmcnt(9)
	v_mfma_f32_16x16x32_bf16 v[24:27], v[92:95], v[56:59], v[28:31]
	ds_read_b128 v[92:95], v19 offset:61120
	s_nop 5
	s_waitcnt lgkmcnt(9)
	v_mfma_f32_16x16x32_bf16 v[24:27], v[96:99], v[64:67], v[24:27]
	ds_read_b128 v[96:99], v19 offset:65280
	s_waitcnt vmcnt(0)
	v_lshlrev_b32_e32 v28, 16, v178
	v_mul_f32_e32 v0, 0x3d372713, v28
	v_mul_f32_e32 v0, v0, v28
	v_mov_b32_e32 v30, v28
	v_and_b32_e32 v29, 0xffff0000, v178
	v_fmac_f32_e32 v30, v0, v30
	v_mul_f32_e32 v0, 0x3f4c422a, v30
	v_mul_f32_e32 v30, 0x3d372713, v29
	v_mul_f32_e32 v30, v30, v29
	v_mov_b32_e32 v31, v29
	v_fmac_f32_e32 v31, v30, v31
	v_mul_f32_e32 v0, 0xc038aa3b, v0
	v_mul_f32_e32 v30, 0x3f4c422a, v31
	v_exp_f32_e32 v0, v0
	v_mul_f32_e32 v30, 0xc038aa3b, v30
	v_exp_f32_e32 v31, v30
	s_waitcnt lgkmcnt(9)
; __device__ __forceinline__ unsigned pk2(float lo, float hi) { return pg8::cvt_pk_bf16(lo, hi); }
; __device__ __forceinline__ float gelu_tanh(float x) { const float z = 0.7978845608028654f * (x + 0.044715f * x * x * x); return x * frcp(1.f + fexp2(-2.f * LOG2E * z)); }
; __device__ __forceinline__ void sgu_unit(LAS unsigned char* lds, const bfu* PROJ, const bfu* SW  , const float* ln_g, const float* ln_b, const float* sb, bfu* CAT, int s) {
;     ...
;     wave_mma(acc, Ws, Vt, m0, fr, fq);
;     const float bias = sb[g * 128 + t_];
;     const bfu* up = PROJ + (row0 + t_) * INW + C_SU + g * 128 + 4 * fq; bfu* op = CAT + (row0 + t_) * DM + 1536 + g * 128 + 4 * fq;
; #pragma unroll
;     for (int t = 0; t < 8; ++t) { const v2u uw = *(const v2u*)(up + 16 * t);
;         v2u w; w.x = pk2(gelu_tanh(bflo(uw.x)) * (acc[t][0] + bias), gelu_tanh(bfhi(uw.x)) * (acc[t][1] + bias)); w.y = pk2(gelu_tanh(bflo(uw.y)) * (acc[t][2] + bias), gelu_tanh(bfhi(uw.y)) * (acc[t][3] + bias));
;         *(v2u*)(op + 16 * t) = w; }
	v_mfma_f32_16x16x32_bf16 v[24:27], v[44:47], v[76:79], v[24:27]
	ds_read_b128 v[44:47], v19 offset:65344
	v_add_f32_e32 v0, 1.0, v0
	v_rcp_f32_e32 v30, v0
	v_add_f32_e32 v0, 1.0, v31
	v_lshlrev_b32_e32 v32, 16, v179
	v_rcp_f32_e32 v31, v0
	v_mul_f32_e32 v0, 0x3d372713, v32
	v_mul_f32_e32 v0, v0, v32
	v_mov_b32_e32 v34, v32
	v_and_b32_e32 v33, 0xffff0000, v179
	v_fmac_f32_e32 v34, v0, v34
	v_mul_f32_e32 v0, 0x3f4c422a, v34
	v_mul_f32_e32 v34, 0x3d372713, v33
	v_mul_f32_e32 v34, v34, v33
	v_mov_b32_e32 v35, v33
	v_fmac_f32_e32 v35, v34, v35
	v_mul_f32_e32 v0, 0xc038aa3b, v0
	v_mul_f32_e32 v34, 0x3f4c422a, v35
	v_exp_f32_e32 v0, v0
	v_mul_f32_e32 v34, 0xc038aa3b, v34
	v_exp_f32_e32 v37, v34
	v_pk_mul_f32 v[34:35], v[30:31], v[28:29]
	v_add_f32_e32 v0, 1.0, v0
	v_rcp_f32_e32 v36, v0
	v_add_f32_e32 v0, 1.0, v37
	v_rcp_f32_e32 v37, v0
	v_pk_add_f32 v[24:25], v[24:25], v[18:19] op_sel_hi:[1,0]
	v_pk_add_f32 v[26:27], v[26:27], v[18:19] op_sel_hi:[1,0]
	v_pk_mul_f32 v[24:25], v[24:25], v[34:35]
	v_pk_mul_f32 v[32:33], v[36:37], v[32:33]
	v_cvt_pk_bf16_f32 v24, v24, v25
	v_pk_mul_f32 v[26:27], v[26:27], v[32:33]
	v_cvt_pk_bf16_f32 v25, v26, v27
	global_store_dwordx2 v[22:23], v[24:25], off offset:128
	s_waitcnt lgkmcnt(9)
	v_mfma_f32_16x16x32_bf16 v[28:31], v[48:51], v[52:55], 0
	ds_read_b128 v[48:51], v19 offset:65408
	s_waitcnt lgkmcnt(9)
	v_mfma_f32_16x16x32_bf16 v[24:27], v[100:103], v[56:59], v[28:31]
	ds_read_b128 v[100:103], v19 offset:65472
	s_nop 5
	s_waitcnt lgkmcnt(9)
	v_mfma_f32_16x16x32_bf16 v[24:27], v[60:63], v[64:67], v[24:27]
	s_waitcnt vmcnt(0)
	v_lshlrev_b32_e32 v28, 16, v180
	v_mul_f32_e32 v0, 0x3d372713, v28
	v_mul_f32_e32 v0, v0, v28
	v_mov_b32_e32 v30, v28
	v_and_b32_e32 v29, 0xffff0000, v180
	v_fmac_f32_e32 v30, v0, v30
	v_mul_f32_e32 v0, 0x3f4c422a, v30
	v_mul_f32_e32 v30, 0x3d372713, v29
	v_mul_f32_e32 v30, v30, v29
	v_mov_b32_e32 v31, v29
	v_fmac_f32_e32 v31, v30, v31
	v_mul_f32_e32 v0, 0xc038aa3b, v0
	v_mul_f32_e32 v30, 0x3f4c422a, v31
	v_exp_f32_e32 v0, v0
	v_mul_f32_e32 v30, 0xc038aa3b, v30
	v_exp_f32_e32 v31, v30
	s_waitcnt lgkmcnt(8)
	v_mfma_f32_16x16x32_bf16 v[24:27], v[72:75], v[76:79], v[24:27]
	v_add_f32_e32 v0, 1.0, v0
	v_rcp_f32_e32 v30, v0
	v_add_f32_e32 v0, 1.0, v31
	v_lshlrev_b32_e32 v32, 16, v181
	v_rcp_f32_e32 v31, v0
	v_mul_f32_e32 v0, 0x3d372713, v32
	v_mul_f32_e32 v0, v0, v32
	v_mov_b32_e32 v34, v32
	v_and_b32_e32 v33, 0xffff0000, v181
	v_fmac_f32_e32 v34, v0, v34
	v_mul_f32_e32 v0, 0x3f4c422a, v34
	v_mul_f32_e32 v34, 0x3d372713, v33
	v_mul_f32_e32 v34, v34, v33
	v_mov_b32_e32 v35, v33
	v_fmac_f32_e32 v35, v34, v35
	v_mul_f32_e32 v0, 0xc038aa3b, v0
	v_mul_f32_e32 v34, 0x3f4c422a, v35
	v_exp_f32_e32 v0, v0
	v_mul_f32_e32 v34, 0xc038aa3b, v34
	v_exp_f32_e32 v37, v34
	v_pk_mul_f32 v[34:35], v[30:31], v[28:29]
	v_add_f32_e32 v0, 1.0, v0
	v_rcp_f32_e32 v36, v0
	v_add_f32_e32 v0, 1.0, v37
	v_rcp_f32_e32 v37, v0
	v_pk_add_f32 v[24:25], v[24:25], v[18:19] op_sel_hi:[1,0]
	v_pk_add_f32 v[26:27], v[26:27], v[18:19] op_sel_hi:[1,0]
	v_pk_mul_f32 v[24:25], v[24:25], v[34:35]
	v_pk_mul_f32 v[32:33], v[36:37], v[32:33]
	v_cvt_pk_bf16_f32 v24, v24, v25
	v_pk_mul_f32 v[26:27], v[26:27], v[32:33]
	v_cvt_pk_bf16_f32 v25, v26, v27
	global_store_dwordx2 v[22:23], v[24:25], off offset:160
	s_waitcnt lgkmcnt(7)
	v_mfma_f32_16x16x32_bf16 v[28:31], v[80:83], v[52:55], 0
	s_waitcnt lgkmcnt(6)
	v_mfma_f32_16x16x32_bf16 v[24:27], v[84:87], v[56:59], v[28:31]
	s_nop 5
	s_waitcnt lgkmcnt(5)
	v_mfma_f32_16x16x32_bf16 v[24:27], v[88:91], v[64:67], v[24:27]
	s_waitcnt vmcnt(0)
; __device__ __forceinline__ unsigned pk2(float lo, float hi) { return pg8::cvt_pk_bf16(lo, hi); }
; __device__ __forceinline__ float gelu_tanh(float x) { const float z = 0.7978845608028654f * (x + 0.044715f * x * x * x); return x * frcp(1.f + fexp2(-2.f * LOG2E * z)); }
; __device__ __forceinline__ void sgu_unit(LAS unsigned char* lds, const bfu* PROJ, const bfu* SW  , const float* ln_g, const float* ln_b, const float* sb, bfu* CAT, int s) {
;     ...
;     wave_mma(acc, Ws, Vt, m0, fr, fq);
;     const float bias = sb[g * 128 + t_];
;     const bfu* up = PROJ + (row0 + t_) * INW + C_SU + g * 128 + 4 * fq; bfu* op = CAT + (row0 + t_) * DM + 1536 + g * 128 + 4 * fq;
; #pragma unroll
;     for (int t = 0; t < 8; ++t) { const v2u uw = *(const v2u*)(up + 16 * t);
;         v2u w; w.x = pk2(gelu_tanh(bflo(uw.x)) * (acc[t][0] + bias), gelu_tanh(bfhi(uw.x)) * (acc[t][1] + bias)); w.y = pk2(gelu_tanh(bflo(uw.y)) * (acc[t][2] + bias), gelu_tanh(bfhi(uw.y)) * (acc[t][3] + bias));
;         *(v2u*)(op + 16 * t) = w; }
;     __syncthreads();
	v_lshlrev_b32_e32 v28, 16, v182
	v_mul_f32_e32 v0, 0x3d372713, v28
	v_mul_f32_e32 v0, v0, v28
	v_mov_b32_e32 v30, v28
	v_and_b32_e32 v29, 0xffff0000, v182
	v_fmac_f32_e32 v30, v0, v30
	v_mul_f32_e32 v0, 0x3f4c422a, v30
	v_mul_f32_e32 v30, 0x3d372713, v29
	v_mul_f32_e32 v30, v30, v29
	v_mov_b32_e32 v31, v29
	v_fmac_f32_e32 v31, v30, v31
	v_mul_f32_e32 v0, 0xc038aa3b, v0
	v_mul_f32_e32 v30, 0x3f4c422a, v31
	v_exp_f32_e32 v0, v0
	v_mul_f32_e32 v30, 0xc038aa3b, v30
	v_exp_f32_e32 v31, v30
	s_waitcnt lgkmcnt(4)
	v_mfma_f32_16x16x32_bf16 v[24:27], v[92:95], v[76:79], v[24:27]
	v_add_f32_e32 v0, 1.0, v0
	v_rcp_f32_e32 v30, v0
	v_add_f32_e32 v0, 1.0, v31
	v_lshlrev_b32_e32 v32, 16, v183
	v_rcp_f32_e32 v31, v0
	v_mul_f32_e32 v0, 0x3d372713, v32
	v_mul_f32_e32 v0, v0, v32
	v_mov_b32_e32 v34, v32
	v_and_b32_e32 v33, 0xffff0000, v183
	v_fmac_f32_e32 v34, v0, v34
	v_mul_f32_e32 v0, 0x3f4c422a, v34
	v_mul_f32_e32 v34, 0x3d372713, v33
	v_mul_f32_e32 v34, v34, v33
	v_mov_b32_e32 v35, v33
	v_fmac_f32_e32 v35, v34, v35
	v_mul_f32_e32 v0, 0xc038aa3b, v0
	v_mul_f32_e32 v34, 0x3f4c422a, v35
	v_exp_f32_e32 v0, v0
	v_mul_f32_e32 v34, 0xc038aa3b, v34
	v_exp_f32_e32 v37, v34
	v_pk_mul_f32 v[34:35], v[30:31], v[28:29]
	v_add_f32_e32 v0, 1.0, v0
	v_rcp_f32_e32 v36, v0
	v_add_f32_e32 v0, 1.0, v37
	v_rcp_f32_e32 v37, v0
	v_pk_add_f32 v[24:25], v[24:25], v[18:19] op_sel_hi:[1,0]
	v_pk_add_f32 v[26:27], v[26:27], v[18:19] op_sel_hi:[1,0]
	v_pk_mul_f32 v[24:25], v[24:25], v[34:35]
	v_pk_mul_f32 v[32:33], v[36:37], v[32:33]
	v_cvt_pk_bf16_f32 v24, v24, v25
	v_pk_mul_f32 v[26:27], v[26:27], v[32:33]
	v_cvt_pk_bf16_f32 v25, v26, v27
	global_store_dwordx2 v[22:23], v[24:25], off offset:192
	s_waitcnt lgkmcnt(3)
	v_mfma_f32_16x16x32_bf16 v[10:13], v[96:99], v[52:55], 0
	s_waitcnt lgkmcnt(2)
	v_mfma_f32_16x16x32_bf16 v[6:9], v[44:47], v[56:59], v[10:13]
	s_nop 5
	s_waitcnt lgkmcnt(1)
	v_mfma_f32_16x16x32_bf16 v[6:9], v[48:51], v[64:67], v[6:9]
	s_waitcnt vmcnt(0)
	v_lshlrev_b32_e32 v10, 16, v184
	v_mul_f32_e32 v0, 0x3d372713, v10
	v_mul_f32_e32 v0, v0, v10
	v_mov_b32_e32 v12, v10
	v_and_b32_e32 v11, 0xffff0000, v184
	v_fmac_f32_e32 v12, v0, v12
	v_mul_f32_e32 v0, 0x3f4c422a, v12
	v_mul_f32_e32 v12, 0x3d372713, v11
	v_mul_f32_e32 v12, v12, v11
	v_mov_b32_e32 v13, v11
	v_fmac_f32_e32 v13, v12, v13
	v_mul_f32_e32 v0, 0xc038aa3b, v0
	v_mul_f32_e32 v12, 0x3f4c422a, v13
	v_exp_f32_e32 v0, v0
	v_mul_f32_e32 v12, 0xc038aa3b, v12
	v_exp_f32_e32 v12, v12
	s_waitcnt lgkmcnt(0)
	v_mfma_f32_16x16x32_bf16 v[2:5], v[100:103], v[76:79], v[6:9]
	v_add_f32_e32 v0, 1.0, v0
	s_waitcnt lgkmcnt(0)
	s_nop 1
	v_rcp_f32_e32 v6, v0
	v_add_f32_e32 v0, 1.0, v12
	v_lshlrev_b32_e32 v8, 16, v185
	v_rcp_f32_e32 v7, v0
	v_mul_f32_e32 v0, 0x3d372713, v8
	v_mul_f32_e32 v0, v0, v8
	v_mov_b32_e32 v12, v8
	v_and_b32_e32 v9, 0xffff0000, v185
	v_fmac_f32_e32 v12, v0, v12
	v_mul_f32_e32 v0, 0x3f4c422a, v12
	v_mul_f32_e32 v12, 0x3d372713, v9
	v_mul_f32_e32 v12, v12, v9
	v_mov_b32_e32 v13, v9
	v_fmac_f32_e32 v13, v12, v13
	v_mul_f32_e32 v0, 0xc038aa3b, v0
	v_mul_f32_e32 v12, 0x3f4c422a, v13
	v_exp_f32_e32 v0, v0
	v_mul_f32_e32 v12, 0xc038aa3b, v12
	v_exp_f32_e32 v12, v12
	v_pk_mul_f32 v[6:7], v[6:7], v[10:11]
	v_add_f32_e32 v0, 1.0, v0
	v_rcp_f32_e32 v10, v0
	v_add_f32_e32 v0, 1.0, v12
	v_rcp_f32_e32 v11, v0
	v_pk_add_f32 v[2:3], v[18:19], v[2:3] op_sel_hi:[0,1]
	v_pk_mul_f32 v[2:3], v[2:3], v[6:7]
	v_pk_add_f32 v[4:5], v[18:19], v[4:5] op_sel_hi:[0,1]
	v_pk_mul_f32 v[6:7], v[10:11], v[8:9]
	v_cvt_pk_bf16_f32 v2, v2, v3
	v_pk_mul_f32 v[4:5], v[4:5], v[6:7]
	s_nop 0
	v_cvt_pk_bf16_f32 v3, v4, v5
	global_store_dwordx2 v[22:23], v[2:3], off offset:224
	s_barrier
	s_cbranch_execnz .LBB0_411
